# projection GEMM epilogues (qkv, w_in, uq, ukv): the lane^16 / lane^32 exchanges of the per-row RMS sums moved from ds_bpermute round trips to permlane16/32 swaps + a DPP row-masked move
# speedup vs baseline: 1.0005x; 1.0005x over previous
; DI float shx(float v, int m, int lane) { return __builtin_bit_cast(float, __builtin_amdgcn_ds_bpermute((lane ^ m) << 2, __builtin_bit_cast(int, v))); }
;     DI void operator()(const Acc& acc, const Unit& u, int wr, int wc, int fr, int fq) const {
;     ...
;         {
;             f32x4 qv[2][4];
;             const int slot = fq < 3 ? fq : 0;
; #pragma unroll
;             for (int ai = 0; ai < 2; ++ai)
; #pragma unroll
;                 for (int m = 0; m < 4; ++m) qv[ai][m] = *(const f32x4*)(ssq + (size_t)(rowb + ai * HALF + wr * 64 + m * 16 + fr) * 20 + slot * 4);
; #pragma unroll
;             for (int ai = 0; ai < 2; ++ai)
; #pragma unroll
;                 for (int m = 0; m < 4; ++m) {
;                     float t = fq < 3 ? (qv[ai][m][0] + qv[ai][m][1]) + (qv[ai][m][2] + qv[ai][m][3]) : 0.f;
;                     t += shx(t, 16, 16 * fq + fr); t += shx(t, 32, 16 * fq + fr);
;                     rs[ai][m] = rsqrtf(t * (1.f / 384.f) + LN_EPS);
;                 }
;             __builtin_amdgcn_sched_barrier(0);
;         }
; #pragma unroll
;         for (int ai = 0; ai < 2; ++ai)
; #pragma unroll
;             for (int m = 0; m < 4; ++m) {
;                 const int rl = ai * HALF + wr * 64 + m * 16 + fr, r = rowb + rl;
;                 const float rstd = rs[ai][m];
; #pragma unroll
;                 for (int bj = 0; bj < 2; ++bj) {
;                     const int gidx = u.pn * 8 + bj * 4 + wc, head = gidx / 3, part = gidx - head * 3;
;                     f32x4 x1 = acc[ai][bj][m][0] * rstd, x2 = acc[ai][bj][m][1] * rstd;
;                     bf16_t* qrow = Q + (size_t)r * 1536 + head * 96;
.LBB0_362:
	s_or_b64 exec, exec, s[6:7]
	s_waitcnt vmcnt(0)
	v_mov_b32_e32 v172, v153
	v_mov_b32_e32 v173, v154
	v_mov_b32_e32 v153, v155
	v_pk_add_f32 v[152:153], v[172:173], v[152:153]
	v_mov_b32_e32 v228, v181
	v_mov_b32_e32 v171, v181
	s_nop 1
	v_permlane16_swap_b32_e32 v228, v171
	s_nop 1
	v_mov_b32_dpp v171, v228 quad_perm:[0,1,2,3] row_mask:0xa bank_mask:0xf
	v_add_f32_e32 v152, v152, v153
	v_cndmask_b32_e64 v180, v152, 0, s[2:3]
	v_mov_b32_e32 v228, v180
	v_mov_b32_e32 v170, v180
	s_nop 1
	v_permlane16_swap_b32_e32 v228, v170
	s_nop 1
	v_mov_b32_dpp v170, v228 quad_perm:[0,1,2,3] row_mask:0xa bank_mask:0xf
	s_mov_b32 s8, 0x3b2aaaab
	s_cmp_lt_i32 s57, 64
	s_cselect_b64 s[6:7], -1, 0
	s_and_b32 s54, s17, 0x700
	s_waitcnt lgkmcnt(0)
	v_pk_add_f32 v[152:153], v[180:181], v[170:171]
	v_mov_b32_e32 v228, v153
	v_mov_b32_e32 v155, v153
	s_nop 1
	v_permlane32_swap_b32_e32 v228, v155
	s_nop 1
	v_mov_b32_dpp v155, v228 quad_perm:[0,1,2,3] row_mask:0xc bank_mask:0xf
	v_mov_b32_e32 v228, v152
	v_mov_b32_e32 v154, v152
	s_nop 1
	v_permlane32_swap_b32_e32 v228, v154
	s_nop 1
	v_mov_b32_dpp v154, v228 quad_perm:[0,1,2,3] row_mask:0xc bank_mask:0xf
	v_mov_b32_e32 v170, v149
	v_mov_b32_e32 v171, v150
	v_mov_b32_e32 v149, v151
	v_mov_b32_e32 v150, v145
	v_mov_b32_e32 v151, v146
	v_mov_b32_e32 v145, v147
	s_waitcnt lgkmcnt(0)
	v_pk_add_f32 v[152:153], v[152:153], v[154:155]
	v_pk_add_f32 v[148:149], v[170:171], v[148:149]
	v_pk_add_f32 v[144:145], v[150:151], v[144:145]
	v_pk_fma_f32 v[152:153], v[152:153], s[8:9], v[250:251] op_sel_hi:[1,0,0]
	v_mov_b32_e32 v146, v144
	v_mov_b32_e32 v147, v148
	v_mov_b32_e32 v148, v145
	s_mov_b32 s8, 0x800000
	v_pk_add_f32 v[144:145], v[146:147], v[148:149]
	v_mul_f32_e32 v148, 0x4b800000, v153
	v_cmp_gt_f32_e32 vcc, s8, v153
	v_mov_b32_e32 v149, v142
	v_mov_b32_e32 v142, v137
	v_cndmask_b32_e32 v148, v153, v148, vcc
	v_rsq_f32_e32 v150, v148
	v_mov_b32_e32 v148, v141
	v_mov_b32_e32 v141, v143
	v_mov_b32_e32 v143, v138
	v_mov_b32_e32 v137, v139
	v_pk_add_f32 v[140:141], v[148:149], v[140:141]
	v_pk_add_f32 v[136:137], v[142:143], v[136:137]
	v_mov_b32_e32 v139, v140
	v_mov_b32_e32 v138, v136
	v_mov_b32_e32 v140, v137
	v_pk_add_f32 v[136:137], v[138:139], v[140:141]
	v_mov_b32_e32 v140, v133
	v_mov_b32_e32 v141, v134
	v_mov_b32_e32 v133, v135
	v_mov_b32_e32 v134, v129
	v_mov_b32_e32 v135, v130
	v_mov_b32_e32 v129, v131
	v_pk_add_f32 v[132:133], v[140:141], v[132:133]
	v_pk_add_f32 v[128:129], v[134:135], v[128:129]
	v_mov_b32_e32 v131, v132
	v_mov_b32_e32 v130, v128
	v_mov_b32_e32 v132, v129
	v_pk_add_f32 v[128:129], v[130:131], v[132:133]
	v_cndmask_b32_e64 v145, v145, 0, s[2:3]
	v_cndmask_b32_e64 v144, v144, 0, s[2:3]
	v_cndmask_b32_e64 v137, v137, 0, s[2:3]
	v_cndmask_b32_e64 v136, v136, 0, s[2:3]
	v_cndmask_b32_e64 v129, v129, 0, s[2:3]
	v_cndmask_b32_e64 v128, v128, 0, s[2:3]
	v_mov_b32_e32 v228, v145
	v_mov_b32_e32 v147, v145
	s_nop 1
	v_permlane16_swap_b32_e32 v228, v147
	s_nop 1
	v_mov_b32_dpp v147, v228 quad_perm:[0,1,2,3] row_mask:0xa bank_mask:0xf
	v_mov_b32_e32 v228, v144
	v_mov_b32_e32 v146, v144
	s_nop 1
	v_permlane16_swap_b32_e32 v228, v146
	s_nop 1
	v_mov_b32_dpp v146, v228 quad_perm:[0,1,2,3] row_mask:0xa bank_mask:0xf
	v_mov_b32_e32 v228, v137
	v_mov_b32_e32 v139, v137
	s_nop 1
	v_permlane16_swap_b32_e32 v228, v139
	s_nop 1
	v_mov_b32_dpp v139, v228 quad_perm:[0,1,2,3] row_mask:0xa bank_mask:0xf
	v_mov_b32_e32 v228, v136
	v_mov_b32_e32 v138, v136
	s_nop 1
	v_permlane16_swap_b32_e32 v228, v138
	s_nop 1
	v_mov_b32_dpp v138, v228 quad_perm:[0,1,2,3] row_mask:0xa bank_mask:0xf
	v_mov_b32_e32 v228, v129
	v_mov_b32_e32 v131, v129
	s_nop 1
	v_permlane16_swap_b32_e32 v228, v131
	s_nop 1
	v_mov_b32_dpp v131, v228 quad_perm:[0,1,2,3] row_mask:0xa bank_mask:0xf
	v_mov_b32_e32 v228, v128
	v_mov_b32_e32 v130, v128
	s_nop 1
	v_permlane16_swap_b32_e32 v228, v130
	s_nop 1
	v_mov_b32_dpp v130, v228 quad_perm:[0,1,2,3] row_mask:0xa bank_mask:0xf
	s_waitcnt lgkmcnt(4)
	v_pk_add_f32 v[144:145], v[144:145], v[146:147]
	v_mov_b32_e32 v228, v145
	v_mov_b32_e32 v147, v145
	s_nop 1
	v_permlane32_swap_b32_e32 v228, v147
	s_nop 1
	v_mov_b32_dpp v147, v228 quad_perm:[0,1,2,3] row_mask:0xc bank_mask:0xf
	s_waitcnt lgkmcnt(3)
	v_pk_add_f32 v[140:141], v[136:137], v[138:139]
	v_mov_b32_e32 v228, v144
	v_mov_b32_e32 v146, v144
	s_nop 1
	v_permlane32_swap_b32_e32 v228, v146
	s_nop 1
	v_mov_b32_dpp v146, v228 quad_perm:[0,1,2,3] row_mask:0xc bank_mask:0xf
	s_waitcnt lgkmcnt(2)
	v_pk_add_f32 v[136:137], v[128:129], v[130:131]
	v_mov_b32_e32 v228, v141
	v_mov_b32_e32 v143, v141
	s_nop 1
	v_permlane32_swap_b32_e32 v228, v143
	s_nop 1
	v_mov_b32_dpp v143, v228 quad_perm:[0,1,2,3] row_mask:0xc bank_mask:0xf
	v_mov_b32_e32 v228, v140
	v_mov_b32_e32 v142, v140
	s_nop 1
	v_permlane32_swap_b32_e32 v228, v142
	s_nop 1
	v_mov_b32_dpp v142, v228 quad_perm:[0,1,2,3] row_mask:0xc bank_mask:0xf
	v_mov_b32_e32 v228, v137
	v_mov_b32_e32 v139, v137
	s_nop 1
	v_permlane32_swap_b32_e32 v228, v139
	s_nop 1
	v_mov_b32_dpp v139, v228 quad_perm:[0,1,2,3] row_mask:0xc bank_mask:0xf
	v_mov_b32_e32 v228, v136
	v_mov_b32_e32 v138, v136
	s_nop 1
	v_permlane32_swap_b32_e32 v228, v138
	s_nop 1
	v_mov_b32_dpp v138, v228 quad_perm:[0,1,2,3] row_mask:0xc bank_mask:0xf
	v_mul_f32_e32 v128, 0x45800000, v150
	v_cmp_gt_f32_e64 s[8:9], s8, v152
	v_cndmask_b32_e32 v148, v150, v128, vcc
	s_lshl_b32 s10, s56, 3
	s_or_b32 s56, s10, s43
	s_mul_hi_i32 s10, s56, 0x55555556
	s_lshr_b32 s11, s10, 31
	s_add_i32 s55, s54, s46
	s_add_i32 s12, s10, s11
	v_readlane_b32 s10, v254, 27
	v_mov_b32_e32 v128, s55
	s_mul_i32 s58, s12, -3
	v_readlane_b32 s11, v254, 28
	s_mul_i32 s64, s12, 0x60
	v_cndmask_b32_e64 v153, v190, v128, s[4:5]
	s_add_i32 s58, s58, s56
	v_mov_b64_e32 v[128:129], s[10:11]
	s_movk_i32 s10, 0xc00
	s_ashr_i32 s65, s64, 31
	v_mad_i64_i32 v[150:151], s[10:11], v168, s10, v[128:129]
	s_cmp_gt_i32 s58, 1
	s_cselect_b64 s[10:11], -1, 0
	v_cndmask_b32_e64 v128, 0, 1, s[6:7]
	v_pk_mul_f32 v[126:127], v[126:127], v[148:149] op_sel_hi:[1,0]
	v_pk_mul_f32 v[124:125], v[124:125], v[148:149] op_sel_hi:[1,0]
	v_pk_mul_f32 v[122:123], v[122:123], v[148:149] op_sel_hi:[1,0]
	v_pk_mul_f32 v[120:121], v[120:121], v[148:149] op_sel_hi:[1,0]
	v_lshl_add_u64 v[154:155], s[64:65], 1, v[150:151]
	s_mov_b64 s[12:13], -1
	s_and_b64 vcc, exec, s[10:11]
	v_cmp_ne_u32_e64 s[6:7], 1, v128
	s_cbranch_vccz .LBB0_367
; #define LAS __attribute__((address_space(3)))
;     DI void operator()(const Acc& acc, const Unit& u, int wr, int wc, int fr, int fq) const {
;     ...
;                         if (latent) {
;                             const int s = s0 + rl, pos = (fq >> 1) ? (s & 63) : (s >> 6);
;                             const LAS float* tp = tab + (pos * 8 + 4 * (fq & 1)) * 2;
;                             const f32x4 t0 = *(const LAS f32x4*)tp, t1 = *(const LAS f32x4*)(tp + 4);
;                             const f32x4 cs = {t0[0], t0[2], t1[0], t1[2]}, sn = {t0[1], t0[3], t1[1], t1[3]};
;                             const f32x4 y1 = x1 * cs - x2 * sn, y2 = x2 * cs + x1 * sn; x1 = y1; x2 = y2;
;                         }
	s_and_b64 vcc, exec, s[6:7]
	s_cbranch_vccnz .LBB0_365
	v_add_u32_e32 v128, v202, v153
	ds_read_b128 v[132:135], v128
	ds_read_b128 v[204:207], v128 offset:16
	s_waitcnt lgkmcnt(1)
	v_mov_b32_e32 v170, v133
	v_mov_b32_e32 v171, v135
	s_waitcnt lgkmcnt(0)
	v_mov_b32_e32 v172, v205
	v_mov_b32_e32 v173, v207
	v_pk_mul_f32 v[128:129], v[120:121], v[170:171]
	v_pk_mul_f32 v[130:131], v[122:123], v[172:173]
	v_mov_b32_e32 v205, v206
	v_mov_b32_e32 v133, v134
	v_pk_mul_f32 v[170:171], v[124:125], v[170:171]
	v_pk_mul_f32 v[134:135], v[126:127], v[172:173]
	v_pk_fma_f32 v[130:131], v[126:127], v[204:205], v[130:131] neg_lo:[0,0,1] neg_hi:[0,0,1]
	v_pk_fma_f32 v[128:129], v[124:125], v[132:133], v[128:129] neg_lo:[0,0,1] neg_hi:[0,0,1]
	v_pk_fma_f32 v[134:135], v[122:123], v[204:205], v[134:135]
	v_pk_fma_f32 v[132:133], v[120:121], v[132:133], v[170:171]
	s_branch .LBB0_366

; DI float shx(float v, int m, int lane) { return __builtin_bit_cast(float, __builtin_amdgcn_ds_bpermute((lane ^ m) << 2, __builtin_bit_cast(int, v))); }
;     DI void operator()(const Acc& acc, const Unit& u, int wr, int wc, int fr, int fq) const {
;     ...
;         {
;             f32x4 qv[2][4];
;             const int slot = fq < 2 ? fq : 0;
; #pragma unroll
;             for (int ai = 0; ai < 2; ++ai)
; #pragma unroll
;                 for (int m = 0; m < 4; ++m) qv[ai][m] = *(const f32x4*)(ssq + (size_t)(rowb + ai * HALF + wr * 64 + m * 16 + fr) * 20 + 12 + slot * 4);
; #pragma unroll
;             for (int ai = 0; ai < 2; ++ai)
; #pragma unroll
;                 for (int m = 0; m < 4; ++m) {
;                     float t = fq < 2 ? (qv[ai][m][0] + qv[ai][m][1]) + (qv[ai][m][2] + qv[ai][m][3]) : 0.f;
;                     t += shx(t, 16, 16 * fq + fr); t += shx(t, 32, 16 * fq + fr);
;                     rs[ai][m] = rsqrtf(t * (1.f / 256.f) + LN_EPS);
;                 }
;             __builtin_amdgcn_sched_barrier(0);
;         }
.LBB0_482:
	s_or_b64 exec, exec, s[4:5]
	s_waitcnt vmcnt(0)
	v_mov_b32_e32 v172, v153
	v_mov_b32_e32 v173, v154
	v_mov_b32_e32 v153, v155
	v_pk_add_f32 v[152:153], v[172:173], v[152:153]
	v_mov_b32_e32 v228, v157
	v_mov_b32_e32 v171, v157
	s_nop 1
	v_permlane16_swap_b32_e32 v228, v171
	s_nop 1
	v_mov_b32_dpp v171, v228 quad_perm:[0,1,2,3] row_mask:0xa bank_mask:0xf
	v_add_f32_e32 v152, v152, v153
	v_cndmask_b32_e64 v156, 0, v152, s[0:1]
	v_mov_b32_e32 v228, v156
	v_mov_b32_e32 v170, v156
	s_nop 1
	v_permlane16_swap_b32_e32 v228, v170
	s_nop 1
	v_mov_b32_dpp v170, v228 quad_perm:[0,1,2,3] row_mask:0xa bank_mask:0xf
	s_add_i32 s4, s16, 0xffffc000
	s_and_b32 s60, s16, 0x700
	s_lshr_b32 s4, s4, 8
	s_addk_i32 s60, 0x100
	s_waitcnt lgkmcnt(0)
	v_pk_add_f32 v[152:153], v[156:157], v[170:171]
	v_mov_b32_e32 v170, v149
	v_mov_b32_e32 v171, v150
	v_mov_b32_e32 v149, v151
	v_mov_b32_e32 v150, v145
	v_mov_b32_e32 v151, v146
	v_mov_b32_e32 v145, v147
	v_pk_add_f32 v[148:149], v[170:171], v[148:149]
	v_pk_add_f32 v[144:145], v[150:151], v[144:145]
	v_mov_b32_e32 v147, v148
	v_mov_b32_e32 v146, v144
	v_mov_b32_e32 v148, v145
	v_pk_add_f32 v[144:145], v[146:147], v[148:149]
	v_mov_b32_e32 v228, v153
	v_mov_b32_e32 v155, v153
	s_nop 1
	v_permlane32_swap_b32_e32 v228, v155
	s_nop 1
	v_mov_b32_dpp v155, v228 quad_perm:[0,1,2,3] row_mask:0xc bank_mask:0xf
	v_mov_b32_e32 v228, v152
	v_mov_b32_e32 v154, v152
	s_nop 1
	v_permlane32_swap_b32_e32 v228, v154
	s_nop 1
	v_mov_b32_dpp v154, v228 quad_perm:[0,1,2,3] row_mask:0xc bank_mask:0xf
	v_cndmask_b32_e64 v145, 0, v145, s[0:1]
	v_cndmask_b32_e64 v144, 0, v144, s[0:1]
	v_mov_b32_e32 v228, v145
	v_mov_b32_e32 v147, v145
	s_nop 1
	v_permlane16_swap_b32_e32 v228, v147
	s_nop 1
	v_mov_b32_dpp v147, v228 quad_perm:[0,1,2,3] row_mask:0xa bank_mask:0xf
	v_mov_b32_e32 v228, v144
	v_mov_b32_e32 v146, v144
	s_nop 1
	v_permlane16_swap_b32_e32 v228, v146
	s_nop 1
	v_mov_b32_dpp v146, v228 quad_perm:[0,1,2,3] row_mask:0xa bank_mask:0xf
	v_mov_b32_e32 v148, v141
	v_mov_b32_e32 v149, v142
	v_mov_b32_e32 v141, v143
	v_mov_b32_e32 v142, v137
	v_mov_b32_e32 v143, v138
	v_mov_b32_e32 v137, v139
	v_pk_add_f32 v[140:141], v[148:149], v[140:141]
	v_pk_add_f32 v[136:137], v[142:143], v[136:137]
	s_lshr_b32 s5, s84, 3
	s_waitcnt lgkmcnt(2)
	v_pk_add_f32 v[152:153], v[152:153], v[154:155]
	v_mov_b64_e32 v[156:157], s[38:39]
	s_mov_b32 s36, 0x3b800000
	v_mov_b32_e32 v138, v136
	v_mov_b32_e32 v139, v140
	v_mov_b32_e32 v140, v137
	s_cmp_lt_i32 s84, 64
	v_pk_fma_f32 v[152:153], v[152:153], s[36:37], v[156:157] op_sel_hi:[1,0,0]
	s_mov_b32 s16, 0x800000
	s_waitcnt lgkmcnt(0)
	v_pk_add_f32 v[144:145], v[144:145], v[146:147]
	v_pk_add_f32 v[136:137], v[138:139], v[140:141]
	s_cselect_b32 s61, s5, s4
	v_mul_f32_e32 v154, 0x4b800000, v153
	v_cmp_gt_f32_e64 s[4:5], s16, v153
	v_mov_b32_e32 v228, v145
	v_mov_b32_e32 v147, v145
	s_nop 1
	v_permlane32_swap_b32_e32 v228, v147
	s_nop 1
	v_mov_b32_dpp v147, v228 quad_perm:[0,1,2,3] row_mask:0xc bank_mask:0xf
	v_mov_b32_e32 v228, v144
	v_mov_b32_e32 v146, v144
	s_nop 1
	v_permlane32_swap_b32_e32 v228, v146
	s_nop 1
	v_mov_b32_dpp v146, v228 quad_perm:[0,1,2,3] row_mask:0xc bank_mask:0xf
	v_cndmask_b32_e64 v137, 0, v137, s[0:1]
	v_cndmask_b32_e64 v136, 0, v136, s[0:1]
	v_cndmask_b32_e64 v153, v153, v154, s[4:5]
	v_mov_b32_e32 v228, v137
	v_mov_b32_e32 v139, v137
	s_nop 1
	v_permlane16_swap_b32_e32 v228, v139
	s_nop 1
	v_mov_b32_dpp v139, v228 quad_perm:[0,1,2,3] row_mask:0xa bank_mask:0xf
	v_mov_b32_e32 v228, v136
	v_mov_b32_e32 v138, v136
	s_nop 1
	v_permlane16_swap_b32_e32 v228, v138
	s_nop 1
	v_mov_b32_dpp v138, v228 quad_perm:[0,1,2,3] row_mask:0xa bank_mask:0xf
	v_rsq_f32_e32 v153, v153
	v_mov_b32_e32 v140, v133
	v_mov_b32_e32 v141, v134
	v_mov_b32_e32 v133, v135
	v_mov_b32_e32 v134, v129
	v_mov_b32_e32 v135, v130
	v_mov_b32_e32 v129, v131
	v_pk_add_f32 v[132:133], v[140:141], v[132:133]
	v_pk_add_f32 v[128:129], v[134:135], v[128:129]
	s_waitcnt lgkmcnt(2)
	v_pk_add_f32 v[144:145], v[144:145], v[146:147]
	v_mov_b32_e32 v130, v128
	v_mov_b32_e32 v131, v132
	v_mov_b32_e32 v132, v129
	v_mul_f32_e32 v154, 0x45800000, v153
	v_pk_fma_f32 v[144:145], v[144:145], s[36:37], v[156:157] op_sel_hi:[1,0,0]
	s_waitcnt lgkmcnt(0)
	v_pk_add_f32 v[136:137], v[136:137], v[138:139]
	v_pk_add_f32 v[128:129], v[130:131], v[132:133]
	v_cmp_gt_f32_e32 vcc, s16, v152
	v_cndmask_b32_e64 v154, v153, v154, s[4:5]
	v_mul_f32_e32 v153, 0x4b800000, v152
	v_mul_f32_e32 v146, 0x4b800000, v145
	v_cmp_gt_f32_e64 s[4:5], s16, v145
	v_mov_b32_e32 v228, v137
	v_mov_b32_e32 v139, v137
	s_nop 1
	v_permlane32_swap_b32_e32 v228, v139
	s_nop 1
	v_mov_b32_dpp v139, v228 quad_perm:[0,1,2,3] row_mask:0xc bank_mask:0xf
	v_mov_b32_e32 v228, v136
	v_mov_b32_e32 v138, v136
	s_nop 1
	v_permlane32_swap_b32_e32 v228, v138
	s_nop 1
	v_mov_b32_dpp v138, v228 quad_perm:[0,1,2,3] row_mask:0xc bank_mask:0xf
	v_cndmask_b32_e64 v129, 0, v129, s[0:1]
	v_cndmask_b32_e64 v128, 0, v128, s[0:1]
	v_cndmask_b32_e32 v152, v152, v153, vcc
	v_cndmask_b32_e64 v145, v145, v146, s[4:5]
	v_mov_b32_e32 v228, v129
	v_mov_b32_e32 v131, v129
	s_nop 1
	v_permlane16_swap_b32_e32 v228, v131
	s_nop 1
	v_mov_b32_dpp v131, v228 quad_perm:[0,1,2,3] row_mask:0xa bank_mask:0xf
	v_mov_b32_e32 v228, v128
	v_mov_b32_e32 v130, v128
	s_nop 1
	v_permlane16_swap_b32_e32 v228, v130
	s_nop 1
	v_mov_b32_dpp v130, v228 quad_perm:[0,1,2,3] row_mask:0xa bank_mask:0xf
	v_rsq_f32_e32 v152, v152
	v_rsq_f32_e32 v145, v145
	s_waitcnt lgkmcnt(2)
	v_pk_add_f32 v[136:137], v[136:137], v[138:139]
	s_cselect_b32 s84, s60, 0
	v_mul_f32_e32 v153, 0x45800000, v152
	v_mul_f32_e32 v146, 0x45800000, v145
	v_pk_fma_f32 v[136:137], v[136:137], s[36:37], v[156:157] op_sel_hi:[1,0,0]
	s_waitcnt lgkmcnt(0)
; DI float shx(float v, int m, int lane) { return __builtin_bit_cast(float, __builtin_amdgcn_ds_bpermute((lane ^ m) << 2, __builtin_bit_cast(int, v))); }
;     DI void operator()(const Acc& acc, const Unit& u, int wr, int wc, int fr, int fq) const {
;     ...
;                 for (int m = 0; m < 4; ++m) {
;                     float t = fq < 2 ? (qv[ai][m][0] + qv[ai][m][1]) + (qv[ai][m][2] + qv[ai][m][3]) : 0.f;
;                     t += shx(t, 16, 16 * fq + fr); t += shx(t, 32, 16 * fq + fr);
;                     rs[ai][m] = rsqrtf(t * (1.f / 256.f) + LN_EPS);
;                 }
;             __builtin_amdgcn_sched_barrier(0);
;         }
; #pragma unroll
;         for (int ai = 0; ai < 2; ++ai)
; #pragma unroll
;             for (int m = 0; m < 4; ++m) {
;                 const int rl = ai * HALF + wr * 64 + m * 16 + fr, r = rowb + rl;
;                 const float rstd = rs[ai][m];
; #pragma unroll
;                 for (int bj = 0; bj < 2; ++bj) {
;                     const int head = u.pn * 2 + bj;
;                     const f32x4 x1 = acc[ai][bj][m][0] * rstd, x2 = acc[ai][bj][m][1] * rstd;
;                     if (wc < 2) {
;                         u32x4 o; o[0] = pk_bf16(x1[0], x1[1]); o[1] = pk_bf16(x1[2], x1[3]); o[2] = pk_bf16(x2[0], x2[1]); o[3] = pk_bf16(x2[2], x2[3]);
;                         *(u32x4*)(Kd + ((size_t)(b * 16 + head) * NKEY + kp0 + rl) * 64 + wc * 32 + 8 * fq) = o;
;                     } else {
;                         u32x4 o; o[0] = pk_bf16(x1[0], x1[1]); o[1] = pk_bf16(x1[2], x1[3]); o[2] = pk_bf16(x2[0], x2[1]); o[3] = pk_bf16(x2[2], x2[3]);
;                         *(u32x4*)(Vt + ((size_t)(b * 16 + head) * NKEY + kp0 + rl) * 64 + (wc - 2) * 32 + 8 * fq) = o;
	v_pk_add_f32 v[128:129], v[128:129], v[130:131]
	v_cndmask_b32_e32 v152, v152, v153, vcc
	v_cmp_gt_f32_e32 vcc, s16, v144
	v_cndmask_b32_e64 v146, v145, v146, s[4:5]
	v_mul_f32_e32 v145, 0x4b800000, v144
	v_mul_f32_e32 v138, 0x4b800000, v137
	v_cmp_gt_f32_e64 s[4:5], s16, v137
	v_mov_b32_e32 v228, v129
	v_mov_b32_e32 v131, v129
	s_nop 1
	v_permlane32_swap_b32_e32 v228, v131
	s_nop 1
	v_mov_b32_dpp v131, v228 quad_perm:[0,1,2,3] row_mask:0xc bank_mask:0xf
	v_mov_b32_e32 v228, v128
	v_mov_b32_e32 v130, v128
	s_nop 1
	v_permlane32_swap_b32_e32 v228, v130
	s_nop 1
	v_mov_b32_dpp v130, v228 quad_perm:[0,1,2,3] row_mask:0xc bank_mask:0xf
	v_cndmask_b32_e32 v144, v144, v145, vcc
	v_cndmask_b32_e64 v137, v137, v138, s[4:5]
	v_rsq_f32_e32 v144, v144
	v_rsq_f32_e32 v137, v137
	s_waitcnt lgkmcnt(0)
	v_pk_add_f32 v[128:129], v[128:129], v[130:131]
	v_mul_f32_e32 v145, 0x45800000, v144
	v_mul_f32_e32 v138, 0x45800000, v137
	v_pk_fma_f32 v[128:129], v[128:129], s[36:37], v[156:157] op_sel_hi:[1,0,0]
	v_cndmask_b32_e32 v144, v144, v145, vcc
	v_cmp_gt_f32_e32 vcc, s16, v136
	v_cndmask_b32_e64 v138, v137, v138, s[4:5]
	v_mul_f32_e32 v137, 0x4b800000, v136
	v_mul_f32_e32 v130, 0x4b800000, v129
	v_cmp_gt_f32_e64 s[4:5], s16, v129
	v_cndmask_b32_e32 v136, v136, v137, vcc
	v_rsq_f32_e32 v136, v136
	v_cndmask_b32_e64 v129, v129, v130, s[4:5]
	v_rsq_f32_e32 v129, v129
	v_mul_f32_e32 v137, 0x45800000, v136
	v_cndmask_b32_e32 v136, v136, v137, vcc
	v_mul_f32_e32 v130, 0x45800000, v129
	v_cmp_gt_f32_e32 vcc, s16, v128
	v_cndmask_b32_e64 v130, v129, v130, s[4:5]
	v_mul_f32_e32 v129, 0x4b800000, v128
	v_cndmask_b32_e32 v128, v128, v129, vcc
	v_rsq_f32_e32 v128, v128
	s_nop 0
	v_mul_f32_e32 v129, 0x45800000, v128
	v_cndmask_b32_e32 v128, v128, v129, vcc
	s_lshl_b32 s4, s15, 1
	s_lshl_b32 s5, s61, 4
	v_lshl_add_u64 v[132:133], s[84:85], 0, v[162:163]
	v_pk_mul_f32 v[124:125], v[124:125], v[154:155] op_sel_hi:[1,0]
	s_add_i32 s4, s5, s4
	v_pk_mul_f32 v[134:135], v[122:123], v[154:155] op_sel_hi:[1,0]
	v_pk_mul_f32 v[122:123], v[120:121], v[154:155] op_sel_hi:[1,0]
	v_cvt_pk_bf16_f32 v120, v124, v125
	v_mad_i64_i32 v[124:125], s[60:61], s4, v252, v[132:133]
	v_pk_mul_f32 v[126:127], v[126:127], v[154:155] op_sel_hi:[1,0]
	v_lshlrev_b64 v[124:125], 7, v[124:125]
	s_movk_i32 s36, 0xff80
	v_cvt_pk_bf16_f32 v121, v126, v127
	v_lshl_add_u64 v[126:127], s[12:13], 0, v[124:125]
	s_mov_b32 s37, -1
	v_lshl_add_u64 v[126:127], v[126:127], 0, s[36:37]
	v_lshl_add_u64 v[124:125], s[52:53], 0, v[124:125]
	v_cndmask_b32_e64 v125, v127, v125, s[2:3]
	v_cndmask_b32_e64 v124, v126, v124, s[2:3]
	v_cvt_pk_bf16_f32 v122, v122, v123
	v_cvt_pk_bf16_f32 v123, v134, v135
	v_lshl_add_u64 v[124:125], v[124:125], 0, v[168:169]
	v_pk_mul_f32 v[116:117], v[116:117], v[154:155] op_sel_hi:[1,0]
	s_or_b32 s5, s4, 1
	global_store_dwordx4 v[124:125], v[120:123], off
	v_pk_mul_f32 v[118:119], v[118:119], v[154:155] op_sel_hi:[1,0]
	v_pk_mul_f32 v[108:109], v[108:109], v[152:153] op_sel_hi:[1,0]
	v_pk_mul_f32 v[120:121], v[114:115], v[154:155] op_sel_hi:[1,0]
	v_pk_mul_f32 v[114:115], v[112:113], v[154:155] op_sel_hi:[1,0]
	v_cvt_pk_bf16_f32 v112, v116, v117
	v_mad_i64_i32 v[116:117], s[60:61], s5, v252, v[132:133]
	v_lshlrev_b64 v[116:117], 7, v[116:117]
	v_cvt_pk_bf16_f32 v113, v118, v119
	v_lshl_add_u64 v[118:119], s[52:53], 0, v[116:117]
	v_lshl_add_u64 v[116:117], s[12:13], 0, v[116:117]
	v_lshl_add_u64 v[116:117], v[116:117], 0, s[36:37]
	v_cndmask_b32_e64 v117, v117, v119, s[2:3]
	v_cndmask_b32_e64 v116, v116, v118, s[2:3]
	v_cvt_pk_bf16_f32 v114, v114, v115
	v_cvt_pk_bf16_f32 v115, v120, v121
	v_lshl_add_u64 v[116:117], v[116:117], 0, v[168:169]
	global_store_dwordx4 v[116:117], v[112:115], off
	v_pk_mul_f32 v[110:111], v[110:111], v[152:153] op_sel_hi:[1,0]
	v_pk_mul_f32 v[100:101], v[100:101], v[152:153] op_sel_hi:[1,0]
	v_lshl_add_u64 v[112:113], s[84:85], 0, v[164:165]
	v_pk_mul_f32 v[114:115], v[106:107], v[152:153] op_sel_hi:[1,0]
	v_pk_mul_f32 v[106:107], v[104:105], v[152:153] op_sel_hi:[1,0]
	v_cvt_pk_bf16_f32 v104, v108, v109
	v_mad_i64_i32 v[108:109], s[60:61], s4, v252, v[112:113]
	v_lshlrev_b64 v[108:109], 7, v[108:109]
	v_cvt_pk_bf16_f32 v105, v110, v111
	v_lshl_add_u64 v[110:111], s[52:53], 0, v[108:109]
	v_lshl_add_u64 v[108:109], s[12:13], 0, v[108:109]
	v_lshl_add_u64 v[108:109], v[108:109], 0, s[36:37]
	v_cndmask_b32_e64 v109, v109, v111, s[2:3]
	v_cndmask_b32_e64 v108, v108, v110, s[2:3]
	v_cvt_pk_bf16_f32 v106, v106, v107
	v_cvt_pk_bf16_f32 v107, v114, v115
	v_lshl_add_u64 v[108:109], v[108:109], 0, v[168:169]
	global_store_dwordx4 v[108:109], v[104:107], off
	v_pk_mul_f32 v[102:103], v[102:103], v[152:153] op_sel_hi:[1,0]
	v_pk_mul_f32 v[92:93], v[92:93], v[146:147] op_sel_hi:[1,0]
	v_pk_mul_f32 v[104:105], v[98:99], v[152:153] op_sel_hi:[1,0]
	v_pk_mul_f32 v[98:99], v[96:97], v[152:153] op_sel_hi:[1,0]
	v_cvt_pk_bf16_f32 v96, v100, v101
	v_mad_i64_i32 v[100:101], s[60:61], s5, v252, v[112:113]
	v_lshlrev_b64 v[100:101], 7, v[100:101]
	v_cvt_pk_bf16_f32 v97, v102, v103
	v_lshl_add_u64 v[102:103], s[52:53], 0, v[100:101]
	v_lshl_add_u64 v[100:101], s[12:13], 0, v[100:101]
	v_lshl_add_u64 v[100:101], v[100:101], 0, s[36:37]
	v_cndmask_b32_e64 v101, v101, v103, s[2:3]
	v_cndmask_b32_e64 v100, v100, v102, s[2:3]
	v_cvt_pk_bf16_f32 v98, v98, v99
	v_cvt_pk_bf16_f32 v99, v104, v105
	v_lshl_add_u64 v[100:101], v[100:101], 0, v[168:169]
	global_store_dwordx4 v[100:101], v[96:99], off
	v_pk_mul_f32 v[94:95], v[94:95], v[146:147] op_sel_hi:[1,0]
	v_pk_mul_f32 v[84:85], v[84:85], v[146:147] op_sel_hi:[1,0]
	v_lshl_add_u64 v[96:97], s[84:85], 0, v[166:167]
;     DI void operator()(const Acc& acc, const Unit& u, int wr, int wc, int fr, int fq) const {
;     ...
; #pragma unroll
;         for (int ai = 0; ai < 2; ++ai)
; #pragma unroll
;             for (int m = 0; m < 4; ++m) {
;                 const int rl = ai * HALF + wr * 64 + m * 16 + fr, r = rowb + rl;
;                 const float rstd = rs[ai][m];
; #pragma unroll
;                 for (int bj = 0; bj < 2; ++bj) {
;                     const int head = u.pn * 2 + bj;
;                     const f32x4 x1 = acc[ai][bj][m][0] * rstd, x2 = acc[ai][bj][m][1] * rstd;
;                     if (wc < 2) {
;                         u32x4 o; o[0] = pk_bf16(x1[0], x1[1]); o[1] = pk_bf16(x1[2], x1[3]); o[2] = pk_bf16(x2[0], x2[1]); o[3] = pk_bf16(x2[2], x2[3]);
;                         *(u32x4*)(Kd + ((size_t)(b * 16 + head) * NKEY + kp0 + rl) * 64 + wc * 32 + 8 * fq) = o;
;                     } else {
;                         u32x4 o; o[0] = pk_bf16(x1[0], x1[1]); o[1] = pk_bf16(x1[2], x1[3]); o[2] = pk_bf16(x2[0], x2[1]); o[3] = pk_bf16(x2[2], x2[3]);
;                         *(u32x4*)(Vt + ((size_t)(b * 16 + head) * NKEY + kp0 + rl) * 64 + (wc - 2) * 32 + 8 * fq) = o;
;                     }
;                 }
;             }
	v_pk_mul_f32 v[98:99], v[90:91], v[146:147] op_sel_hi:[1,0]
	v_pk_mul_f32 v[90:91], v[88:89], v[146:147] op_sel_hi:[1,0]
	v_cvt_pk_bf16_f32 v88, v92, v93
	v_mad_i64_i32 v[92:93], s[60:61], s4, v252, v[96:97]
	v_lshlrev_b64 v[92:93], 7, v[92:93]
	v_cvt_pk_bf16_f32 v89, v94, v95
	v_lshl_add_u64 v[94:95], s[52:53], 0, v[92:93]
	v_lshl_add_u64 v[92:93], s[12:13], 0, v[92:93]
	v_lshl_add_u64 v[92:93], v[92:93], 0, s[36:37]
	v_cndmask_b32_e64 v93, v93, v95, s[2:3]
	v_cndmask_b32_e64 v92, v92, v94, s[2:3]
	v_cvt_pk_bf16_f32 v90, v90, v91
	v_cvt_pk_bf16_f32 v91, v98, v99
	v_lshl_add_u64 v[92:93], v[92:93], 0, v[168:169]
	global_store_dwordx4 v[92:93], v[88:91], off
	v_pk_mul_f32 v[86:87], v[86:87], v[146:147] op_sel_hi:[1,0]
	v_pk_mul_f32 v[76:77], v[76:77], v[144:145] op_sel_hi:[1,0]
	v_pk_mul_f32 v[88:89], v[82:83], v[146:147] op_sel_hi:[1,0]
	v_pk_mul_f32 v[82:83], v[80:81], v[146:147] op_sel_hi:[1,0]
	v_cvt_pk_bf16_f32 v80, v84, v85
	v_mad_i64_i32 v[84:85], s[60:61], s5, v252, v[96:97]
	v_lshlrev_b64 v[84:85], 7, v[84:85]
	v_cvt_pk_bf16_f32 v81, v86, v87
	v_lshl_add_u64 v[86:87], s[52:53], 0, v[84:85]
	v_lshl_add_u64 v[84:85], s[12:13], 0, v[84:85]
	v_lshl_add_u64 v[84:85], v[84:85], 0, s[36:37]
	v_cndmask_b32_e64 v85, v85, v87, s[2:3]
	v_cndmask_b32_e64 v84, v84, v86, s[2:3]
	v_cvt_pk_bf16_f32 v82, v82, v83
	v_cvt_pk_bf16_f32 v83, v88, v89
	v_lshl_add_u64 v[84:85], v[84:85], 0, v[168:169]
	global_store_dwordx4 v[84:85], v[80:83], off
	v_pk_mul_f32 v[78:79], v[78:79], v[144:145] op_sel_hi:[1,0]
	v_pk_mul_f32 v[68:69], v[68:69], v[144:145] op_sel_hi:[1,0]
	v_lshl_add_u64 v[80:81], s[84:85], 0, v[176:177]
	v_pk_mul_f32 v[82:83], v[74:75], v[144:145] op_sel_hi:[1,0]
	v_pk_mul_f32 v[74:75], v[72:73], v[144:145] op_sel_hi:[1,0]
	v_cvt_pk_bf16_f32 v72, v76, v77
	v_mad_i64_i32 v[76:77], s[60:61], s4, v252, v[80:81]
	v_lshlrev_b64 v[76:77], 7, v[76:77]
	v_cvt_pk_bf16_f32 v73, v78, v79
	v_lshl_add_u64 v[78:79], s[52:53], 0, v[76:77]
	v_lshl_add_u64 v[76:77], s[12:13], 0, v[76:77]
	v_lshl_add_u64 v[76:77], v[76:77], 0, s[36:37]
	v_cndmask_b32_e64 v77, v77, v79, s[2:3]
	v_cndmask_b32_e64 v76, v76, v78, s[2:3]
	v_cvt_pk_bf16_f32 v74, v74, v75
	v_cvt_pk_bf16_f32 v75, v82, v83
	v_lshl_add_u64 v[76:77], v[76:77], 0, v[168:169]
	global_store_dwordx4 v[76:77], v[72:75], off
	v_pk_mul_f32 v[70:71], v[70:71], v[144:145] op_sel_hi:[1,0]
	v_pk_mul_f32 v[60:61], v[60:61], v[138:139] op_sel_hi:[1,0]
	v_pk_mul_f32 v[72:73], v[66:67], v[144:145] op_sel_hi:[1,0]
	v_pk_mul_f32 v[66:67], v[64:65], v[144:145] op_sel_hi:[1,0]
	v_cvt_pk_bf16_f32 v64, v68, v69
	v_mad_i64_i32 v[68:69], s[60:61], s5, v252, v[80:81]
	v_lshlrev_b64 v[68:69], 7, v[68:69]
	v_cvt_pk_bf16_f32 v65, v70, v71
	v_lshl_add_u64 v[70:71], s[52:53], 0, v[68:69]
	v_lshl_add_u64 v[68:69], s[12:13], 0, v[68:69]
	v_lshl_add_u64 v[68:69], v[68:69], 0, s[36:37]
	v_cndmask_b32_e64 v69, v69, v71, s[2:3]
	v_cndmask_b32_e64 v68, v68, v70, s[2:3]
	v_cvt_pk_bf16_f32 v66, v66, v67
	v_cvt_pk_bf16_f32 v67, v72, v73
	v_lshl_add_u64 v[68:69], v[68:69], 0, v[168:169]
	global_store_dwordx4 v[68:69], v[64:67], off
	v_pk_mul_f32 v[62:63], v[62:63], v[138:139] op_sel_hi:[1,0]
	v_pk_mul_f32 v[52:53], v[52:53], v[138:139] op_sel_hi:[1,0]
	v_lshl_add_u64 v[64:65], s[84:85], 0, v[178:179]
	v_pk_mul_f32 v[66:67], v[58:59], v[138:139] op_sel_hi:[1,0]
	v_pk_mul_f32 v[58:59], v[56:57], v[138:139] op_sel_hi:[1,0]
	v_cvt_pk_bf16_f32 v56, v60, v61
	v_mad_i64_i32 v[60:61], s[60:61], s4, v252, v[64:65]
	v_lshlrev_b64 v[60:61], 7, v[60:61]
	v_cvt_pk_bf16_f32 v57, v62, v63
	v_lshl_add_u64 v[62:63], s[52:53], 0, v[60:61]
	v_lshl_add_u64 v[60:61], s[12:13], 0, v[60:61]
	v_lshl_add_u64 v[60:61], v[60:61], 0, s[36:37]
	v_cndmask_b32_e64 v61, v61, v63, s[2:3]
	v_cndmask_b32_e64 v60, v60, v62, s[2:3]
	v_cvt_pk_bf16_f32 v58, v58, v59
	v_cvt_pk_bf16_f32 v59, v66, v67
	v_lshl_add_u64 v[60:61], v[60:61], 0, v[168:169]
	global_store_dwordx4 v[60:61], v[56:59], off
	v_pk_mul_f32 v[54:55], v[54:55], v[138:139] op_sel_hi:[1,0]
	v_pk_mul_f32 v[44:45], v[44:45], v[136:137] op_sel_hi:[1,0]
	v_pk_mul_f32 v[56:57], v[50:51], v[138:139] op_sel_hi:[1,0]
	v_pk_mul_f32 v[50:51], v[48:49], v[138:139] op_sel_hi:[1,0]
	v_cvt_pk_bf16_f32 v48, v52, v53
	v_mad_i64_i32 v[52:53], s[60:61], s5, v252, v[64:65]
	v_lshlrev_b64 v[52:53], 7, v[52:53]
	v_cvt_pk_bf16_f32 v49, v54, v55
	v_lshl_add_u64 v[54:55], s[52:53], 0, v[52:53]
	v_lshl_add_u64 v[52:53], s[12:13], 0, v[52:53]
	v_lshl_add_u64 v[52:53], v[52:53], 0, s[36:37]
	v_cndmask_b32_e64 v53, v53, v55, s[2:3]
	v_cndmask_b32_e64 v52, v52, v54, s[2:3]
	v_cvt_pk_bf16_f32 v50, v50, v51
	v_cvt_pk_bf16_f32 v51, v56, v57
	v_lshl_add_u64 v[52:53], v[52:53], 0, v[168:169]
	global_store_dwordx4 v[52:53], v[48:51], off
	v_pk_mul_f32 v[46:47], v[46:47], v[136:137] op_sel_hi:[1,0]
	v_pk_mul_f32 v[36:37], v[36:37], v[136:137] op_sel_hi:[1,0]
;     DI void operator()(const Acc& acc, const Unit& u, int wr, int wc, int fr, int fq) const {
;     ...
; #pragma unroll
;         for (int ai = 0; ai < 2; ++ai)
; #pragma unroll
;             for (int m = 0; m < 4; ++m) {
;                 const int rl = ai * HALF + wr * 64 + m * 16 + fr, r = rowb + rl;
;                 const float rstd = rs[ai][m];
; #pragma unroll
;                 for (int bj = 0; bj < 2; ++bj) {
;                     const int head = u.pn * 2 + bj;
;                     const f32x4 x1 = acc[ai][bj][m][0] * rstd, x2 = acc[ai][bj][m][1] * rstd;
;                     if (wc < 2) {
;                         u32x4 o; o[0] = pk_bf16(x1[0], x1[1]); o[1] = pk_bf16(x1[2], x1[3]); o[2] = pk_bf16(x2[0], x2[1]); o[3] = pk_bf16(x2[2], x2[3]);
;                         *(u32x4*)(Kd + ((size_t)(b * 16 + head) * NKEY + kp0 + rl) * 64 + wc * 32 + 8 * fq) = o;
;                     } else {
;                         u32x4 o; o[0] = pk_bf16(x1[0], x1[1]); o[1] = pk_bf16(x1[2], x1[3]); o[2] = pk_bf16(x2[0], x2[1]); o[3] = pk_bf16(x2[2], x2[3]);
;                         *(u32x4*)(Vt + ((size_t)(b * 16 + head) * NKEY + kp0 + rl) * 64 + (wc - 2) * 32 + 8 * fq) = o;
;                     }
;                 }
;             }
	v_lshl_add_u64 v[48:49], s[84:85], 0, v[180:181]
	v_pk_mul_f32 v[50:51], v[42:43], v[136:137] op_sel_hi:[1,0]
	v_pk_mul_f32 v[42:43], v[40:41], v[136:137] op_sel_hi:[1,0]
	v_cvt_pk_bf16_f32 v40, v44, v45
	v_mad_i64_i32 v[44:45], s[60:61], s4, v252, v[48:49]
	v_lshlrev_b64 v[44:45], 7, v[44:45]
	v_cvt_pk_bf16_f32 v41, v46, v47
	v_lshl_add_u64 v[46:47], s[52:53], 0, v[44:45]
	v_lshl_add_u64 v[44:45], s[12:13], 0, v[44:45]
	v_lshl_add_u64 v[44:45], v[44:45], 0, s[36:37]
	v_cndmask_b32_e64 v45, v45, v47, s[2:3]
	v_cndmask_b32_e64 v44, v44, v46, s[2:3]
	v_cvt_pk_bf16_f32 v42, v42, v43
	v_cvt_pk_bf16_f32 v43, v50, v51
	v_lshl_add_u64 v[44:45], v[44:45], 0, v[168:169]
	global_store_dwordx4 v[44:45], v[40:43], off
	v_pk_mul_f32 v[38:39], v[38:39], v[136:137] op_sel_hi:[1,0]
	v_pk_mul_f32 v[28:29], v[28:29], v[130:131] op_sel_hi:[1,0]
	v_pk_mul_f32 v[40:41], v[34:35], v[136:137] op_sel_hi:[1,0]
	v_pk_mul_f32 v[34:35], v[32:33], v[136:137] op_sel_hi:[1,0]
	v_cvt_pk_bf16_f32 v32, v36, v37
	v_mad_i64_i32 v[36:37], s[60:61], s5, v252, v[48:49]
	v_lshlrev_b64 v[36:37], 7, v[36:37]
	v_cvt_pk_bf16_f32 v33, v38, v39
	v_lshl_add_u64 v[38:39], s[52:53], 0, v[36:37]
	v_lshl_add_u64 v[36:37], s[12:13], 0, v[36:37]
	v_lshl_add_u64 v[36:37], v[36:37], 0, s[36:37]
	v_cndmask_b32_e64 v37, v37, v39, s[2:3]
	v_cndmask_b32_e64 v36, v36, v38, s[2:3]
	v_cvt_pk_bf16_f32 v34, v34, v35
	v_cvt_pk_bf16_f32 v35, v40, v41
	v_lshl_add_u64 v[36:37], v[36:37], 0, v[168:169]
	global_store_dwordx4 v[36:37], v[32:35], off
	v_pk_mul_f32 v[30:31], v[30:31], v[130:131] op_sel_hi:[1,0]
	v_pk_mul_f32 v[20:21], v[20:21], v[130:131] op_sel_hi:[1,0]
	v_lshl_add_u64 v[32:33], s[84:85], 0, v[182:183]
	v_pk_mul_f32 v[34:35], v[26:27], v[130:131] op_sel_hi:[1,0]
	v_pk_mul_f32 v[26:27], v[24:25], v[130:131] op_sel_hi:[1,0]
	v_cvt_pk_bf16_f32 v24, v28, v29
	v_mad_i64_i32 v[28:29], s[60:61], s4, v252, v[32:33]
	v_lshlrev_b64 v[28:29], 7, v[28:29]
	v_cvt_pk_bf16_f32 v25, v30, v31
	v_lshl_add_u64 v[30:31], s[52:53], 0, v[28:29]
	v_lshl_add_u64 v[28:29], s[12:13], 0, v[28:29]
	v_lshl_add_u64 v[28:29], v[28:29], 0, s[36:37]
	v_cndmask_b32_e64 v29, v29, v31, s[2:3]
	v_cndmask_b32_e64 v28, v28, v30, s[2:3]
	v_cvt_pk_bf16_f32 v26, v26, v27
	v_cvt_pk_bf16_f32 v27, v34, v35
	v_lshl_add_u64 v[28:29], v[28:29], 0, v[168:169]
	global_store_dwordx4 v[28:29], v[24:27], off
	v_pk_mul_f32 v[22:23], v[22:23], v[130:131] op_sel_hi:[1,0]
	v_pk_mul_f32 v[12:13], v[12:13], v[128:129] op_sel_hi:[1,0]
	v_pk_mul_f32 v[24:25], v[18:19], v[130:131] op_sel_hi:[1,0]
	v_pk_mul_f32 v[18:19], v[16:17], v[130:131] op_sel_hi:[1,0]
	v_cvt_pk_bf16_f32 v16, v20, v21
	v_mad_i64_i32 v[20:21], s[60:61], s5, v252, v[32:33]
	v_lshlrev_b64 v[20:21], 7, v[20:21]
	v_cvt_pk_bf16_f32 v17, v22, v23
	v_lshl_add_u64 v[22:23], s[52:53], 0, v[20:21]
	v_lshl_add_u64 v[20:21], s[12:13], 0, v[20:21]
	v_lshl_add_u64 v[20:21], v[20:21], 0, s[36:37]
	v_cndmask_b32_e64 v21, v21, v23, s[2:3]
	v_cndmask_b32_e64 v20, v20, v22, s[2:3]
	v_cvt_pk_bf16_f32 v18, v18, v19
	v_cvt_pk_bf16_f32 v19, v24, v25
	v_lshl_add_u64 v[20:21], v[20:21], 0, v[168:169]
	global_store_dwordx4 v[20:21], v[16:19], off
	v_pk_mul_f32 v[14:15], v[14:15], v[128:129] op_sel_hi:[1,0]
	v_pk_mul_f32 v[6:7], v[6:7], v[128:129] op_sel_hi:[1,0]
	v_lshl_add_u64 v[16:17], s[84:85], 0, v[184:185]
	v_pk_mul_f32 v[18:19], v[10:11], v[128:129] op_sel_hi:[1,0]
	v_pk_mul_f32 v[10:11], v[8:9], v[128:129] op_sel_hi:[1,0]
	v_cvt_pk_bf16_f32 v8, v12, v13
	v_mad_i64_i32 v[12:13], s[60:61], s4, v252, v[16:17]
	v_lshlrev_b64 v[12:13], 7, v[12:13]
	v_cvt_pk_bf16_f32 v9, v14, v15
	v_lshl_add_u64 v[14:15], s[52:53], 0, v[12:13]
	v_lshl_add_u64 v[12:13], s[12:13], 0, v[12:13]
	v_lshl_add_u64 v[12:13], v[12:13], 0, s[36:37]
	v_cndmask_b32_e64 v13, v13, v15, s[2:3]
	v_cndmask_b32_e64 v12, v12, v14, s[2:3]
	v_cvt_pk_bf16_f32 v10, v10, v11
	v_cvt_pk_bf16_f32 v11, v18, v19
	v_lshl_add_u64 v[12:13], v[12:13], 0, v[168:169]
	global_store_dwordx4 v[12:13], v[8:11], off
	v_pk_mul_f32 v[4:5], v[4:5], v[128:129] op_sel_hi:[1,0]
	v_pk_mul_f32 v[2:3], v[2:3], v[128:129] op_sel_hi:[1,0]
	v_mad_i64_i32 v[8:9], s[4:5], s5, v252, v[16:17]
	v_lshlrev_b64 v[8:9], 7, v[8:9]
	v_lshl_add_u64 v[10:11], s[52:53], 0, v[8:9]
	v_lshl_add_u64 v[8:9], s[12:13], 0, v[8:9]
	v_lshl_add_u64 v[8:9], v[8:9], 0, s[36:37]
	v_cndmask_b32_e64 v9, v9, v11, s[2:3]
	v_cndmask_b32_e64 v8, v8, v10, s[2:3]
	v_pk_mul_f32 v[0:1], v[0:1], v[128:129] op_sel_hi:[1,0]
	v_cvt_pk_bf16_f32 v4, v4, v5
	v_cvt_pk_bf16_f32 v5, v6, v7
	v_cvt_pk_bf16_f32 v6, v0, v1
	v_cvt_pk_bf16_f32 v7, v2, v3
	v_lshl_add_u64 v[0:1], v[8:9], 0, v[168:169]
	s_and_b64 vcc, exec, s[54:55]
	s_mov_b32 s15, s80
	s_mov_b32 s84, s81
	s_mov_b64 s[60:61], s[58:59]
	s_mov_b64 s[4:5], s[56:57]
	global_store_dwordx4 v[0:1], v[4:7], off
	s_cbranch_vccnz .LBB0_497

; DI float shx(float v, int m, int lane) { return __builtin_bit_cast(float, __builtin_amdgcn_ds_bpermute((lane ^ m) << 2, __builtin_bit_cast(int, v))); }
;     DI void operator()(const Acc& acc, const Unit& u, int wr, int wc, int fr, int fq) const {
;     ...
;         for (int bj = 0; bj < 2; ++bj) {
;             const int L = u.pn * BM + bj * HALF + wc * 32;
;             if (L < 640) {
; #pragma unroll
;                 for (int ai = 0; ai < 2; ++ai)
; #pragma unroll
;                     for (int m = 0; m < 4; ++m) {
;                         const int r = rowb + ai * HALF + wr * 64 + m * 16 + fr;
;                         const f32x4 a = acc[ai][bj][m][0], c = acc[ai][bj][m][1];
;                         float ss = a[0] * a[0] + a[1] * a[1] + a[2] * a[2] + a[3] * a[3] + c[0] * c[0] + c[1] * c[1] + c[2] * c[2] + c[3] * c[3];
;                         ss += shx(ss, 16, 16 * fq + fr); ss += shx(ss, 32, 16 * fq + fr);
;                         if (fq == 0) ssq[(size_t)r * 20 + (L >> 5)] = ss;
;                         u32x4 o; o[0] = pk_bf16(a[0], a[1]); o[1] = pk_bf16(a[2], a[3]); o[2] = pk_bf16(c[0], c[1]); o[3] = pk_bf16(c[2], c[3]);
;                         bf16_t* dst = L < 384 ? cq + (size_t)r * 384 + L + 8 * fq : ckv + (size_t)r * 256 + (L - 384) + 8 * fq;
;                         *(u32x4*)dst = o;
.LBB0_570:
	s_lshl_b32 s28, s26, 8
	s_lshl_b32 s4, s27, 8
	s_or_b32 s84, s4, s19
	v_or_b32_e32 v156, s28, v135
	s_cmpk_gt_i32 s84, 0x27f
	v_add_u32_e32 v156, s18, v156
	s_cbranch_scc1 .LBB0_589
	v_mul_f32_e32 v157, v125, v125
	v_fmac_f32_e32 v157, v124, v124
	v_fmac_f32_e32 v157, v126, v126
	v_fmac_f32_e32 v157, v127, v127
	v_fmac_f32_e32 v157, v120, v120
	v_fmac_f32_e32 v157, v121, v121
	v_fmac_f32_e32 v157, v122, v122
	v_fmac_f32_e32 v157, v123, v123
	v_mov_b32_e32 v228, v157
	v_mov_b32_e32 v158, v157
	s_nop 1
	v_permlane16_swap_b32_e32 v228, v158
	s_nop 1
	v_mov_b32_dpp v158, v228 quad_perm:[0,1,2,3] row_mask:0xa bank_mask:0xf
	s_waitcnt lgkmcnt(0)
	v_add_f32_e32 v158, v157, v158
	v_mov_b32_e32 v228, v158
	v_mov_b32_e32 v159, v158
	s_nop 1
	v_permlane32_swap_b32_e32 v228, v159
	s_nop 1
	v_mov_b32_dpp v159, v228 quad_perm:[0,1,2,3] row_mask:0xc bank_mask:0xf
	s_and_saveexec_b64 s[4:5], s[2:3]
	s_xor_b64 s[4:5], exec, s[4:5]
	v_ashrrev_i32_e32 v157, 31, v156
	s_or_saveexec_b64 s[4:5], s[4:5]
	s_ashr_i32 s56, s84, 5
	s_ashr_i32 s57, s56, 31
	s_xor_b64 exec, exec, s[4:5]
	s_cbranch_execz .LBB0_575
	v_readlane_b32 s30, v254, 42
	v_readlane_b32 s31, v254, 43
	s_waitcnt lgkmcnt(0)
	v_add_f32_e32 v168, v158, v159
	s_movk_i32 s27, 0x50
	v_mov_b64_e32 v[158:159], s[30:31]
	v_mad_i64_i32 v[158:159], s[30:31], v156, s27, v[158:159]
	v_ashrrev_i32_e32 v157, 31, v156
	v_lshl_add_u64 v[158:159], s[56:57], 2, v[158:159]
	global_store_dword v[158:159], v168, off

; DI float shx(float v, int m, int lane) { return __builtin_bit_cast(float, __builtin_amdgcn_ds_bpermute((lane ^ m) << 2, __builtin_bit_cast(int, v))); }
;     DI void operator()(const Acc& acc, const Unit& u, int wr, int wc, int fr, int fq) const {
;     ...
;                 for (int ai = 0; ai < 2; ++ai)
; #pragma unroll
;                     for (int m = 0; m < 4; ++m) {
;                         const int r = rowb + ai * HALF + wr * 64 + m * 16 + fr;
;                         const f32x4 a = acc[ai][bj][m][0], c = acc[ai][bj][m][1];
;                         float ss = a[0] * a[0] + a[1] * a[1] + a[2] * a[2] + a[3] * a[3] + c[0] * c[0] + c[1] * c[1] + c[2] * c[2] + c[3] * c[3];
;                         ss += shx(ss, 16, 16 * fq + fr); ss += shx(ss, 32, 16 * fq + fr);
;                         if (fq == 0) ssq[(size_t)r * 20 + (L >> 5)] = ss;
;                         u32x4 o; o[0] = pk_bf16(a[0], a[1]); o[1] = pk_bf16(a[2], a[3]); o[2] = pk_bf16(c[0], c[1]); o[3] = pk_bf16(c[2], c[3]);
;                         bf16_t* dst = L < 384 ? cq + (size_t)r * 384 + L + 8 * fq : ckv + (size_t)r * 256 + (L - 384) + 8 * fq;
;                         *(u32x4*)dst = o;
;                     }
.LBB0_579:
	v_lshlrev_b32_e32 v168, 1, v134
	v_cvt_pk_bf16_f32 v124, v124, v125
	v_cvt_pk_bf16_f32 v125, v126, v127
	v_cvt_pk_bf16_f32 v126, v120, v121
	v_cvt_pk_bf16_f32 v127, v122, v123
	s_waitcnt lgkmcnt(0)
	v_lshl_add_u64 v[120:121], v[158:159], 0, v[168:169]
	global_store_dwordx4 v[120:121], v[124:127], off
	v_mul_f32_e32 v121, v117, v117
	v_fmac_f32_e32 v121, v116, v116
	v_fmac_f32_e32 v121, v118, v118
	v_fmac_f32_e32 v121, v119, v119
	v_fmac_f32_e32 v121, v112, v112
	v_fmac_f32_e32 v121, v113, v113
	v_fmac_f32_e32 v121, v114, v114
	v_fmac_f32_e32 v121, v115, v115
	v_mov_b32_e32 v228, v121
	v_mov_b32_e32 v122, v121
	s_nop 1
	v_permlane16_swap_b32_e32 v228, v122
	s_nop 1
	v_mov_b32_dpp v122, v228 quad_perm:[0,1,2,3] row_mask:0xa bank_mask:0xf
	v_or_b32_e32 v120, 16, v156
	s_waitcnt lgkmcnt(0)
	v_add_f32_e32 v122, v121, v122
	v_mov_b32_e32 v228, v122
	v_mov_b32_e32 v123, v122
	s_nop 1
	v_permlane32_swap_b32_e32 v228, v123
	s_nop 1
	v_mov_b32_dpp v123, v228 quad_perm:[0,1,2,3] row_mask:0xc bank_mask:0xf
	v_ashrrev_i32_e32 v121, 31, v120
	s_and_saveexec_b64 s[4:5], s[2:3]
	s_xor_b64 s[4:5], exec, s[4:5]
	s_andn2_saveexec_b64 s[4:5], s[4:5]
	s_cbranch_execz .LBB0_583
	v_readlane_b32 s30, v254, 42
	v_readlane_b32 s31, v254, 43
	s_waitcnt lgkmcnt(0)
	v_add_f32_e32 v124, v122, v123
	s_movk_i32 s27, 0x50
	v_mov_b64_e32 v[122:123], s[30:31]
	v_mad_i64_i32 v[122:123], s[30:31], v120, s27, v[122:123]
	v_lshl_add_u64 v[122:123], s[56:57], 2, v[122:123]
	global_store_dword v[122:123], v124, off

; DI float shx(float v, int m, int lane) { return __builtin_bit_cast(float, __builtin_amdgcn_ds_bpermute((lane ^ m) << 2, __builtin_bit_cast(int, v))); }
;     DI void operator()(const Acc& acc, const Unit& u, int wr, int wc, int fr, int fq) const {
;     ...
;                 for (int ai = 0; ai < 2; ++ai)
; #pragma unroll
;                     for (int m = 0; m < 4; ++m) {
;                         const int r = rowb + ai * HALF + wr * 64 + m * 16 + fr;
;                         const f32x4 a = acc[ai][bj][m][0], c = acc[ai][bj][m][1];
;                         float ss = a[0] * a[0] + a[1] * a[1] + a[2] * a[2] + a[3] * a[3] + c[0] * c[0] + c[1] * c[1] + c[2] * c[2] + c[3] * c[3];
;                         ss += shx(ss, 16, 16 * fq + fr); ss += shx(ss, 32, 16 * fq + fr);
;                         if (fq == 0) ssq[(size_t)r * 20 + (L >> 5)] = ss;
;                         u32x4 o; o[0] = pk_bf16(a[0], a[1]); o[1] = pk_bf16(a[2], a[3]); o[2] = pk_bf16(c[0], c[1]); o[3] = pk_bf16(c[2], c[3]);
;                         bf16_t* dst = L < 384 ? cq + (size_t)r * 384 + L + 8 * fq : ckv + (size_t)r * 256 + (L - 384) + 8 * fq;
;                         *(u32x4*)dst = o;
;                     }
.LBB0_587:
	v_cvt_pk_bf16_f32 v116, v116, v117
	v_cvt_pk_bf16_f32 v117, v118, v119
	v_cvt_pk_bf16_f32 v118, v112, v113
	v_cvt_pk_bf16_f32 v119, v114, v115
	s_waitcnt lgkmcnt(0)
	v_lshl_add_u64 v[112:113], v[122:123], 0, v[168:169]
	global_store_dwordx4 v[112:113], v[116:119], off
	v_mul_f32_e32 v113, v109, v109
	v_fmac_f32_e32 v113, v108, v108
	v_fmac_f32_e32 v113, v110, v110
	v_fmac_f32_e32 v113, v111, v111
	v_fmac_f32_e32 v113, v104, v104
	v_fmac_f32_e32 v113, v105, v105
	v_fmac_f32_e32 v113, v106, v106
	v_fmac_f32_e32 v113, v107, v107
	v_mov_b32_e32 v228, v113
	v_mov_b32_e32 v114, v113
	s_nop 1
	v_permlane16_swap_b32_e32 v228, v114
	s_nop 1
	v_mov_b32_dpp v114, v228 quad_perm:[0,1,2,3] row_mask:0xa bank_mask:0xf
	v_or_b32_e32 v112, 32, v156
	s_waitcnt lgkmcnt(0)
	v_add_f32_e32 v114, v113, v114
	v_mov_b32_e32 v228, v114
	v_mov_b32_e32 v115, v114
	s_nop 1
	v_permlane32_swap_b32_e32 v228, v115
	s_nop 1
	v_mov_b32_dpp v115, v228 quad_perm:[0,1,2,3] row_mask:0xc bank_mask:0xf
	v_ashrrev_i32_e32 v113, 31, v112
	s_and_saveexec_b64 s[30:31], s[2:3]
	s_xor_b64 s[60:61], exec, s[30:31]
	s_cbranch_execz .LBB0_609
	s_andn2_saveexec_b64 s[60:61], s[60:61]
	s_cbranch_execz .LBB0_611
	s_branch .LBB0_610

; DI float shx(float v, int m, int lane) { return __builtin_bit_cast(float, __builtin_amdgcn_ds_bpermute((lane ^ m) << 2, __builtin_bit_cast(int, v))); }
;     DI void operator()(const Acc& acc, const Unit& u, int wr, int wc, int fr, int fq) const {
;     ...
;                 for (int ai = 0; ai < 2; ++ai)
; #pragma unroll
;                     for (int m = 0; m < 4; ++m) {
;                         const int r = rowb + ai * HALF + wr * 64 + m * 16 + fr;
;                         const f32x4 a = acc[ai][bj][m][0], c = acc[ai][bj][m][1];
;                         float ss = a[0] * a[0] + a[1] * a[1] + a[2] * a[2] + a[3] * a[3] + c[0] * c[0] + c[1] * c[1] + c[2] * c[2] + c[3] * c[3];
;                         ss += shx(ss, 16, 16 * fq + fr); ss += shx(ss, 32, 16 * fq + fr);
;                         if (fq == 0) ssq[(size_t)r * 20 + (L >> 5)] = ss;
;                         u32x4 o; o[0] = pk_bf16(a[0], a[1]); o[1] = pk_bf16(a[2], a[3]); o[2] = pk_bf16(c[0], c[1]); o[3] = pk_bf16(c[2], c[3]);
;                         bf16_t* dst = L < 384 ? cq + (size_t)r * 384 + L + 8 * fq : ckv + (size_t)r * 256 + (L - 384) + 8 * fq;
;                         *(u32x4*)dst = o;
;                     }
.LBB0_615:
	v_cvt_pk_bf16_f32 v108, v108, v109
	v_cvt_pk_bf16_f32 v109, v110, v111
	v_cvt_pk_bf16_f32 v110, v104, v105
	v_cvt_pk_bf16_f32 v111, v106, v107
	s_waitcnt lgkmcnt(0)
	v_lshl_add_u64 v[104:105], v[114:115], 0, v[168:169]
	global_store_dwordx4 v[104:105], v[108:111], off
	v_mul_f32_e32 v105, v101, v101
	v_fmac_f32_e32 v105, v100, v100
	v_fmac_f32_e32 v105, v102, v102
	v_fmac_f32_e32 v105, v103, v103
	v_fmac_f32_e32 v105, v96, v96
	v_fmac_f32_e32 v105, v97, v97
	v_fmac_f32_e32 v105, v98, v98
	v_fmac_f32_e32 v105, v99, v99
	v_mov_b32_e32 v228, v105
	v_mov_b32_e32 v106, v105
	s_nop 1
	v_permlane16_swap_b32_e32 v228, v106
	s_nop 1
	v_mov_b32_dpp v106, v228 quad_perm:[0,1,2,3] row_mask:0xa bank_mask:0xf
	v_or_b32_e32 v104, 48, v156
	s_waitcnt lgkmcnt(0)
	v_add_f32_e32 v106, v105, v106
	v_mov_b32_e32 v228, v106
	v_mov_b32_e32 v107, v106
	s_nop 1
	v_permlane32_swap_b32_e32 v228, v107
	s_nop 1
	v_mov_b32_dpp v107, v228 quad_perm:[0,1,2,3] row_mask:0xc bank_mask:0xf
	v_ashrrev_i32_e32 v105, 31, v104
	s_and_saveexec_b64 s[30:31], s[2:3]
	s_xor_b64 s[60:61], exec, s[30:31]
	s_cbranch_execz .LBB0_617
	s_andn2_saveexec_b64 s[60:61], s[60:61]
	s_cbranch_execz .LBB0_619
	s_branch .LBB0_618

; DI float shx(float v, int m, int lane) { return __builtin_bit_cast(float, __builtin_amdgcn_ds_bpermute((lane ^ m) << 2, __builtin_bit_cast(int, v))); }
;     DI void operator()(const Acc& acc, const Unit& u, int wr, int wc, int fr, int fq) const {
;     ...
;                 for (int ai = 0; ai < 2; ++ai)
; #pragma unroll
;                     for (int m = 0; m < 4; ++m) {
;                         const int r = rowb + ai * HALF + wr * 64 + m * 16 + fr;
;                         const f32x4 a = acc[ai][bj][m][0], c = acc[ai][bj][m][1];
;                         float ss = a[0] * a[0] + a[1] * a[1] + a[2] * a[2] + a[3] * a[3] + c[0] * c[0] + c[1] * c[1] + c[2] * c[2] + c[3] * c[3];
;                         ss += shx(ss, 16, 16 * fq + fr); ss += shx(ss, 32, 16 * fq + fr);
;                         if (fq == 0) ssq[(size_t)r * 20 + (L >> 5)] = ss;
;                         u32x4 o; o[0] = pk_bf16(a[0], a[1]); o[1] = pk_bf16(a[2], a[3]); o[2] = pk_bf16(c[0], c[1]); o[3] = pk_bf16(c[2], c[3]);
;                         bf16_t* dst = L < 384 ? cq + (size_t)r * 384 + L + 8 * fq : ckv + (size_t)r * 256 + (L - 384) + 8 * fq;
;                         *(u32x4*)dst = o;
;                     }
.LBB0_623:
	v_cvt_pk_bf16_f32 v100, v100, v101
	v_cvt_pk_bf16_f32 v101, v102, v103
	v_cvt_pk_bf16_f32 v102, v96, v97
	v_cvt_pk_bf16_f32 v103, v98, v99
	s_waitcnt lgkmcnt(0)
	v_lshl_add_u64 v[96:97], v[106:107], 0, v[168:169]
	global_store_dwordx4 v[96:97], v[100:103], off
	v_mul_f32_e32 v97, v93, v93
	v_fmac_f32_e32 v97, v92, v92
	v_fmac_f32_e32 v97, v94, v94
	v_fmac_f32_e32 v97, v95, v95
	v_fmac_f32_e32 v97, v88, v88
	v_fmac_f32_e32 v97, v89, v89
	v_fmac_f32_e32 v97, v90, v90
	v_fmac_f32_e32 v97, v91, v91
	v_mov_b32_e32 v228, v97
	v_mov_b32_e32 v98, v97
	s_nop 1
	v_permlane16_swap_b32_e32 v228, v98
	s_nop 1
	v_mov_b32_dpp v98, v228 quad_perm:[0,1,2,3] row_mask:0xa bank_mask:0xf
	v_add_u32_e32 v96, 0x80, v156
	s_waitcnt lgkmcnt(0)
	v_add_f32_e32 v98, v97, v98
	v_mov_b32_e32 v228, v98
	v_mov_b32_e32 v99, v98
	s_nop 1
	v_permlane32_swap_b32_e32 v228, v99
	s_nop 1
	v_mov_b32_dpp v99, v228 quad_perm:[0,1,2,3] row_mask:0xc bank_mask:0xf
	v_ashrrev_i32_e32 v97, 31, v96
	s_and_saveexec_b64 s[30:31], s[2:3]
	s_xor_b64 s[60:61], exec, s[30:31]
	s_cbranch_execz .LBB0_625
	s_andn2_saveexec_b64 s[60:61], s[60:61]
	s_cbranch_execz .LBB0_627
	s_branch .LBB0_626

; DI float shx(float v, int m, int lane) { return __builtin_bit_cast(float, __builtin_amdgcn_ds_bpermute((lane ^ m) << 2, __builtin_bit_cast(int, v))); }
;     DI void operator()(const Acc& acc, const Unit& u, int wr, int wc, int fr, int fq) const {
;     ...
;                 for (int ai = 0; ai < 2; ++ai)
; #pragma unroll
;                     for (int m = 0; m < 4; ++m) {
;                         const int r = rowb + ai * HALF + wr * 64 + m * 16 + fr;
;                         const f32x4 a = acc[ai][bj][m][0], c = acc[ai][bj][m][1];
;                         float ss = a[0] * a[0] + a[1] * a[1] + a[2] * a[2] + a[3] * a[3] + c[0] * c[0] + c[1] * c[1] + c[2] * c[2] + c[3] * c[3];
;                         ss += shx(ss, 16, 16 * fq + fr); ss += shx(ss, 32, 16 * fq + fr);
;                         if (fq == 0) ssq[(size_t)r * 20 + (L >> 5)] = ss;
;                         u32x4 o; o[0] = pk_bf16(a[0], a[1]); o[1] = pk_bf16(a[2], a[3]); o[2] = pk_bf16(c[0], c[1]); o[3] = pk_bf16(c[2], c[3]);
;                         bf16_t* dst = L < 384 ? cq + (size_t)r * 384 + L + 8 * fq : ckv + (size_t)r * 256 + (L - 384) + 8 * fq;
;                         *(u32x4*)dst = o;
;                     }
.LBB0_631:
	v_cvt_pk_bf16_f32 v92, v92, v93
	v_cvt_pk_bf16_f32 v93, v94, v95
	v_cvt_pk_bf16_f32 v94, v88, v89
	v_cvt_pk_bf16_f32 v95, v90, v91
	s_waitcnt lgkmcnt(0)
	v_lshl_add_u64 v[88:89], v[98:99], 0, v[168:169]
	global_store_dwordx4 v[88:89], v[92:95], off
	v_mul_f32_e32 v89, v85, v85
	v_fmac_f32_e32 v89, v84, v84
	v_fmac_f32_e32 v89, v86, v86
	v_fmac_f32_e32 v89, v87, v87
	v_fmac_f32_e32 v89, v80, v80
	v_fmac_f32_e32 v89, v81, v81
	v_fmac_f32_e32 v89, v82, v82
	v_fmac_f32_e32 v89, v83, v83
	v_mov_b32_e32 v228, v89
	v_mov_b32_e32 v90, v89
	s_nop 1
	v_permlane16_swap_b32_e32 v228, v90
	s_nop 1
	v_mov_b32_dpp v90, v228 quad_perm:[0,1,2,3] row_mask:0xa bank_mask:0xf
	v_add_u32_e32 v88, 0x90, v156
	s_waitcnt lgkmcnt(0)
	v_add_f32_e32 v90, v89, v90
	v_mov_b32_e32 v228, v90
	v_mov_b32_e32 v91, v90
	s_nop 1
	v_permlane32_swap_b32_e32 v228, v91
	s_nop 1
	v_mov_b32_dpp v91, v228 quad_perm:[0,1,2,3] row_mask:0xc bank_mask:0xf
	v_ashrrev_i32_e32 v89, 31, v88
	s_and_saveexec_b64 s[30:31], s[2:3]
	s_xor_b64 s[60:61], exec, s[30:31]
	s_cbranch_execz .LBB0_633
	s_andn2_saveexec_b64 s[60:61], s[60:61]
	s_cbranch_execz .LBB0_635
	s_branch .LBB0_634

; DI float shx(float v, int m, int lane) { return __builtin_bit_cast(float, __builtin_amdgcn_ds_bpermute((lane ^ m) << 2, __builtin_bit_cast(int, v))); }
;     DI void operator()(const Acc& acc, const Unit& u, int wr, int wc, int fr, int fq) const {
;     ...
;                 for (int ai = 0; ai < 2; ++ai)
; #pragma unroll
;                     for (int m = 0; m < 4; ++m) {
;                         const int r = rowb + ai * HALF + wr * 64 + m * 16 + fr;
;                         const f32x4 a = acc[ai][bj][m][0], c = acc[ai][bj][m][1];
;                         float ss = a[0] * a[0] + a[1] * a[1] + a[2] * a[2] + a[3] * a[3] + c[0] * c[0] + c[1] * c[1] + c[2] * c[2] + c[3] * c[3];
;                         ss += shx(ss, 16, 16 * fq + fr); ss += shx(ss, 32, 16 * fq + fr);
;                         if (fq == 0) ssq[(size_t)r * 20 + (L >> 5)] = ss;
;                         u32x4 o; o[0] = pk_bf16(a[0], a[1]); o[1] = pk_bf16(a[2], a[3]); o[2] = pk_bf16(c[0], c[1]); o[3] = pk_bf16(c[2], c[3]);
;                         bf16_t* dst = L < 384 ? cq + (size_t)r * 384 + L + 8 * fq : ckv + (size_t)r * 256 + (L - 384) + 8 * fq;
;                         *(u32x4*)dst = o;
;                     }
.LBB0_639:
	v_cvt_pk_bf16_f32 v84, v84, v85
	v_cvt_pk_bf16_f32 v85, v86, v87
	v_cvt_pk_bf16_f32 v86, v80, v81
	v_cvt_pk_bf16_f32 v87, v82, v83
	s_waitcnt lgkmcnt(0)
	v_lshl_add_u64 v[80:81], v[90:91], 0, v[168:169]
	global_store_dwordx4 v[80:81], v[84:87], off
	v_mul_f32_e32 v81, v77, v77
	v_fmac_f32_e32 v81, v76, v76
	v_fmac_f32_e32 v81, v78, v78
	v_fmac_f32_e32 v81, v79, v79
	v_fmac_f32_e32 v81, v72, v72
	v_fmac_f32_e32 v81, v73, v73
	v_fmac_f32_e32 v81, v74, v74
	v_fmac_f32_e32 v81, v75, v75
	v_mov_b32_e32 v228, v81
	v_mov_b32_e32 v82, v81
	s_nop 1
	v_permlane16_swap_b32_e32 v228, v82
	s_nop 1
	v_mov_b32_dpp v82, v228 quad_perm:[0,1,2,3] row_mask:0xa bank_mask:0xf
	v_add_u32_e32 v80, 0xa0, v156
	s_waitcnt lgkmcnt(0)
	v_add_f32_e32 v82, v81, v82
	v_mov_b32_e32 v228, v82
	v_mov_b32_e32 v83, v82
	s_nop 1
	v_permlane32_swap_b32_e32 v228, v83
	s_nop 1
	v_mov_b32_dpp v83, v228 quad_perm:[0,1,2,3] row_mask:0xc bank_mask:0xf
	v_ashrrev_i32_e32 v81, 31, v80
	s_and_saveexec_b64 s[30:31], s[2:3]
	s_xor_b64 s[60:61], exec, s[30:31]
	s_cbranch_execz .LBB0_641
	s_andn2_saveexec_b64 s[60:61], s[60:61]
	s_cbranch_execz .LBB0_643
	s_branch .LBB0_642

; DI float shx(float v, int m, int lane) { return __builtin_bit_cast(float, __builtin_amdgcn_ds_bpermute((lane ^ m) << 2, __builtin_bit_cast(int, v))); }
;     DI void operator()(const Acc& acc, const Unit& u, int wr, int wc, int fr, int fq) const {
;     ...
;                 for (int ai = 0; ai < 2; ++ai)
; #pragma unroll
;                     for (int m = 0; m < 4; ++m) {
;                         const int r = rowb + ai * HALF + wr * 64 + m * 16 + fr;
;                         const f32x4 a = acc[ai][bj][m][0], c = acc[ai][bj][m][1];
;                         float ss = a[0] * a[0] + a[1] * a[1] + a[2] * a[2] + a[3] * a[3] + c[0] * c[0] + c[1] * c[1] + c[2] * c[2] + c[3] * c[3];
;                         ss += shx(ss, 16, 16 * fq + fr); ss += shx(ss, 32, 16 * fq + fr);
;                         if (fq == 0) ssq[(size_t)r * 20 + (L >> 5)] = ss;
;                         u32x4 o; o[0] = pk_bf16(a[0], a[1]); o[1] = pk_bf16(a[2], a[3]); o[2] = pk_bf16(c[0], c[1]); o[3] = pk_bf16(c[2], c[3]);
;                         bf16_t* dst = L < 384 ? cq + (size_t)r * 384 + L + 8 * fq : ckv + (size_t)r * 256 + (L - 384) + 8 * fq;
;                         *(u32x4*)dst = o;
;                     }
.LBB0_647:
	v_cvt_pk_bf16_f32 v76, v76, v77
	v_cvt_pk_bf16_f32 v77, v78, v79
	v_cvt_pk_bf16_f32 v78, v72, v73
	v_cvt_pk_bf16_f32 v79, v74, v75
	s_waitcnt lgkmcnt(0)
	v_lshl_add_u64 v[72:73], v[82:83], 0, v[168:169]
	global_store_dwordx4 v[72:73], v[76:79], off
	v_mul_f32_e32 v73, v69, v69
	v_fmac_f32_e32 v73, v68, v68
	v_fmac_f32_e32 v73, v70, v70
	v_fmac_f32_e32 v73, v71, v71
	v_fmac_f32_e32 v73, v64, v64
	v_fmac_f32_e32 v73, v65, v65
	v_fmac_f32_e32 v73, v66, v66
	v_fmac_f32_e32 v73, v67, v67
	v_mov_b32_e32 v228, v73
	v_mov_b32_e32 v74, v73
	s_nop 1
	v_permlane16_swap_b32_e32 v228, v74
	s_nop 1
	v_mov_b32_dpp v74, v228 quad_perm:[0,1,2,3] row_mask:0xa bank_mask:0xf
	v_add_u32_e32 v72, 0xb0, v156
	s_waitcnt lgkmcnt(0)
	v_add_f32_e32 v74, v73, v74
	v_mov_b32_e32 v228, v74
	v_mov_b32_e32 v75, v74
	s_nop 1
	v_permlane32_swap_b32_e32 v228, v75
	s_nop 1
	v_mov_b32_dpp v75, v228 quad_perm:[0,1,2,3] row_mask:0xc bank_mask:0xf
	v_ashrrev_i32_e32 v73, 31, v72
	s_and_saveexec_b64 s[30:31], s[2:3]
	s_xor_b64 s[60:61], exec, s[30:31]
	s_andn2_saveexec_b64 s[60:61], s[60:61]
	s_cbranch_execz .LBB0_651
	v_readlane_b32 s30, v254, 42
	v_readlane_b32 s31, v254, 43
	s_waitcnt lgkmcnt(0)
	v_add_f32_e32 v76, v74, v75
	s_movk_i32 s27, 0x50
	v_mov_b64_e32 v[74:75], s[30:31]
	v_mad_i64_i32 v[74:75], s[30:31], v72, s27, v[74:75]
	v_lshl_add_u64 v[74:75], s[56:57], 2, v[74:75]
	global_store_dword v[74:75], v76, off

; DI float shx(float v, int m, int lane) { return __builtin_bit_cast(float, __builtin_amdgcn_ds_bpermute((lane ^ m) << 2, __builtin_bit_cast(int, v))); }
;     DI void operator()(const Acc& acc, const Unit& u, int wr, int wc, int fr, int fq) const {
;     ...
;                 for (int ai = 0; ai < 2; ++ai)
; #pragma unroll
;                     for (int m = 0; m < 4; ++m) {
;                         const int r = rowb + ai * HALF + wr * 64 + m * 16 + fr;
;                         const f32x4 a = acc[ai][bj][m][0], c = acc[ai][bj][m][1];
;                         float ss = a[0] * a[0] + a[1] * a[1] + a[2] * a[2] + a[3] * a[3] + c[0] * c[0] + c[1] * c[1] + c[2] * c[2] + c[3] * c[3];
;                         ss += shx(ss, 16, 16 * fq + fr); ss += shx(ss, 32, 16 * fq + fr);
;                         if (fq == 0) ssq[(size_t)r * 20 + (L >> 5)] = ss;
;                         u32x4 o; o[0] = pk_bf16(a[0], a[1]); o[1] = pk_bf16(a[2], a[3]); o[2] = pk_bf16(c[0], c[1]); o[3] = pk_bf16(c[2], c[3]);
;                         bf16_t* dst = L < 384 ? cq + (size_t)r * 384 + L + 8 * fq : ckv + (size_t)r * 256 + (L - 384) + 8 * fq;
;                         *(u32x4*)dst = o;
;                     }
.LBB0_657:
	v_mul_f32_e32 v64, v57, v57
	v_fmac_f32_e32 v64, v56, v56
	v_fmac_f32_e32 v64, v58, v58
	v_fmac_f32_e32 v64, v59, v59
	v_fmac_f32_e32 v64, v60, v60
	v_fmac_f32_e32 v64, v61, v61
	v_fmac_f32_e32 v64, v62, v62
	v_fmac_f32_e32 v64, v63, v63
	v_mov_b32_e32 v228, v64
	v_mov_b32_e32 v65, v64
	s_nop 1
	v_permlane16_swap_b32_e32 v228, v65
	s_nop 1
	v_mov_b32_dpp v65, v228 quad_perm:[0,1,2,3] row_mask:0xa bank_mask:0xf
	v_ashrrev_i32_e32 v157, 31, v156
	s_waitcnt lgkmcnt(0)
	v_add_f32_e32 v64, v64, v65
	v_mov_b32_e32 v228, v64
	v_mov_b32_e32 v65, v64
	s_nop 1
	v_permlane32_swap_b32_e32 v228, v65
	s_nop 1
	v_mov_b32_dpp v65, v228 quad_perm:[0,1,2,3] row_mask:0xc bank_mask:0xf
	s_and_saveexec_b64 s[4:5], s[2:3]
	s_xor_b64 s[4:5], exec, s[4:5]
	s_or_saveexec_b64 s[4:5], s[4:5]
	s_ashr_i32 s56, s27, 5
	s_ashr_i32 s57, s56, 31
	s_xor_b64 exec, exec, s[4:5]
	s_cbranch_execz .LBB0_661
	v_readlane_b32 s28, v254, 42
	v_readlane_b32 s29, v254, 43
	s_waitcnt lgkmcnt(0)
	v_add_f32_e32 v66, v64, v65
	s_movk_i32 s26, 0x50
	v_mov_b64_e32 v[64:65], s[28:29]
	v_mad_i64_i32 v[64:65], s[28:29], v156, s26, v[64:65]
	v_lshl_add_u64 v[64:65], s[56:57], 2, v[64:65]
	global_store_dword v[64:65], v66, off

; DI float shx(float v, int m, int lane) { return __builtin_bit_cast(float, __builtin_amdgcn_ds_bpermute((lane ^ m) << 2, __builtin_bit_cast(int, v))); }
;     DI void operator()(const Acc& acc, const Unit& u, int wr, int wc, int fr, int fq) const {
;     ...
;                 for (int ai = 0; ai < 2; ++ai)
; #pragma unroll
;                     for (int m = 0; m < 4; ++m) {
;                         const int r = rowb + ai * HALF + wr * 64 + m * 16 + fr;
;                         const f32x4 a = acc[ai][bj][m][0], c = acc[ai][bj][m][1];
;                         float ss = a[0] * a[0] + a[1] * a[1] + a[2] * a[2] + a[3] * a[3] + c[0] * c[0] + c[1] * c[1] + c[2] * c[2] + c[3] * c[3];
;                         ss += shx(ss, 16, 16 * fq + fr); ss += shx(ss, 32, 16 * fq + fr);
;                         if (fq == 0) ssq[(size_t)r * 20 + (L >> 5)] = ss;
;                         u32x4 o; o[0] = pk_bf16(a[0], a[1]); o[1] = pk_bf16(a[2], a[3]); o[2] = pk_bf16(c[0], c[1]); o[3] = pk_bf16(c[2], c[3]);
;                         bf16_t* dst = L < 384 ? cq + (size_t)r * 384 + L + 8 * fq : ckv + (size_t)r * 256 + (L - 384) + 8 * fq;
;                         *(u32x4*)dst = o;
;                     }
.LBB0_665:
	v_lshlrev_b32_e32 v168, 1, v134
	v_cvt_pk_bf16_f32 v56, v56, v57
	v_cvt_pk_bf16_f32 v57, v58, v59
	v_cvt_pk_bf16_f32 v58, v60, v61
	v_cvt_pk_bf16_f32 v59, v62, v63
	s_waitcnt lgkmcnt(0)
	v_lshl_add_u64 v[60:61], v[64:65], 0, v[168:169]
	global_store_dwordx4 v[60:61], v[56:59], off
	s_nop 1
	v_mul_f32_e32 v57, v53, v53
	v_fmac_f32_e32 v57, v52, v52
	v_fmac_f32_e32 v57, v54, v54
	v_fmac_f32_e32 v57, v55, v55
	v_fmac_f32_e32 v57, v48, v48
	v_fmac_f32_e32 v57, v49, v49
	v_fmac_f32_e32 v57, v50, v50
	v_fmac_f32_e32 v57, v51, v51
	v_mov_b32_e32 v228, v57
	v_mov_b32_e32 v58, v57
	s_nop 1
	v_permlane16_swap_b32_e32 v228, v58
	s_nop 1
	v_mov_b32_dpp v58, v228 quad_perm:[0,1,2,3] row_mask:0xa bank_mask:0xf
	v_or_b32_e32 v56, 16, v156
	s_waitcnt lgkmcnt(0)
	v_add_f32_e32 v58, v57, v58
	v_mov_b32_e32 v228, v58
	v_mov_b32_e32 v59, v58
	s_nop 1
	v_permlane32_swap_b32_e32 v228, v59
	s_nop 1
	v_mov_b32_dpp v59, v228 quad_perm:[0,1,2,3] row_mask:0xc bank_mask:0xf
	v_ashrrev_i32_e32 v57, 31, v56
	s_and_saveexec_b64 s[4:5], s[2:3]
	s_xor_b64 s[4:5], exec, s[4:5]
	s_andn2_saveexec_b64 s[4:5], s[4:5]
	s_cbranch_execz .LBB0_669
	v_readlane_b32 s26, v254, 42
	v_readlane_b32 s27, v254, 43
	s_waitcnt lgkmcnt(0)
	v_add_f32_e32 v60, v58, v59
	v_mov_b64_e32 v[58:59], s[26:27]
	s_movk_i32 s26, 0x50
	v_mad_i64_i32 v[58:59], s[26:27], v56, s26, v[58:59]
	v_lshl_add_u64 v[58:59], s[56:57], 2, v[58:59]
	global_store_dword v[58:59], v60, off

; DI float shx(float v, int m, int lane) { return __builtin_bit_cast(float, __builtin_amdgcn_ds_bpermute((lane ^ m) << 2, __builtin_bit_cast(int, v))); }
;     DI void operator()(const Acc& acc, const Unit& u, int wr, int wc, int fr, int fq) const {
;     ...
;                 for (int ai = 0; ai < 2; ++ai)
; #pragma unroll
;                     for (int m = 0; m < 4; ++m) {
;                         const int r = rowb + ai * HALF + wr * 64 + m * 16 + fr;
;                         const f32x4 a = acc[ai][bj][m][0], c = acc[ai][bj][m][1];
;                         float ss = a[0] * a[0] + a[1] * a[1] + a[2] * a[2] + a[3] * a[3] + c[0] * c[0] + c[1] * c[1] + c[2] * c[2] + c[3] * c[3];
;                         ss += shx(ss, 16, 16 * fq + fr); ss += shx(ss, 32, 16 * fq + fr);
;                         if (fq == 0) ssq[(size_t)r * 20 + (L >> 5)] = ss;
;                         u32x4 o; o[0] = pk_bf16(a[0], a[1]); o[1] = pk_bf16(a[2], a[3]); o[2] = pk_bf16(c[0], c[1]); o[3] = pk_bf16(c[2], c[3]);
;                         bf16_t* dst = L < 384 ? cq + (size_t)r * 384 + L + 8 * fq : ckv + (size_t)r * 256 + (L - 384) + 8 * fq;
;                         *(u32x4*)dst = o;
.LBB0_673:
	v_cvt_pk_bf16_f32 v52, v52, v53
	v_cvt_pk_bf16_f32 v53, v54, v55
	v_cvt_pk_bf16_f32 v54, v48, v49
	v_cvt_pk_bf16_f32 v55, v50, v51
	s_waitcnt lgkmcnt(0)
	v_lshl_add_u64 v[48:49], v[58:59], 0, v[168:169]
	global_store_dwordx4 v[48:49], v[52:55], off
	v_mul_f32_e32 v49, v45, v45
	v_fmac_f32_e32 v49, v44, v44
	v_fmac_f32_e32 v49, v46, v46
	v_fmac_f32_e32 v49, v47, v47
	v_fmac_f32_e32 v49, v40, v40
	v_fmac_f32_e32 v49, v41, v41
	v_fmac_f32_e32 v49, v42, v42
	v_fmac_f32_e32 v49, v43, v43
	v_mov_b32_e32 v228, v49
	v_mov_b32_e32 v50, v49
	s_nop 1
	v_permlane16_swap_b32_e32 v228, v50
	s_nop 1
	v_mov_b32_dpp v50, v228 quad_perm:[0,1,2,3] row_mask:0xa bank_mask:0xf
	v_or_b32_e32 v48, 32, v156
	s_waitcnt lgkmcnt(0)
	v_add_f32_e32 v50, v49, v50
	v_mov_b32_e32 v228, v50
	v_mov_b32_e32 v51, v50
	s_nop 1
	v_permlane32_swap_b32_e32 v228, v51
	s_nop 1
	v_mov_b32_dpp v51, v228 quad_perm:[0,1,2,3] row_mask:0xc bank_mask:0xf
	v_ashrrev_i32_e32 v49, 31, v48
	s_and_saveexec_b64 s[26:27], s[2:3]
	s_xor_b64 s[58:59], exec, s[26:27]
	s_cbranch_execz .LBB0_675
	s_andn2_saveexec_b64 s[58:59], s[58:59]
	s_cbranch_execz .LBB0_677
	s_branch .LBB0_676

; DI float shx(float v, int m, int lane) { return __builtin_bit_cast(float, __builtin_amdgcn_ds_bpermute((lane ^ m) << 2, __builtin_bit_cast(int, v))); }
;     DI void operator()(const Acc& acc, const Unit& u, int wr, int wc, int fr, int fq) const {
;     ...
;                 for (int ai = 0; ai < 2; ++ai)
; #pragma unroll
;                     for (int m = 0; m < 4; ++m) {
;                         const int r = rowb + ai * HALF + wr * 64 + m * 16 + fr;
;                         const f32x4 a = acc[ai][bj][m][0], c = acc[ai][bj][m][1];
;                         float ss = a[0] * a[0] + a[1] * a[1] + a[2] * a[2] + a[3] * a[3] + c[0] * c[0] + c[1] * c[1] + c[2] * c[2] + c[3] * c[3];
;                         ss += shx(ss, 16, 16 * fq + fr); ss += shx(ss, 32, 16 * fq + fr);
;                         if (fq == 0) ssq[(size_t)r * 20 + (L >> 5)] = ss;
;                         u32x4 o; o[0] = pk_bf16(a[0], a[1]); o[1] = pk_bf16(a[2], a[3]); o[2] = pk_bf16(c[0], c[1]); o[3] = pk_bf16(c[2], c[3]);
;                         bf16_t* dst = L < 384 ? cq + (size_t)r * 384 + L + 8 * fq : ckv + (size_t)r * 256 + (L - 384) + 8 * fq;
;                         *(u32x4*)dst = o;
.LBB0_681:
	v_cvt_pk_bf16_f32 v44, v44, v45
	v_cvt_pk_bf16_f32 v45, v46, v47
	v_cvt_pk_bf16_f32 v46, v40, v41
	v_cvt_pk_bf16_f32 v47, v42, v43
	s_waitcnt lgkmcnt(0)
	v_lshl_add_u64 v[40:41], v[50:51], 0, v[168:169]
	global_store_dwordx4 v[40:41], v[44:47], off
	v_mul_f32_e32 v41, v37, v37
	v_fmac_f32_e32 v41, v36, v36
	v_fmac_f32_e32 v41, v38, v38
	v_fmac_f32_e32 v41, v39, v39
	v_fmac_f32_e32 v41, v32, v32
	v_fmac_f32_e32 v41, v33, v33
	v_fmac_f32_e32 v41, v34, v34
	v_fmac_f32_e32 v41, v35, v35
	v_mov_b32_e32 v228, v41
	v_mov_b32_e32 v42, v41
	s_nop 1
	v_permlane16_swap_b32_e32 v228, v42
	s_nop 1
	v_mov_b32_dpp v42, v228 quad_perm:[0,1,2,3] row_mask:0xa bank_mask:0xf
	v_or_b32_e32 v40, 48, v156
	s_waitcnt lgkmcnt(0)
	v_add_f32_e32 v42, v41, v42
	v_mov_b32_e32 v228, v42
	v_mov_b32_e32 v43, v42
	s_nop 1
	v_permlane32_swap_b32_e32 v228, v43
	s_nop 1
	v_mov_b32_dpp v43, v228 quad_perm:[0,1,2,3] row_mask:0xc bank_mask:0xf
	v_ashrrev_i32_e32 v41, 31, v40
	s_and_saveexec_b64 s[26:27], s[2:3]
	s_xor_b64 s[58:59], exec, s[26:27]
	s_cbranch_execz .LBB0_683
	s_andn2_saveexec_b64 s[58:59], s[58:59]
	s_cbranch_execz .LBB0_685
	s_branch .LBB0_684

; DI float shx(float v, int m, int lane) { return __builtin_bit_cast(float, __builtin_amdgcn_ds_bpermute((lane ^ m) << 2, __builtin_bit_cast(int, v))); }
;     DI void operator()(const Acc& acc, const Unit& u, int wr, int wc, int fr, int fq) const {
;     ...
;                 for (int ai = 0; ai < 2; ++ai)
; #pragma unroll
;                     for (int m = 0; m < 4; ++m) {
;                         const int r = rowb + ai * HALF + wr * 64 + m * 16 + fr;
;                         const f32x4 a = acc[ai][bj][m][0], c = acc[ai][bj][m][1];
;                         float ss = a[0] * a[0] + a[1] * a[1] + a[2] * a[2] + a[3] * a[3] + c[0] * c[0] + c[1] * c[1] + c[2] * c[2] + c[3] * c[3];
;                         ss += shx(ss, 16, 16 * fq + fr); ss += shx(ss, 32, 16 * fq + fr);
;                         if (fq == 0) ssq[(size_t)r * 20 + (L >> 5)] = ss;
;                         u32x4 o; o[0] = pk_bf16(a[0], a[1]); o[1] = pk_bf16(a[2], a[3]); o[2] = pk_bf16(c[0], c[1]); o[3] = pk_bf16(c[2], c[3]);
;                         bf16_t* dst = L < 384 ? cq + (size_t)r * 384 + L + 8 * fq : ckv + (size_t)r * 256 + (L - 384) + 8 * fq;
;                         *(u32x4*)dst = o;
.LBB0_689:
	v_cvt_pk_bf16_f32 v36, v36, v37
	v_cvt_pk_bf16_f32 v37, v38, v39
	v_cvt_pk_bf16_f32 v38, v32, v33
	v_cvt_pk_bf16_f32 v39, v34, v35
	s_waitcnt lgkmcnt(0)
	v_lshl_add_u64 v[32:33], v[42:43], 0, v[168:169]
	global_store_dwordx4 v[32:33], v[36:39], off
	v_mul_f32_e32 v33, v29, v29
	v_fmac_f32_e32 v33, v28, v28
	v_fmac_f32_e32 v33, v30, v30
	v_fmac_f32_e32 v33, v31, v31
	v_fmac_f32_e32 v33, v24, v24
	v_fmac_f32_e32 v33, v25, v25
	v_fmac_f32_e32 v33, v26, v26
	v_fmac_f32_e32 v33, v27, v27
	v_mov_b32_e32 v228, v33
	v_mov_b32_e32 v34, v33
	s_nop 1
	v_permlane16_swap_b32_e32 v228, v34
	s_nop 1
	v_mov_b32_dpp v34, v228 quad_perm:[0,1,2,3] row_mask:0xa bank_mask:0xf
	v_add_u32_e32 v32, 0x80, v156
	s_waitcnt lgkmcnt(0)
	v_add_f32_e32 v34, v33, v34
	v_mov_b32_e32 v228, v34
	v_mov_b32_e32 v35, v34
	s_nop 1
	v_permlane32_swap_b32_e32 v228, v35
	s_nop 1
	v_mov_b32_dpp v35, v228 quad_perm:[0,1,2,3] row_mask:0xc bank_mask:0xf
	v_ashrrev_i32_e32 v33, 31, v32
	s_and_saveexec_b64 s[26:27], s[2:3]
	s_xor_b64 s[58:59], exec, s[26:27]
	s_cbranch_execz .LBB0_691
	s_andn2_saveexec_b64 s[58:59], s[58:59]
	s_cbranch_execz .LBB0_693
	s_branch .LBB0_692

; DI float shx(float v, int m, int lane) { return __builtin_bit_cast(float, __builtin_amdgcn_ds_bpermute((lane ^ m) << 2, __builtin_bit_cast(int, v))); }
;     DI void operator()(const Acc& acc, const Unit& u, int wr, int wc, int fr, int fq) const {
;     ...
;                 for (int ai = 0; ai < 2; ++ai)
; #pragma unroll
;                     for (int m = 0; m < 4; ++m) {
;                         const int r = rowb + ai * HALF + wr * 64 + m * 16 + fr;
;                         const f32x4 a = acc[ai][bj][m][0], c = acc[ai][bj][m][1];
;                         float ss = a[0] * a[0] + a[1] * a[1] + a[2] * a[2] + a[3] * a[3] + c[0] * c[0] + c[1] * c[1] + c[2] * c[2] + c[3] * c[3];
;                         ss += shx(ss, 16, 16 * fq + fr); ss += shx(ss, 32, 16 * fq + fr);
;                         if (fq == 0) ssq[(size_t)r * 20 + (L >> 5)] = ss;
;                         u32x4 o; o[0] = pk_bf16(a[0], a[1]); o[1] = pk_bf16(a[2], a[3]); o[2] = pk_bf16(c[0], c[1]); o[3] = pk_bf16(c[2], c[3]);
;                         bf16_t* dst = L < 384 ? cq + (size_t)r * 384 + L + 8 * fq : ckv + (size_t)r * 256 + (L - 384) + 8 * fq;
;                         *(u32x4*)dst = o;
.LBB0_697:
	v_cvt_pk_bf16_f32 v28, v28, v29
	v_cvt_pk_bf16_f32 v29, v30, v31
	v_cvt_pk_bf16_f32 v30, v24, v25
	v_cvt_pk_bf16_f32 v31, v26, v27
	s_waitcnt lgkmcnt(0)
	v_lshl_add_u64 v[24:25], v[34:35], 0, v[168:169]
	global_store_dwordx4 v[24:25], v[28:31], off
	v_mul_f32_e32 v25, v21, v21
	v_fmac_f32_e32 v25, v20, v20
	v_fmac_f32_e32 v25, v22, v22
	v_fmac_f32_e32 v25, v23, v23
	v_fmac_f32_e32 v25, v16, v16
	v_fmac_f32_e32 v25, v17, v17
	v_fmac_f32_e32 v25, v18, v18
	v_fmac_f32_e32 v25, v19, v19
	v_mov_b32_e32 v228, v25
	v_mov_b32_e32 v26, v25
	s_nop 1
	v_permlane16_swap_b32_e32 v228, v26
	s_nop 1
	v_mov_b32_dpp v26, v228 quad_perm:[0,1,2,3] row_mask:0xa bank_mask:0xf
	v_add_u32_e32 v24, 0x90, v156
	s_waitcnt lgkmcnt(0)
	v_add_f32_e32 v26, v25, v26
	v_mov_b32_e32 v228, v26
	v_mov_b32_e32 v27, v26
	s_nop 1
	v_permlane32_swap_b32_e32 v228, v27
	s_nop 1
	v_mov_b32_dpp v27, v228 quad_perm:[0,1,2,3] row_mask:0xc bank_mask:0xf
	v_ashrrev_i32_e32 v25, 31, v24
	s_and_saveexec_b64 s[26:27], s[2:3]
	s_xor_b64 s[58:59], exec, s[26:27]
	s_cbranch_execz .LBB0_699
	s_andn2_saveexec_b64 s[58:59], s[58:59]
	s_cbranch_execz .LBB0_701
	s_branch .LBB0_700

; DI float shx(float v, int m, int lane) { return __builtin_bit_cast(float, __builtin_amdgcn_ds_bpermute((lane ^ m) << 2, __builtin_bit_cast(int, v))); }
;     DI void operator()(const Acc& acc, const Unit& u, int wr, int wc, int fr, int fq) const {
;     ...
;                 for (int ai = 0; ai < 2; ++ai)
; #pragma unroll
;                     for (int m = 0; m < 4; ++m) {
;                         const int r = rowb + ai * HALF + wr * 64 + m * 16 + fr;
;                         const f32x4 a = acc[ai][bj][m][0], c = acc[ai][bj][m][1];
;                         float ss = a[0] * a[0] + a[1] * a[1] + a[2] * a[2] + a[3] * a[3] + c[0] * c[0] + c[1] * c[1] + c[2] * c[2] + c[3] * c[3];
;                         ss += shx(ss, 16, 16 * fq + fr); ss += shx(ss, 32, 16 * fq + fr);
;                         if (fq == 0) ssq[(size_t)r * 20 + (L >> 5)] = ss;
;                         u32x4 o; o[0] = pk_bf16(a[0], a[1]); o[1] = pk_bf16(a[2], a[3]); o[2] = pk_bf16(c[0], c[1]); o[3] = pk_bf16(c[2], c[3]);
;                         bf16_t* dst = L < 384 ? cq + (size_t)r * 384 + L + 8 * fq : ckv + (size_t)r * 256 + (L - 384) + 8 * fq;
;                         *(u32x4*)dst = o;
.LBB0_705:
	v_cvt_pk_bf16_f32 v20, v20, v21
	v_cvt_pk_bf16_f32 v21, v22, v23
	v_cvt_pk_bf16_f32 v22, v16, v17
	v_cvt_pk_bf16_f32 v23, v18, v19
	s_waitcnt lgkmcnt(0)
	v_lshl_add_u64 v[16:17], v[26:27], 0, v[168:169]
	global_store_dwordx4 v[16:17], v[20:23], off
	v_mul_f32_e32 v17, v13, v13
	v_fmac_f32_e32 v17, v12, v12
	v_fmac_f32_e32 v17, v14, v14
	v_fmac_f32_e32 v17, v15, v15
	v_fmac_f32_e32 v17, v8, v8
	v_fmac_f32_e32 v17, v9, v9
	v_fmac_f32_e32 v17, v10, v10
	v_fmac_f32_e32 v17, v11, v11
	v_mov_b32_e32 v228, v17
	v_mov_b32_e32 v18, v17
	s_nop 1
	v_permlane16_swap_b32_e32 v228, v18
	s_nop 1
	v_mov_b32_dpp v18, v228 quad_perm:[0,1,2,3] row_mask:0xa bank_mask:0xf
	v_add_u32_e32 v16, 0xa0, v156
	s_waitcnt lgkmcnt(0)
	v_add_f32_e32 v18, v17, v18
	v_mov_b32_e32 v228, v18
	v_mov_b32_e32 v19, v18
	s_nop 1
	v_permlane32_swap_b32_e32 v228, v19
	s_nop 1
	v_mov_b32_dpp v19, v228 quad_perm:[0,1,2,3] row_mask:0xc bank_mask:0xf
	v_ashrrev_i32_e32 v17, 31, v16
	s_and_saveexec_b64 s[26:27], s[2:3]
	s_xor_b64 s[58:59], exec, s[26:27]
	s_cbranch_execz .LBB0_707
	s_andn2_saveexec_b64 s[58:59], s[58:59]
	s_cbranch_execz .LBB0_709
	s_branch .LBB0_708

; DI float shx(float v, int m, int lane) { return __builtin_bit_cast(float, __builtin_amdgcn_ds_bpermute((lane ^ m) << 2, __builtin_bit_cast(int, v))); }
;     DI void operator()(const Acc& acc, const Unit& u, int wr, int wc, int fr, int fq) const {
;     ...
;                 for (int ai = 0; ai < 2; ++ai)
; #pragma unroll
;                     for (int m = 0; m < 4; ++m) {
;                         const int r = rowb + ai * HALF + wr * 64 + m * 16 + fr;
;                         const f32x4 a = acc[ai][bj][m][0], c = acc[ai][bj][m][1];
;                         float ss = a[0] * a[0] + a[1] * a[1] + a[2] * a[2] + a[3] * a[3] + c[0] * c[0] + c[1] * c[1] + c[2] * c[2] + c[3] * c[3];
;                         ss += shx(ss, 16, 16 * fq + fr); ss += shx(ss, 32, 16 * fq + fr);
;                         if (fq == 0) ssq[(size_t)r * 20 + (L >> 5)] = ss;
;                         u32x4 o; o[0] = pk_bf16(a[0], a[1]); o[1] = pk_bf16(a[2], a[3]); o[2] = pk_bf16(c[0], c[1]); o[3] = pk_bf16(c[2], c[3]);
;                         bf16_t* dst = L < 384 ? cq + (size_t)r * 384 + L + 8 * fq : ckv + (size_t)r * 256 + (L - 384) + 8 * fq;
;                         *(u32x4*)dst = o;
.LBB0_713:
	v_cvt_pk_bf16_f32 v12, v12, v13
	v_cvt_pk_bf16_f32 v13, v14, v15
	v_cvt_pk_bf16_f32 v14, v8, v9
	v_cvt_pk_bf16_f32 v15, v10, v11
	s_waitcnt lgkmcnt(0)
	v_lshl_add_u64 v[8:9], v[18:19], 0, v[168:169]
	global_store_dwordx4 v[8:9], v[12:15], off
	v_mul_f32_e32 v9, v5, v5
	v_fmac_f32_e32 v9, v4, v4
	v_fmac_f32_e32 v9, v6, v6
	v_fmac_f32_e32 v9, v7, v7
	v_fmac_f32_e32 v9, v0, v0
	v_fmac_f32_e32 v9, v1, v1
	v_fmac_f32_e32 v9, v2, v2
	v_fmac_f32_e32 v9, v3, v3
	v_mov_b32_e32 v228, v9
	v_mov_b32_e32 v10, v9
	s_nop 1
	v_permlane16_swap_b32_e32 v228, v10
	s_nop 1
	v_mov_b32_dpp v10, v228 quad_perm:[0,1,2,3] row_mask:0xa bank_mask:0xf
	v_add_u32_e32 v8, 0xb0, v156
	s_waitcnt lgkmcnt(0)
	v_add_f32_e32 v10, v9, v10
	v_mov_b32_e32 v228, v10
	v_mov_b32_e32 v11, v10
	s_nop 1
	v_permlane32_swap_b32_e32 v228, v11
	s_nop 1
	v_mov_b32_dpp v11, v228 quad_perm:[0,1,2,3] row_mask:0xc bank_mask:0xf
	v_ashrrev_i32_e32 v9, 31, v8
	s_and_saveexec_b64 s[26:27], s[2:3]
	s_xor_b64 s[58:59], exec, s[26:27]
	s_cbranch_execz .LBB0_715
	s_andn2_saveexec_b64 s[58:59], s[58:59]
	s_cbranch_execz .LBB0_717
	s_branch .LBB0_716

; #define LAS __attribute__((address_space(3)))
; DI float shx(float v, int m, int lane) { return __builtin_bit_cast(float, __builtin_amdgcn_ds_bpermute((lane ^ m) << 2, __builtin_bit_cast(int, v))); }
;     DI void operator()(const Acc& acc, const Unit& u, int wr, int wc, int fr, int fq) const {
;     ...
;         if (tile <= 4) {
;             const float* gn = tile < 4 ? qn : kn;
;             f32x4 g[2][2];
; #pragma unroll
;             for (int bj = 0; bj < 2; ++bj)
; #pragma unroll
;                 for (int n = 0; n < 2; ++n) g[bj][n] = *(const f32x4*)(gn + dbase + 16 * bj + 4 * n);
; #pragma unroll
;             for (int ai = 0; ai < 2; ++ai)
; #pragma unroll
;                 for (int m = 0; m < 4; ++m) {
;                     const int rl = ai * HALF + wr * 64 + m * 16 + fr, r = rowb + rl;
;                     float ss = 0.f;
; #pragma unroll
;                     for (int bj = 0; bj < 2; ++bj)
; #pragma unroll
;                         for (int n = 0; n < 2; ++n) { const f32x4 a = acc[ai][bj][m][n]; ss += a[0] * a[0] + a[1] * a[1] + a[2] * a[2] + a[3] * a[3]; }
;                     ss += shx(ss, 16, 16 * fq + fr); ss += shx(ss, 32, 16 * fq + fr);
;                     const float rstd = rsqrtf(ss * (1.f / 64.f) + LN_EPS);
;                     f32x4 v[2][2];
; #pragma unroll
;                     for (int bj = 0; bj < 2; ++bj)
; #pragma unroll
;                         for (int n = 0; n < 2; ++n) v[bj][n] = acc[ai][bj][m][n] * rstd * g[bj][n];
;                     if (latent) {
;                         const int s = s0 + rl, pos = (fq >> 1) ? (s & 63) : (s >> 6);
; #pragma unroll
;                         for (int n = 0; n < 2; ++n) {
;                             const LAS float* tp = tab + (pos * 16 + 8 * (fq & 1) + 4 * n) * 2;
;                             const f32x4 t0 = *(const LAS f32x4*)tp, t1 = *(const LAS f32x4*)(tp + 4);
;                             const f32x4 cs = {t0[0], t0[2], t1[0], t1[2]}, sn = {t0[1], t0[3], t1[1], t1[3]};
;                             const f32x4 x1 = v[0][n], x2 = v[1][n];
;                             v[0][n] = x1 * cs - x2 * sn; v[1][n] = x2 * cs + x1 * sn;
.LBB0_750:
	s_andn2_b64 vcc, exec, s[2:3]
	s_cbranch_vccnz .LBB0_732
	v_writelane_b32 v255, s16, 27
	s_cmp_eq_u32 s21, 4
	s_mov_b64 s[60:61], s[44:45]
	v_writelane_b32 v255, s17, 28
	s_mov_b64 s[16:17], s[42:43]
	s_mov_b32 s24, s39
	s_mov_b32 s25, s38
	s_mov_b64 s[52:53], s[36:37]
	s_cselect_b64 s[2:3], -1, 0
	v_readlane_b32 s36, v254, 11
	s_and_b64 s[4:5], s[2:3], exec
	v_readlane_b32 s37, v254, 12
	v_readlane_b32 s42, v254, 17
	v_readlane_b32 s44, v254, 19
	v_readlane_b32 s43, v254, 18
	v_readlane_b32 s45, v254, 20
	s_cselect_b32 s4, s44, s42
	v_readlane_b32 s36, v255, 19
	s_cselect_b32 s5, s45, s43
	v_readlane_b32 s37, v255, 20
	s_add_u32 s4, s4, s36
	s_addc_u32 s5, s5, s37
	v_lshlrev_b32_e32 v72, 2, v150
	global_load_dwordx4 v[68:71], v72, s[4:5] offset:16
	global_load_dwordx4 v[76:79], v72, s[4:5]
	global_load_dwordx4 v[64:67], v72, s[4:5] offset:80
	s_nop 0
	global_load_dwordx4 v[72:75], v72, s[4:5] offset:64
	v_mov_b32_e32 v172, v137
	v_mov_b32_e32 v173, v141
	v_mov_b32_e32 v170, v136
	v_mov_b32_e32 v171, v140
	v_pk_mul_f32 v[172:173], v[172:173], v[172:173]
	v_mov_b32_e32 v188, v129
	v_pk_fma_f32 v[170:171], v[170:171], v[170:171], v[172:173]
	v_mov_b32_e32 v172, v138
	v_mov_b32_e32 v173, v142
	v_pk_fma_f32 v[170:171], v[172:173], v[172:173], v[170:171]
	v_mov_b32_e32 v172, v139
	v_mov_b32_e32 v173, v143
	v_mov_b32_e32 v189, v133
	v_pk_fma_f32 v[170:171], v[172:173], v[172:173], v[170:171]
	v_mov_b32_e32 v172, v128
	v_mov_b32_e32 v173, v132
	v_pk_mul_f32 v[188:189], v[188:189], v[188:189]
	v_add_f32_e32 v170, v170, v171
	v_pk_fma_f32 v[172:173], v[172:173], v[172:173], v[188:189]
	v_mov_b32_e32 v188, v130
	v_mov_b32_e32 v189, v134
	v_pk_fma_f32 v[172:173], v[188:189], v[188:189], v[172:173]
	v_mov_b32_e32 v188, v131
	v_mov_b32_e32 v189, v135
	v_pk_fma_f32 v[172:173], v[188:189], v[188:189], v[172:173]
	s_mov_b32 s4, 0x800000
	v_add_f32_e32 v170, v173, v170
	v_add_f32_e32 v170, v172, v170
	v_mov_b32_e32 v228, v170
	v_mov_b32_e32 v171, v170
	s_nop 1
	v_permlane16_swap_b32_e32 v228, v171
	s_nop 1
	v_mov_b32_dpp v171, v228 quad_perm:[0,1,2,3] row_mask:0xa bank_mask:0xf
	v_readlane_b32 s38, v254, 13
	v_readlane_b32 s39, v254, 14
	v_readlane_b32 s40, v254, 15
	v_readlane_b32 s41, v254, 16
	s_waitcnt lgkmcnt(0)
	v_add_f32_e32 v170, v170, v171
	v_mov_b32_e32 v228, v170
	v_mov_b32_e32 v171, v170
	s_nop 1
	v_permlane32_swap_b32_e32 v228, v171
	s_nop 1
	v_mov_b32_dpp v171, v228 quad_perm:[0,1,2,3] row_mask:0xc bank_mask:0xf
	v_readlane_b32 s46, v254, 21
	v_readlane_b32 s47, v254, 22
	v_readlane_b32 s48, v254, 23
	v_readlane_b32 s49, v254, 24
	s_waitcnt lgkmcnt(0)
	v_add_f32_e32 v170, v170, v171
	v_fmamk_f32 v170, v170, 0x3c800000, v250
	v_cmp_gt_f32_e32 vcc, s4, v170
	v_mul_f32_e32 v171, 0x4b800000, v170
	v_readlane_b32 s50, v254, 25
	v_cndmask_b32_e32 v170, v170, v171, vcc
	v_rsq_f32_e32 v170, v170
	v_readlane_b32 s51, v254, 26
	v_mul_f32_e32 v171, 0x45800000, v170
	v_cndmask_b32_e32 v170, v170, v171, vcc
	v_pk_mul_f32 v[172:173], v[132:133], v[170:171] op_sel_hi:[1,0]
	v_pk_mul_f32 v[140:141], v[140:141], v[170:171] op_sel_hi:[1,0]
	v_pk_mul_f32 v[142:143], v[142:143], v[170:171] op_sel_hi:[1,0]
	v_pk_mul_f32 v[136:137], v[136:137], v[170:171] op_sel_hi:[1,0]
	v_pk_mul_f32 v[138:139], v[138:139], v[170:171] op_sel_hi:[1,0]
	v_pk_mul_f32 v[132:133], v[134:135], v[170:171] op_sel_hi:[1,0]
	s_andn2_b64 vcc, exec, s[58:59]
	s_waitcnt vmcnt(0)
	v_mul_f32_e32 v64, 0x3ed96d27, v64
	v_mul_f32_e32 v65, 0x3ed96d27, v65
	v_mul_f32_e32 v66, 0x3ed96d27, v66
	v_mul_f32_e32 v67, 0x3ed96d27, v67
	v_mul_f32_e32 v68, 0x3ed96d27, v68
	v_mul_f32_e32 v69, 0x3ed96d27, v69
	v_mul_f32_e32 v70, 0x3ed96d27, v70
	v_mul_f32_e32 v71, 0x3ed96d27, v71
	v_mul_f32_e32 v72, 0x3ed96d27, v72
	v_mul_f32_e32 v73, 0x3ed96d27, v73
	v_mul_f32_e32 v74, 0x3ed96d27, v74
	v_mul_f32_e32 v75, 0x3ed96d27, v75
	v_mul_f32_e32 v76, 0x3ed96d27, v76
	v_mul_f32_e32 v77, 0x3ed96d27, v77
	v_mul_f32_e32 v78, 0x3ed96d27, v78
	v_mul_f32_e32 v79, 0x3ed96d27, v79
	v_pk_mul_f32 v[138:139], v[70:71], v[138:139]
	v_pk_mul_f32 v[142:143], v[78:79], v[142:143]
	v_pk_mul_f32 v[140:141], v[76:77], v[140:141]
	v_pk_mul_f32 v[134:135], v[72:73], v[172:173]
	v_pk_mul_f32 v[172:173], v[128:129], v[170:171] op_sel_hi:[1,0]
	v_pk_mul_f32 v[128:129], v[130:131], v[170:171] op_sel_hi:[1,0]
	v_cndmask_b32_e64 v170, 0, 1, s[58:59]
	v_pk_mul_f32 v[136:137], v[68:69], v[136:137]
	v_pk_mul_f32 v[132:133], v[74:75], v[132:133]
	v_pk_mul_f32 v[128:129], v[66:67], v[128:129]
	v_pk_mul_f32 v[130:131], v[64:65], v[172:173]
	v_cmp_ne_u32_e64 s[4:5], 1, v170
	s_cbranch_vccnz .LBB0_753
	s_mov_b32 s39, s24
	s_add_i32 s24, s20, s24
	s_lshr_b32 s24, s24, 6
	v_mov_b32_e32 v170, s24
	s_mov_b64 s[44:45], s[60:61]
	v_cndmask_b32_e64 v170, v151, v170, s[44:45]
	v_lshlrev_b32_e32 v200, 7, v170
	v_add_u32_e32 v170, v185, v200
	ds_read_b128 v[188:191], v170
	ds_read_b128 v[192:195], v170 offset:16
	s_mov_b32 s38, s25
	s_waitcnt lgkmcnt(1)
	v_mov_b32_e32 v170, v189
	v_mov_b32_e32 v171, v191
	v_mov_b32_e32 v189, v190
	v_pk_mul_f32 v[172:173], v[134:135], v[170:171]
	s_waitcnt lgkmcnt(0)
	v_mov_b32_e32 v198, v193
	v_mov_b32_e32 v199, v195
	v_mov_b32_e32 v193, v194
	v_pk_mul_f32 v[134:135], v[134:135], v[188:189]
	v_pk_mul_f32 v[196:197], v[132:133], v[198:199]
	v_pk_mul_f32 v[132:133], v[132:133], v[192:193]
	v_pk_fma_f32 v[134:135], v[140:141], v[170:171], v[134:135]
	v_add_u32_e32 v170, v186, v200
	v_pk_fma_f32 v[196:197], v[142:143], v[192:193], v[196:197] neg_lo:[0,0,1] neg_hi:[0,0,1]
	v_pk_fma_f32 v[194:195], v[140:141], v[188:189], v[172:173] neg_lo:[0,0,1] neg_hi:[0,0,1]
	v_pk_fma_f32 v[132:133], v[142:143], v[198:199], v[132:133]
	ds_read_b128 v[140:143], v170
	ds_read_b128 v[188:191], v170 offset:16
	s_waitcnt lgkmcnt(1)
	v_mov_b32_e32 v170, v141
	v_mov_b32_e32 v171, v143
	v_pk_mul_f32 v[172:173], v[130:131], v[170:171]
	s_waitcnt lgkmcnt(0)
	v_mov_b32_e32 v198, v189
	v_mov_b32_e32 v199, v191
	v_mov_b32_e32 v189, v190
	v_mov_b32_e32 v141, v142
	v_pk_mul_f32 v[192:193], v[128:129], v[198:199]
	v_pk_fma_f32 v[190:191], v[136:137], v[140:141], v[172:173] neg_lo:[0,0,1] neg_hi:[0,0,1]
	v_pk_mul_f32 v[130:131], v[130:131], v[140:141]
	v_pk_mul_f32 v[128:129], v[128:129], v[188:189]
	v_pk_fma_f32 v[192:193], v[138:139], v[188:189], v[192:193] neg_lo:[0,0,1] neg_hi:[0,0,1]
	v_pk_fma_f32 v[128:129], v[138:139], v[198:199], v[128:129]
	v_pk_fma_f32 v[130:131], v[136:137], v[170:171], v[130:131]
	v_mov_b64_e32 v[136:137], v[190:191]
	v_mov_b64_e32 v[140:141], v[194:195]
	v_mov_b64_e32 v[138:139], v[192:193]
	v_mov_b64_e32 v[142:143], v[196:197]
	s_branch .LBB0_754

; #define LAS __attribute__((address_space(3)))
;     DI void operator()(const Acc& acc, const Unit& u, int wr, int wc, int fr, int fq) const {
;     ...
; #pragma unroll
;             for (int ai = 0; ai < 2; ++ai)
; #pragma unroll
;                 for (int m = 0; m < 4; ++m) {
;                     const int rl = ai * HALF + wr * 64 + m * 16 + fr, r = rowb + rl;
;                     float ss = 0.f;
; #pragma unroll
;                     for (int bj = 0; bj < 2; ++bj)
; #pragma unroll
;                         for (int n = 0; n < 2; ++n) { const f32x4 a = acc[ai][bj][m][n]; ss += a[0] * a[0] + a[1] * a[1] + a[2] * a[2] + a[3] * a[3]; }
;                     ss += shx(ss, 16, 16 * fq + fr); ss += shx(ss, 32, 16 * fq + fr);
;                     const float rstd = rsqrtf(ss * (1.f / 64.f) + LN_EPS);
;                     f32x4 v[2][2];
; #pragma unroll
;                     for (int bj = 0; bj < 2; ++bj)
; #pragma unroll
;                         for (int n = 0; n < 2; ++n) v[bj][n] = acc[ai][bj][m][n] * rstd * g[bj][n];
;                     if (latent) {
;                         const int s = s0 + rl, pos = (fq >> 1) ? (s & 63) : (s >> 6);
; #pragma unroll
;                         for (int n = 0; n < 2; ++n) {
;                             const LAS float* tp = tab + (pos * 16 + 8 * (fq & 1) + 4 * n) * 2;
;                             const f32x4 t0 = *(const LAS f32x4*)tp, t1 = *(const LAS f32x4*)(tp + 4);
;                             const f32x4 cs = {t0[0], t0[2], t1[0], t1[2]}, sn = {t0[1], t0[3], t1[1], t1[3]};
;                             const f32x4 x1 = v[0][n], x2 = v[1][n];
;                             v[0][n] = x1 * cs - x2 * sn; v[1][n] = x2 * cs + x1 * sn;
;                         }
;                     }
; #pragma unroll
;                     for (int bj = 0; bj < 2; ++bj) {
;                         u32x4 o; o[0] = pk_bf16(v[bj][0][0], v[bj][0][1]); o[1] = pk_bf16(v[bj][0][2], v[bj][0][3]); o[2] = pk_bf16(v[bj][1][0], v[bj][1][1]); o[3] = pk_bf16(v[bj][1][2], v[bj][1][3]);
;                         bf16_t* dst = tile < 4 ? Q + (size_t)r * 1024 + (tile * 4 + wc) * 64 + dbase + 16 * bj
;                                                : Kd + ((size_t)(b * 4 + wc) * NKEY + kp0 + rl) * 64 + dbase + 16 * bj;
;                         *(u32x4*)dst = o;
.LBB0_754:
	s_lshl_b32 s21, s21, 8
	v_readlane_b32 s24, v255, 26
	s_or_b32 s58, s21, s24
	s_lshl_b32 s21, s23, 2
	s_or_b32 s21, s21, s38
	s_ashr_i32 s59, s58, 31
	s_mul_hi_i32 s23, s21, 0x900
	s_mulk_i32 s21, 0x900
	s_add_u32 s60, s21, s22
	v_add_u32_e32 v170, s19, v148
	s_addc_u32 s61, s23, 0
	v_ashrrev_i32_e32 v171, 31, v170
	v_readlane_b32 s22, v254, 27
	v_lshlrev_b64 v[170:171], 11, v[170:171]
	v_lshl_add_u64 v[172:173], s[60:61], 0, v[148:149]
	v_readlane_b32 s23, v254, 28
	v_lshlrev_b64 v[172:173], 7, v[172:173]
	v_cvt_pk_bf16_f32 v140, v140, v141
	v_cvt_pk_bf16_f32 v141, v142, v143
	v_cvt_pk_bf16_f32 v142, v136, v137
	v_lshl_add_u64 v[136:137], s[22:23], 0, v[170:171]
	v_cvt_pk_bf16_f32 v143, v138, v139
	v_lshl_add_u64 v[136:137], s[58:59], 1, v[136:137]
	v_lshl_add_u64 v[138:139], s[26:27], 0, v[172:173]
	v_cndmask_b32_e64 v137, v137, v139, s[2:3]
	v_cndmask_b32_e64 v136, v136, v138, s[2:3]
	v_lshl_add_u64 v[138:139], v[136:137], 0, v[168:169]
	v_cvt_pk_bf16_f32 v136, v130, v131
	v_mov_b32_e32 v130, v121
	v_mov_b32_e32 v131, v125
	v_cvt_pk_bf16_f32 v137, v128, v129
	v_mov_b32_e32 v128, v120
	v_mov_b32_e32 v129, v124
	v_pk_mul_f32 v[130:131], v[130:131], v[130:131]
	v_cvt_pk_bf16_f32 v134, v134, v135
	v_pk_fma_f32 v[128:129], v[128:129], v[128:129], v[130:131]
	v_mov_b32_e32 v130, v122
	v_mov_b32_e32 v131, v126
	v_cvt_pk_bf16_f32 v135, v132, v133
	v_pk_fma_f32 v[128:129], v[130:131], v[130:131], v[128:129]
	v_mov_b32_e32 v130, v123
	v_mov_b32_e32 v131, v127
	v_mov_b32_e32 v132, v113
	v_mov_b32_e32 v133, v117
	v_pk_fma_f32 v[128:129], v[130:131], v[130:131], v[128:129]
	v_mov_b32_e32 v130, v112
	v_mov_b32_e32 v131, v116
	v_pk_mul_f32 v[132:133], v[132:133], v[132:133]
	v_add_f32_e32 v128, v128, v129
	v_pk_fma_f32 v[130:131], v[130:131], v[130:131], v[132:133]
	v_mov_b32_e32 v132, v114
	v_mov_b32_e32 v133, v118
	v_pk_fma_f32 v[130:131], v[132:133], v[132:133], v[130:131]
	v_mov_b32_e32 v132, v115
	v_mov_b32_e32 v133, v119
	v_pk_fma_f32 v[130:131], v[132:133], v[132:133], v[130:131]
	s_mov_b32 s21, 0x800000
	v_add_f32_e32 v128, v131, v128
	v_add_f32_e32 v128, v130, v128
	v_mov_b32_e32 v228, v128
	v_mov_b32_e32 v129, v128
	s_nop 1
	v_permlane16_swap_b32_e32 v228, v129
	s_nop 1
	v_mov_b32_dpp v129, v228 quad_perm:[0,1,2,3] row_mask:0xa bank_mask:0xf
	s_mov_b64 s[36:37], s[52:53]
	s_mov_b64 s[42:43], s[16:17]
	global_store_dwordx4 v[138:139], v[140:143], off
	global_store_dwordx4 v[138:139], v[134:137], off offset:32
	s_waitcnt lgkmcnt(0)
	v_add_f32_e32 v128, v128, v129
	v_mov_b32_e32 v228, v128
	v_mov_b32_e32 v129, v128
	s_nop 1
	v_permlane32_swap_b32_e32 v228, v129
	s_nop 1
	v_mov_b32_dpp v129, v228 quad_perm:[0,1,2,3] row_mask:0xc bank_mask:0xf
	s_waitcnt lgkmcnt(0)
	v_add_f32_e32 v128, v128, v129
	v_fmamk_f32 v128, v128, 0x3c800000, v250
	v_cmp_gt_f32_e32 vcc, s21, v128
	v_mul_f32_e32 v129, 0x4b800000, v128
	s_nop 0
	v_cndmask_b32_e32 v128, v128, v129, vcc
	v_rsq_f32_e32 v128, v128
	s_nop 0
	v_mul_f32_e32 v129, 0x45800000, v128
	v_cndmask_b32_e32 v128, v128, v129, vcc
	v_pk_mul_f32 v[130:131], v[116:117], v[128:129] op_sel_hi:[1,0]
	v_pk_mul_f32 v[124:125], v[124:125], v[128:129] op_sel_hi:[1,0]
	v_pk_mul_f32 v[126:127], v[126:127], v[128:129] op_sel_hi:[1,0]
	v_pk_mul_f32 v[120:121], v[120:121], v[128:129] op_sel_hi:[1,0]
	v_pk_mul_f32 v[122:123], v[122:123], v[128:129] op_sel_hi:[1,0]
	v_pk_mul_f32 v[116:117], v[118:119], v[128:129] op_sel_hi:[1,0]
	v_pk_mul_f32 v[118:119], v[72:73], v[130:131]
	v_pk_mul_f32 v[130:131], v[112:113], v[128:129] op_sel_hi:[1,0]
	v_pk_mul_f32 v[112:113], v[114:115], v[128:129] op_sel_hi:[1,0]
	v_pk_mul_f32 v[126:127], v[78:79], v[126:127]
	v_pk_mul_f32 v[124:125], v[76:77], v[124:125]
	v_pk_mul_f32 v[122:123], v[70:71], v[122:123]
	v_pk_mul_f32 v[120:121], v[68:69], v[120:121]
	v_pk_mul_f32 v[116:117], v[74:75], v[116:117]
	v_pk_mul_f32 v[112:113], v[66:67], v[112:113]
	v_pk_mul_f32 v[114:115], v[64:65], v[130:131]
	s_and_b64 vcc, exec, s[4:5]
	s_cbranch_vccnz .LBB0_756
	s_add_i32 s21, s20, s39
	s_lshr_b32 s21, s21, 6
	v_mov_b32_e32 v128, s21
	v_cndmask_b32_e64 v128, v182, v128, s[44:45]
	v_lshlrev_b32_e32 v170, 7, v128
	v_add_u32_e32 v132, v185, v170
	ds_read_b128 v[128:131], v132
	ds_read_b128 v[132:135], v132 offset:16
	s_waitcnt lgkmcnt(1)
	v_mov_b32_e32 v138, v129
	v_mov_b32_e32 v139, v131
	v_pk_mul_f32 v[140:141], v[118:119], v[138:139]
	s_waitcnt lgkmcnt(0)
	v_mov_b32_e32 v142, v133
	v_mov_b32_e32 v143, v135
	v_mov_b32_e32 v133, v134
	v_mov_b32_e32 v129, v130
	v_pk_mul_f32 v[136:137], v[116:117], v[142:143]
	v_pk_fma_f32 v[134:135], v[124:125], v[128:129], v[140:141] neg_lo:[0,0,1] neg_hi:[0,0,1]
	v_pk_mul_f32 v[118:119], v[118:119], v[128:129]
	v_pk_mul_f32 v[116:117], v[116:117], v[132:133]
	v_add_u32_e32 v128, v186, v170
	v_pk_fma_f32 v[136:137], v[126:127], v[132:133], v[136:137] neg_lo:[0,0,1] neg_hi:[0,0,1]
	v_pk_fma_f32 v[116:117], v[126:127], v[142:143], v[116:117]
	v_pk_fma_f32 v[118:119], v[124:125], v[138:139], v[118:119]
	ds_read_b128 v[124:127], v128
	ds_read_b128 v[128:131], v128 offset:16
	s_waitcnt lgkmcnt(1)
	v_mov_b32_e32 v138, v125
	v_mov_b32_e32 v139, v127
	v_pk_mul_f32 v[140:141], v[114:115], v[138:139]
	s_waitcnt lgkmcnt(0)
	v_mov_b32_e32 v142, v129
	v_mov_b32_e32 v143, v131
	v_mov_b32_e32 v129, v130
	v_mov_b32_e32 v125, v126
	v_pk_mul_f32 v[132:133], v[112:113], v[142:143]
	v_pk_fma_f32 v[130:131], v[120:121], v[124:125], v[140:141] neg_lo:[0,0,1] neg_hi:[0,0,1]
	v_pk_mul_f32 v[114:115], v[114:115], v[124:125]
	v_pk_mul_f32 v[112:113], v[112:113], v[128:129]
	v_pk_fma_f32 v[132:133], v[122:123], v[128:129], v[132:133] neg_lo:[0,0,1] neg_hi:[0,0,1]
	v_pk_fma_f32 v[112:113], v[122:123], v[142:143], v[112:113]
	v_pk_fma_f32 v[114:115], v[120:121], v[138:139], v[114:115]
	v_mov_b64_e32 v[120:121], v[130:131]
	v_mov_b64_e32 v[124:125], v[134:135]
	v_mov_b64_e32 v[122:123], v[132:133]
	v_mov_b64_e32 v[126:127], v[136:137]
; #define LAS __attribute__((address_space(3)))
;     DI void operator()(const Acc& acc, const Unit& u, int wr, int wc, int fr, int fq) const {
;     ...
; #pragma unroll
;             for (int ai = 0; ai < 2; ++ai)
; #pragma unroll
;                 for (int m = 0; m < 4; ++m) {
;                     const int rl = ai * HALF + wr * 64 + m * 16 + fr, r = rowb + rl;
;                     float ss = 0.f;
; #pragma unroll
;                     for (int bj = 0; bj < 2; ++bj)
; #pragma unroll
;                         for (int n = 0; n < 2; ++n) { const f32x4 a = acc[ai][bj][m][n]; ss += a[0] * a[0] + a[1] * a[1] + a[2] * a[2] + a[3] * a[3]; }
;                     ss += shx(ss, 16, 16 * fq + fr); ss += shx(ss, 32, 16 * fq + fr);
;                     const float rstd = rsqrtf(ss * (1.f / 64.f) + LN_EPS);
;                     f32x4 v[2][2];
; #pragma unroll
;                     for (int bj = 0; bj < 2; ++bj)
; #pragma unroll
;                         for (int n = 0; n < 2; ++n) v[bj][n] = acc[ai][bj][m][n] * rstd * g[bj][n];
;                     if (latent) {
;                         const int s = s0 + rl, pos = (fq >> 1) ? (s & 63) : (s >> 6);
; #pragma unroll
;                         for (int n = 0; n < 2; ++n) {
;                             const LAS float* tp = tab + (pos * 16 + 8 * (fq & 1) + 4 * n) * 2;
;                             const f32x4 t0 = *(const LAS f32x4*)tp, t1 = *(const LAS f32x4*)(tp + 4);
;                             const f32x4 cs = {t0[0], t0[2], t1[0], t1[2]}, sn = {t0[1], t0[3], t1[1], t1[3]};
;                             const f32x4 x1 = v[0][n], x2 = v[1][n];
;                             v[0][n] = x1 * cs - x2 * sn; v[1][n] = x2 * cs + x1 * sn;
;                         }
;                     }
; #pragma unroll
;                     for (int bj = 0; bj < 2; ++bj) {
;                         u32x4 o; o[0] = pk_bf16(v[bj][0][0], v[bj][0][1]); o[1] = pk_bf16(v[bj][0][2], v[bj][0][3]); o[2] = pk_bf16(v[bj][1][0], v[bj][1][1]); o[3] = pk_bf16(v[bj][1][2], v[bj][1][3]);
;                         bf16_t* dst = tile < 4 ? Q + (size_t)r * 1024 + (tile * 4 + wc) * 64 + dbase + 16 * bj
;                                                : Kd + ((size_t)(b * 4 + wc) * NKEY + kp0 + rl) * 64 + dbase + 16 * bj;
;                         *(u32x4*)dst = o;
.LBB0_756:
	v_add_u32_e32 v128, s19, v152
	v_ashrrev_i32_e32 v129, 31, v128
	v_readlane_b32 s22, v254, 27
	v_lshlrev_b64 v[128:129], 11, v[128:129]
	v_lshl_add_u64 v[130:131], s[60:61], 0, v[152:153]
	v_readlane_b32 s23, v254, 28
	v_lshlrev_b64 v[130:131], 7, v[130:131]
	v_cvt_pk_bf16_f32 v124, v124, v125
	v_cvt_pk_bf16_f32 v125, v126, v127
	v_cvt_pk_bf16_f32 v126, v120, v121
	v_lshl_add_u64 v[120:121], s[22:23], 0, v[128:129]
	v_cvt_pk_bf16_f32 v127, v122, v123
	v_lshl_add_u64 v[120:121], s[58:59], 1, v[120:121]
	v_lshl_add_u64 v[122:123], s[26:27], 0, v[130:131]
	v_cndmask_b32_e64 v121, v121, v123, s[2:3]
	v_cndmask_b32_e64 v120, v120, v122, s[2:3]
	v_lshl_add_u64 v[122:123], v[120:121], 0, v[168:169]
	v_cvt_pk_bf16_f32 v120, v114, v115
	v_mov_b32_e32 v114, v105
	v_mov_b32_e32 v115, v109
	v_cvt_pk_bf16_f32 v121, v112, v113
	v_mov_b32_e32 v112, v104
	v_mov_b32_e32 v113, v108
	v_pk_mul_f32 v[114:115], v[114:115], v[114:115]
	v_cvt_pk_bf16_f32 v118, v118, v119
	v_pk_fma_f32 v[112:113], v[112:113], v[112:113], v[114:115]
	v_mov_b32_e32 v114, v106
	v_mov_b32_e32 v115, v110
	v_cvt_pk_bf16_f32 v119, v116, v117
	v_pk_fma_f32 v[112:113], v[114:115], v[114:115], v[112:113]
	v_mov_b32_e32 v114, v107
	v_mov_b32_e32 v115, v111
	v_mov_b32_e32 v116, v97
	v_mov_b32_e32 v117, v101
	v_pk_fma_f32 v[112:113], v[114:115], v[114:115], v[112:113]
	v_mov_b32_e32 v114, v96
	v_mov_b32_e32 v115, v100
	v_pk_mul_f32 v[116:117], v[116:117], v[116:117]
	v_add_f32_e32 v112, v112, v113
	v_pk_fma_f32 v[114:115], v[114:115], v[114:115], v[116:117]
	v_mov_b32_e32 v116, v98
	v_mov_b32_e32 v117, v102
	v_pk_fma_f32 v[114:115], v[116:117], v[116:117], v[114:115]
	v_mov_b32_e32 v116, v99
	v_mov_b32_e32 v117, v103
	v_pk_fma_f32 v[114:115], v[116:117], v[116:117], v[114:115]
	s_mov_b32 s21, 0x800000
	v_add_f32_e32 v112, v115, v112
	v_add_f32_e32 v112, v114, v112
	v_mov_b32_e32 v228, v112
	v_mov_b32_e32 v113, v112
	s_nop 1
	v_permlane16_swap_b32_e32 v228, v113
	s_nop 1
	v_mov_b32_dpp v113, v228 quad_perm:[0,1,2,3] row_mask:0xa bank_mask:0xf
	v_readlane_b32 s16, v255, 27
	v_readlane_b32 s17, v255, 28
	global_store_dwordx4 v[122:123], v[124:127], off
	global_store_dwordx4 v[122:123], v[118:121], off offset:32
	s_waitcnt lgkmcnt(0)
	v_add_f32_e32 v112, v112, v113
	v_mov_b32_e32 v228, v112
	v_mov_b32_e32 v113, v112
	s_nop 1
	v_permlane32_swap_b32_e32 v228, v113
	s_nop 1
	v_mov_b32_dpp v113, v228 quad_perm:[0,1,2,3] row_mask:0xc bank_mask:0xf
	s_waitcnt lgkmcnt(0)
	v_add_f32_e32 v112, v112, v113
	v_fmamk_f32 v112, v112, 0x3c800000, v250
	v_cmp_gt_f32_e32 vcc, s21, v112
	v_mul_f32_e32 v113, 0x4b800000, v112
	s_nop 0
	v_cndmask_b32_e32 v112, v112, v113, vcc
	v_rsq_f32_e32 v112, v112
	s_nop 0
	v_mul_f32_e32 v113, 0x45800000, v112
	v_cndmask_b32_e32 v112, v112, v113, vcc
	v_pk_mul_f32 v[114:115], v[100:101], v[112:113] op_sel_hi:[1,0]
	v_pk_mul_f32 v[108:109], v[108:109], v[112:113] op_sel_hi:[1,0]
	v_pk_mul_f32 v[110:111], v[110:111], v[112:113] op_sel_hi:[1,0]
	v_pk_mul_f32 v[104:105], v[104:105], v[112:113] op_sel_hi:[1,0]
	v_pk_mul_f32 v[106:107], v[106:107], v[112:113] op_sel_hi:[1,0]
	v_pk_mul_f32 v[100:101], v[102:103], v[112:113] op_sel_hi:[1,0]
	v_pk_mul_f32 v[102:103], v[72:73], v[114:115]
	v_pk_mul_f32 v[114:115], v[96:97], v[112:113] op_sel_hi:[1,0]
	v_pk_mul_f32 v[96:97], v[98:99], v[112:113] op_sel_hi:[1,0]
	v_pk_mul_f32 v[110:111], v[78:79], v[110:111]
	v_pk_mul_f32 v[108:109], v[76:77], v[108:109]
	v_pk_mul_f32 v[106:107], v[70:71], v[106:107]
	v_pk_mul_f32 v[104:105], v[68:69], v[104:105]
	v_pk_mul_f32 v[100:101], v[74:75], v[100:101]
	v_pk_mul_f32 v[96:97], v[66:67], v[96:97]
	v_pk_mul_f32 v[98:99], v[64:65], v[114:115]
	s_and_b64 vcc, exec, s[4:5]
	s_cbranch_vccnz .LBB0_758
	s_add_i32 s21, s20, s39
	s_lshr_b32 s21, s21, 6
	v_mov_b32_e32 v112, s21
	v_cndmask_b32_e64 v112, v183, v112, s[44:45]
	v_lshlrev_b32_e32 v128, 7, v112
	v_add_u32_e32 v116, v185, v128
	ds_read_b128 v[112:115], v116
	ds_read_b128 v[116:119], v116 offset:16
	s_waitcnt lgkmcnt(1)
	v_mov_b32_e32 v122, v113
	v_mov_b32_e32 v123, v115
	v_pk_mul_f32 v[124:125], v[102:103], v[122:123]
	s_waitcnt lgkmcnt(0)
	v_mov_b32_e32 v126, v117
	v_mov_b32_e32 v127, v119
	v_mov_b32_e32 v117, v118
	v_mov_b32_e32 v113, v114
	v_pk_mul_f32 v[120:121], v[100:101], v[126:127]
	v_pk_fma_f32 v[118:119], v[108:109], v[112:113], v[124:125] neg_lo:[0,0,1] neg_hi:[0,0,1]
	v_pk_mul_f32 v[102:103], v[102:103], v[112:113]
	v_pk_mul_f32 v[100:101], v[100:101], v[116:117]
	v_add_u32_e32 v112, v186, v128
	v_pk_fma_f32 v[120:121], v[110:111], v[116:117], v[120:121] neg_lo:[0,0,1] neg_hi:[0,0,1]
	v_pk_fma_f32 v[100:101], v[110:111], v[126:127], v[100:101]
	v_pk_fma_f32 v[102:103], v[108:109], v[122:123], v[102:103]
	ds_read_b128 v[108:111], v112
	ds_read_b128 v[112:115], v112 offset:16
	s_waitcnt lgkmcnt(1)
	v_mov_b32_e32 v122, v109
	v_mov_b32_e32 v123, v111
	v_pk_mul_f32 v[124:125], v[98:99], v[122:123]
	s_waitcnt lgkmcnt(0)
	v_mov_b32_e32 v126, v113
	v_mov_b32_e32 v127, v115
	v_mov_b32_e32 v113, v114
	v_mov_b32_e32 v109, v110
	v_pk_mul_f32 v[116:117], v[96:97], v[126:127]
	v_pk_fma_f32 v[114:115], v[104:105], v[108:109], v[124:125] neg_lo:[0,0,1] neg_hi:[0,0,1]
	v_pk_mul_f32 v[98:99], v[98:99], v[108:109]
	v_pk_mul_f32 v[96:97], v[96:97], v[112:113]
	v_pk_fma_f32 v[116:117], v[106:107], v[112:113], v[116:117] neg_lo:[0,0,1] neg_hi:[0,0,1]
	v_pk_fma_f32 v[96:97], v[106:107], v[126:127], v[96:97]
	v_pk_fma_f32 v[98:99], v[104:105], v[122:123], v[98:99]
	v_mov_b64_e32 v[104:105], v[114:115]
	v_mov_b64_e32 v[108:109], v[118:119]
	v_mov_b64_e32 v[106:107], v[116:117]
	v_mov_b64_e32 v[110:111], v[120:121]
; #define LAS __attribute__((address_space(3)))
;     DI void operator()(const Acc& acc, const Unit& u, int wr, int wc, int fr, int fq) const {
;     ...
; #pragma unroll
;             for (int ai = 0; ai < 2; ++ai)
; #pragma unroll
;                 for (int m = 0; m < 4; ++m) {
;                     const int rl = ai * HALF + wr * 64 + m * 16 + fr, r = rowb + rl;
;                     float ss = 0.f;
; #pragma unroll
;                     for (int bj = 0; bj < 2; ++bj)
; #pragma unroll
;                         for (int n = 0; n < 2; ++n) { const f32x4 a = acc[ai][bj][m][n]; ss += a[0] * a[0] + a[1] * a[1] + a[2] * a[2] + a[3] * a[3]; }
;                     ss += shx(ss, 16, 16 * fq + fr); ss += shx(ss, 32, 16 * fq + fr);
;                     const float rstd = rsqrtf(ss * (1.f / 64.f) + LN_EPS);
;                     f32x4 v[2][2];
; #pragma unroll
;                     for (int bj = 0; bj < 2; ++bj)
; #pragma unroll
;                         for (int n = 0; n < 2; ++n) v[bj][n] = acc[ai][bj][m][n] * rstd * g[bj][n];
;                     if (latent) {
;                         const int s = s0 + rl, pos = (fq >> 1) ? (s & 63) : (s >> 6);
; #pragma unroll
;                         for (int n = 0; n < 2; ++n) {
;                             const LAS float* tp = tab + (pos * 16 + 8 * (fq & 1) + 4 * n) * 2;
;                             const f32x4 t0 = *(const LAS f32x4*)tp, t1 = *(const LAS f32x4*)(tp + 4);
;                             const f32x4 cs = {t0[0], t0[2], t1[0], t1[2]}, sn = {t0[1], t0[3], t1[1], t1[3]};
;                             const f32x4 x1 = v[0][n], x2 = v[1][n];
;                             v[0][n] = x1 * cs - x2 * sn; v[1][n] = x2 * cs + x1 * sn;
;                         }
;                     }
; #pragma unroll
;                     for (int bj = 0; bj < 2; ++bj) {
;                         u32x4 o; o[0] = pk_bf16(v[bj][0][0], v[bj][0][1]); o[1] = pk_bf16(v[bj][0][2], v[bj][0][3]); o[2] = pk_bf16(v[bj][1][0], v[bj][1][1]); o[3] = pk_bf16(v[bj][1][2], v[bj][1][3]);
;                         bf16_t* dst = tile < 4 ? Q + (size_t)r * 1024 + (tile * 4 + wc) * 64 + dbase + 16 * bj
;                                                : Kd + ((size_t)(b * 4 + wc) * NKEY + kp0 + rl) * 64 + dbase + 16 * bj;
;                         *(u32x4*)dst = o;
.LBB0_758:
	v_add_u32_e32 v112, s19, v154
	v_ashrrev_i32_e32 v113, 31, v112
	v_readlane_b32 s22, v254, 27
	v_lshlrev_b64 v[112:113], 11, v[112:113]
	v_lshl_add_u64 v[114:115], s[60:61], 0, v[154:155]
	v_readlane_b32 s23, v254, 28
	v_lshlrev_b64 v[114:115], 7, v[114:115]
	v_cvt_pk_bf16_f32 v108, v108, v109
	v_cvt_pk_bf16_f32 v109, v110, v111
	v_cvt_pk_bf16_f32 v110, v104, v105
	v_lshl_add_u64 v[104:105], s[22:23], 0, v[112:113]
	v_cvt_pk_bf16_f32 v111, v106, v107
	v_lshl_add_u64 v[104:105], s[58:59], 1, v[104:105]
	v_lshl_add_u64 v[106:107], s[26:27], 0, v[114:115]
	v_cndmask_b32_e64 v105, v105, v107, s[2:3]
	v_cndmask_b32_e64 v104, v104, v106, s[2:3]
	v_lshl_add_u64 v[106:107], v[104:105], 0, v[168:169]
	v_cvt_pk_bf16_f32 v104, v98, v99
	v_mov_b32_e32 v98, v89
	v_mov_b32_e32 v99, v93
	v_cvt_pk_bf16_f32 v105, v96, v97
	v_mov_b32_e32 v96, v88
	v_mov_b32_e32 v97, v92
	v_pk_mul_f32 v[98:99], v[98:99], v[98:99]
	v_cvt_pk_bf16_f32 v102, v102, v103
	v_pk_fma_f32 v[96:97], v[96:97], v[96:97], v[98:99]
	v_mov_b32_e32 v98, v90
	v_mov_b32_e32 v99, v94
	v_cvt_pk_bf16_f32 v103, v100, v101
	v_pk_fma_f32 v[96:97], v[98:99], v[98:99], v[96:97]
	v_mov_b32_e32 v98, v91
	v_mov_b32_e32 v99, v95
	v_mov_b32_e32 v100, v81
	v_mov_b32_e32 v101, v85
	v_pk_fma_f32 v[96:97], v[98:99], v[98:99], v[96:97]
	v_mov_b32_e32 v98, v80
	v_mov_b32_e32 v99, v84
	v_pk_mul_f32 v[100:101], v[100:101], v[100:101]
	v_add_f32_e32 v96, v96, v97
	v_pk_fma_f32 v[98:99], v[98:99], v[98:99], v[100:101]
	v_mov_b32_e32 v100, v82
	v_mov_b32_e32 v101, v86
	v_pk_fma_f32 v[98:99], v[100:101], v[100:101], v[98:99]
	v_mov_b32_e32 v100, v83
	v_mov_b32_e32 v101, v87
	v_pk_fma_f32 v[98:99], v[100:101], v[100:101], v[98:99]
	s_mov_b32 s21, 0x800000
	v_add_f32_e32 v96, v99, v96
	v_add_f32_e32 v96, v98, v96
	v_mov_b32_e32 v228, v96
	v_mov_b32_e32 v97, v96
	s_nop 1
	v_permlane16_swap_b32_e32 v228, v97
	s_nop 1
	v_mov_b32_dpp v97, v228 quad_perm:[0,1,2,3] row_mask:0xa bank_mask:0xf
	global_store_dwordx4 v[106:107], v[108:111], off
	global_store_dwordx4 v[106:107], v[102:105], off offset:32
	s_waitcnt lgkmcnt(0)
	v_add_f32_e32 v96, v96, v97
	v_mov_b32_e32 v228, v96
	v_mov_b32_e32 v97, v96
	s_nop 1
	v_permlane32_swap_b32_e32 v228, v97
	s_nop 1
	v_mov_b32_dpp v97, v228 quad_perm:[0,1,2,3] row_mask:0xc bank_mask:0xf
	s_waitcnt lgkmcnt(0)
	v_add_f32_e32 v96, v96, v97
	v_fmamk_f32 v96, v96, 0x3c800000, v250
	v_cmp_gt_f32_e32 vcc, s21, v96
	v_mul_f32_e32 v97, 0x4b800000, v96
	s_nop 0
	v_cndmask_b32_e32 v96, v96, v97, vcc
	v_rsq_f32_e32 v96, v96
	s_nop 0
	v_mul_f32_e32 v97, 0x45800000, v96
	v_cndmask_b32_e32 v96, v96, v97, vcc
	v_pk_mul_f32 v[98:99], v[84:85], v[96:97] op_sel_hi:[1,0]
	v_pk_mul_f32 v[92:93], v[92:93], v[96:97] op_sel_hi:[1,0]
	v_pk_mul_f32 v[94:95], v[94:95], v[96:97] op_sel_hi:[1,0]
	v_pk_mul_f32 v[88:89], v[88:89], v[96:97] op_sel_hi:[1,0]
	v_pk_mul_f32 v[90:91], v[90:91], v[96:97] op_sel_hi:[1,0]
	v_pk_mul_f32 v[84:85], v[86:87], v[96:97] op_sel_hi:[1,0]
	v_pk_mul_f32 v[86:87], v[72:73], v[98:99]
	v_pk_mul_f32 v[98:99], v[80:81], v[96:97] op_sel_hi:[1,0]
	v_pk_mul_f32 v[80:81], v[82:83], v[96:97] op_sel_hi:[1,0]
	v_pk_mul_f32 v[94:95], v[78:79], v[94:95]
	v_pk_mul_f32 v[92:93], v[76:77], v[92:93]
	v_pk_mul_f32 v[90:91], v[70:71], v[90:91]
	v_pk_mul_f32 v[88:89], v[68:69], v[88:89]
	v_pk_mul_f32 v[84:85], v[74:75], v[84:85]
	v_pk_mul_f32 v[80:81], v[66:67], v[80:81]
	v_pk_mul_f32 v[82:83], v[64:65], v[98:99]
	s_and_b64 vcc, exec, s[4:5]
	s_cbranch_vccnz .LBB0_760
	s_add_i32 s21, s20, s39
	s_lshr_b32 s21, s21, 6
	v_mov_b32_e32 v96, s21
	v_cndmask_b32_e64 v96, v184, v96, s[44:45]
	v_lshlrev_b32_e32 v112, 7, v96
	v_add_u32_e32 v100, v185, v112
	ds_read_b128 v[96:99], v100
	ds_read_b128 v[100:103], v100 offset:16
	s_waitcnt lgkmcnt(1)
	v_mov_b32_e32 v106, v97
	v_mov_b32_e32 v107, v99
	v_pk_mul_f32 v[108:109], v[86:87], v[106:107]
	s_waitcnt lgkmcnt(0)
	v_mov_b32_e32 v110, v101
	v_mov_b32_e32 v111, v103
	v_mov_b32_e32 v101, v102
	v_mov_b32_e32 v97, v98
	v_pk_mul_f32 v[104:105], v[84:85], v[110:111]
	v_pk_fma_f32 v[102:103], v[92:93], v[96:97], v[108:109] neg_lo:[0,0,1] neg_hi:[0,0,1]
	v_pk_mul_f32 v[86:87], v[86:87], v[96:97]
	v_pk_mul_f32 v[84:85], v[84:85], v[100:101]
	v_add_u32_e32 v96, v186, v112
	v_pk_fma_f32 v[104:105], v[94:95], v[100:101], v[104:105] neg_lo:[0,0,1] neg_hi:[0,0,1]
	v_pk_fma_f32 v[84:85], v[94:95], v[110:111], v[84:85]
	v_pk_fma_f32 v[86:87], v[92:93], v[106:107], v[86:87]
	ds_read_b128 v[92:95], v96
	ds_read_b128 v[96:99], v96 offset:16
	s_waitcnt lgkmcnt(1)
	v_mov_b32_e32 v106, v93
	v_mov_b32_e32 v107, v95
	v_pk_mul_f32 v[108:109], v[82:83], v[106:107]
	s_waitcnt lgkmcnt(0)
	v_mov_b32_e32 v110, v97
	v_mov_b32_e32 v111, v99
	v_mov_b32_e32 v97, v98
	v_mov_b32_e32 v93, v94
	v_pk_mul_f32 v[100:101], v[80:81], v[110:111]
	v_pk_fma_f32 v[98:99], v[88:89], v[92:93], v[108:109] neg_lo:[0,0,1] neg_hi:[0,0,1]
	v_pk_mul_f32 v[82:83], v[82:83], v[92:93]
	v_pk_mul_f32 v[80:81], v[80:81], v[96:97]
	v_pk_fma_f32 v[100:101], v[90:91], v[96:97], v[100:101] neg_lo:[0,0,1] neg_hi:[0,0,1]
	v_pk_fma_f32 v[80:81], v[90:91], v[110:111], v[80:81]
	v_pk_fma_f32 v[82:83], v[88:89], v[106:107], v[82:83]
	v_mov_b64_e32 v[88:89], v[98:99]
	v_mov_b64_e32 v[92:93], v[102:103]
	v_mov_b64_e32 v[90:91], v[100:101]
	v_mov_b64_e32 v[94:95], v[104:105]
; #define LAS __attribute__((address_space(3)))
;     DI void operator()(const Acc& acc, const Unit& u, int wr, int wc, int fr, int fq) const {
;     ...
; #pragma unroll
;             for (int ai = 0; ai < 2; ++ai)
; #pragma unroll
;                 for (int m = 0; m < 4; ++m) {
;                     const int rl = ai * HALF + wr * 64 + m * 16 + fr, r = rowb + rl;
;                     float ss = 0.f;
; #pragma unroll
;                     for (int bj = 0; bj < 2; ++bj)
; #pragma unroll
;                         for (int n = 0; n < 2; ++n) { const f32x4 a = acc[ai][bj][m][n]; ss += a[0] * a[0] + a[1] * a[1] + a[2] * a[2] + a[3] * a[3]; }
;                     ss += shx(ss, 16, 16 * fq + fr); ss += shx(ss, 32, 16 * fq + fr);
;                     const float rstd = rsqrtf(ss * (1.f / 64.f) + LN_EPS);
;                     f32x4 v[2][2];
; #pragma unroll
;                     for (int bj = 0; bj < 2; ++bj)
; #pragma unroll
;                         for (int n = 0; n < 2; ++n) v[bj][n] = acc[ai][bj][m][n] * rstd * g[bj][n];
;                     if (latent) {
;                         const int s = s0 + rl, pos = (fq >> 1) ? (s & 63) : (s >> 6);
; #pragma unroll
;                         for (int n = 0; n < 2; ++n) {
;                             const LAS float* tp = tab + (pos * 16 + 8 * (fq & 1) + 4 * n) * 2;
;                             const f32x4 t0 = *(const LAS f32x4*)tp, t1 = *(const LAS f32x4*)(tp + 4);
;                             const f32x4 cs = {t0[0], t0[2], t1[0], t1[2]}, sn = {t0[1], t0[3], t1[1], t1[3]};
;                             const f32x4 x1 = v[0][n], x2 = v[1][n];
;                             v[0][n] = x1 * cs - x2 * sn; v[1][n] = x2 * cs + x1 * sn;
;                         }
;                     }
; #pragma unroll
;                     for (int bj = 0; bj < 2; ++bj) {
;                         u32x4 o; o[0] = pk_bf16(v[bj][0][0], v[bj][0][1]); o[1] = pk_bf16(v[bj][0][2], v[bj][0][3]); o[2] = pk_bf16(v[bj][1][0], v[bj][1][1]); o[3] = pk_bf16(v[bj][1][2], v[bj][1][3]);
;                         bf16_t* dst = tile < 4 ? Q + (size_t)r * 1024 + (tile * 4 + wc) * 64 + dbase + 16 * bj
;                                                : Kd + ((size_t)(b * 4 + wc) * NKEY + kp0 + rl) * 64 + dbase + 16 * bj;
;                         *(u32x4*)dst = o;
.LBB0_760:
	v_add_u32_e32 v96, s19, v156
	v_ashrrev_i32_e32 v97, 31, v96
	v_readlane_b32 s22, v254, 27
	v_lshlrev_b64 v[96:97], 11, v[96:97]
	v_lshl_add_u64 v[98:99], s[60:61], 0, v[156:157]
	v_readlane_b32 s23, v254, 28
	v_lshlrev_b64 v[98:99], 7, v[98:99]
	v_cvt_pk_bf16_f32 v92, v92, v93
	v_cvt_pk_bf16_f32 v93, v94, v95
	v_cvt_pk_bf16_f32 v94, v88, v89
	v_lshl_add_u64 v[88:89], s[22:23], 0, v[96:97]
	v_cvt_pk_bf16_f32 v95, v90, v91
	v_lshl_add_u64 v[88:89], s[58:59], 1, v[88:89]
	v_lshl_add_u64 v[90:91], s[26:27], 0, v[98:99]
	v_cndmask_b32_e64 v89, v89, v91, s[2:3]
	v_cndmask_b32_e64 v88, v88, v90, s[2:3]
	v_lshl_add_u64 v[90:91], v[88:89], 0, v[168:169]
	v_cvt_pk_bf16_f32 v88, v82, v83
	v_mov_b32_e32 v82, v57
	v_mov_b32_e32 v83, v61
	v_cvt_pk_bf16_f32 v89, v80, v81
	v_mov_b32_e32 v80, v56
	v_mov_b32_e32 v81, v60
	v_pk_mul_f32 v[82:83], v[82:83], v[82:83]
	v_cvt_pk_bf16_f32 v86, v86, v87
	v_pk_fma_f32 v[80:81], v[80:81], v[80:81], v[82:83]
	v_mov_b32_e32 v82, v58
	v_mov_b32_e32 v83, v62
	v_cvt_pk_bf16_f32 v87, v84, v85
	v_pk_fma_f32 v[80:81], v[82:83], v[82:83], v[80:81]
	v_mov_b32_e32 v82, v59
	v_mov_b32_e32 v83, v63
	v_mov_b32_e32 v84, v49
	v_mov_b32_e32 v85, v53
	v_pk_fma_f32 v[80:81], v[82:83], v[82:83], v[80:81]
	v_mov_b32_e32 v82, v48
	v_mov_b32_e32 v83, v52
	v_pk_mul_f32 v[84:85], v[84:85], v[84:85]
	v_add_f32_e32 v80, v80, v81
	v_pk_fma_f32 v[82:83], v[82:83], v[82:83], v[84:85]
	v_mov_b32_e32 v84, v50
	v_mov_b32_e32 v85, v54
	v_pk_fma_f32 v[82:83], v[84:85], v[84:85], v[82:83]
	v_mov_b32_e32 v84, v51
	v_mov_b32_e32 v85, v55
	v_pk_fma_f32 v[82:83], v[84:85], v[84:85], v[82:83]
	s_mov_b32 s21, 0x800000
	v_add_f32_e32 v80, v83, v80
	v_add_f32_e32 v80, v82, v80
	v_mov_b32_e32 v228, v80
	v_mov_b32_e32 v81, v80
	s_nop 1
	v_permlane16_swap_b32_e32 v228, v81
	s_nop 1
	v_mov_b32_dpp v81, v228 quad_perm:[0,1,2,3] row_mask:0xa bank_mask:0xf
	global_store_dwordx4 v[90:91], v[92:95], off
	global_store_dwordx4 v[90:91], v[86:89], off offset:32
	s_waitcnt lgkmcnt(0)
	v_add_f32_e32 v80, v80, v81
	v_mov_b32_e32 v228, v80
	v_mov_b32_e32 v81, v80
	s_nop 1
	v_permlane32_swap_b32_e32 v228, v81
	s_nop 1
	v_mov_b32_dpp v81, v228 quad_perm:[0,1,2,3] row_mask:0xc bank_mask:0xf
	s_waitcnt lgkmcnt(0)
	v_add_f32_e32 v80, v80, v81
	v_fmamk_f32 v80, v80, 0x3c800000, v250
	v_cmp_gt_f32_e32 vcc, s21, v80
	v_mul_f32_e32 v81, 0x4b800000, v80
	s_nop 0
	v_cndmask_b32_e32 v80, v80, v81, vcc
	v_rsq_f32_e32 v80, v80
	s_nop 0
	v_mul_f32_e32 v81, 0x45800000, v80
	v_cndmask_b32_e32 v80, v80, v81, vcc
	v_pk_mul_f32 v[82:83], v[52:53], v[80:81] op_sel_hi:[1,0]
	v_pk_mul_f32 v[60:61], v[60:61], v[80:81] op_sel_hi:[1,0]
	v_pk_mul_f32 v[62:63], v[62:63], v[80:81] op_sel_hi:[1,0]
	v_pk_mul_f32 v[56:57], v[56:57], v[80:81] op_sel_hi:[1,0]
	v_pk_mul_f32 v[58:59], v[58:59], v[80:81] op_sel_hi:[1,0]
	v_pk_mul_f32 v[52:53], v[54:55], v[80:81] op_sel_hi:[1,0]
	v_pk_mul_f32 v[54:55], v[72:73], v[82:83]
	v_pk_mul_f32 v[82:83], v[48:49], v[80:81] op_sel_hi:[1,0]
	v_pk_mul_f32 v[48:49], v[50:51], v[80:81] op_sel_hi:[1,0]
	v_pk_mul_f32 v[62:63], v[78:79], v[62:63]
	v_pk_mul_f32 v[60:61], v[76:77], v[60:61]
	v_pk_mul_f32 v[58:59], v[70:71], v[58:59]
	v_pk_mul_f32 v[56:57], v[68:69], v[56:57]
	v_pk_mul_f32 v[52:53], v[74:75], v[52:53]
	v_pk_mul_f32 v[48:49], v[66:67], v[48:49]
	v_pk_mul_f32 v[50:51], v[64:65], v[82:83]
	s_and_b64 vcc, exec, s[4:5]
	s_cbranch_vccnz .LBB0_762
	v_add_u32_e32 v80, s20, v158
	v_lshrrev_b32_e32 v80, 6, v80
	v_cndmask_b32_e64 v80, v151, v80, s[44:45]
	v_lshlrev_b32_e32 v96, 7, v80
	v_add_u32_e32 v84, v185, v96
	ds_read_b128 v[80:83], v84
	ds_read_b128 v[84:87], v84 offset:16
	s_waitcnt lgkmcnt(1)
	v_mov_b32_e32 v90, v81
	v_mov_b32_e32 v91, v83
	v_pk_mul_f32 v[92:93], v[54:55], v[90:91]
	s_waitcnt lgkmcnt(0)
	v_mov_b32_e32 v94, v85
	v_mov_b32_e32 v95, v87
	v_mov_b32_e32 v85, v86
	v_mov_b32_e32 v81, v82
	v_pk_mul_f32 v[88:89], v[52:53], v[94:95]
	v_pk_fma_f32 v[86:87], v[60:61], v[80:81], v[92:93] neg_lo:[0,0,1] neg_hi:[0,0,1]
	v_pk_mul_f32 v[54:55], v[54:55], v[80:81]
	v_pk_mul_f32 v[52:53], v[52:53], v[84:85]
	v_add_u32_e32 v80, v186, v96
	v_pk_fma_f32 v[88:89], v[62:63], v[84:85], v[88:89] neg_lo:[0,0,1] neg_hi:[0,0,1]
	v_pk_fma_f32 v[52:53], v[62:63], v[94:95], v[52:53]
	v_pk_fma_f32 v[54:55], v[60:61], v[90:91], v[54:55]
	ds_read_b128 v[60:63], v80
	ds_read_b128 v[80:83], v80 offset:16
	s_waitcnt lgkmcnt(1)
	v_mov_b32_e32 v90, v61
	v_mov_b32_e32 v91, v63
	v_pk_mul_f32 v[92:93], v[50:51], v[90:91]
	s_waitcnt lgkmcnt(0)
	v_mov_b32_e32 v94, v81
	v_mov_b32_e32 v95, v83
	v_mov_b32_e32 v81, v82
	v_mov_b32_e32 v61, v62
	v_pk_mul_f32 v[84:85], v[48:49], v[94:95]
	v_pk_fma_f32 v[82:83], v[56:57], v[60:61], v[92:93] neg_lo:[0,0,1] neg_hi:[0,0,1]
	v_pk_mul_f32 v[50:51], v[50:51], v[60:61]
	v_pk_mul_f32 v[48:49], v[48:49], v[80:81]
	v_pk_fma_f32 v[84:85], v[58:59], v[80:81], v[84:85] neg_lo:[0,0,1] neg_hi:[0,0,1]
	v_pk_fma_f32 v[48:49], v[58:59], v[94:95], v[48:49]
	v_pk_fma_f32 v[50:51], v[56:57], v[90:91], v[50:51]
	v_mov_b64_e32 v[56:57], v[82:83]
	v_mov_b64_e32 v[60:61], v[86:87]
	v_mov_b64_e32 v[58:59], v[84:85]
	v_mov_b64_e32 v[62:63], v[88:89]
; #define LAS __attribute__((address_space(3)))
;     DI void operator()(const Acc& acc, const Unit& u, int wr, int wc, int fr, int fq) const {
;     ...
; #pragma unroll
;             for (int ai = 0; ai < 2; ++ai)
; #pragma unroll
;                 for (int m = 0; m < 4; ++m) {
;                     const int rl = ai * HALF + wr * 64 + m * 16 + fr, r = rowb + rl;
;                     float ss = 0.f;
; #pragma unroll
;                     for (int bj = 0; bj < 2; ++bj)
; #pragma unroll
;                         for (int n = 0; n < 2; ++n) { const f32x4 a = acc[ai][bj][m][n]; ss += a[0] * a[0] + a[1] * a[1] + a[2] * a[2] + a[3] * a[3]; }
;                     ss += shx(ss, 16, 16 * fq + fr); ss += shx(ss, 32, 16 * fq + fr);
;                     const float rstd = rsqrtf(ss * (1.f / 64.f) + LN_EPS);
;                     f32x4 v[2][2];
; #pragma unroll
;                     for (int bj = 0; bj < 2; ++bj)
; #pragma unroll
;                         for (int n = 0; n < 2; ++n) v[bj][n] = acc[ai][bj][m][n] * rstd * g[bj][n];
;                     if (latent) {
;                         const int s = s0 + rl, pos = (fq >> 1) ? (s & 63) : (s >> 6);
; #pragma unroll
;                         for (int n = 0; n < 2; ++n) {
;                             const LAS float* tp = tab + (pos * 16 + 8 * (fq & 1) + 4 * n) * 2;
;                             const f32x4 t0 = *(const LAS f32x4*)tp, t1 = *(const LAS f32x4*)(tp + 4);
;                             const f32x4 cs = {t0[0], t0[2], t1[0], t1[2]}, sn = {t0[1], t0[3], t1[1], t1[3]};
;                             const f32x4 x1 = v[0][n], x2 = v[1][n];
;                             v[0][n] = x1 * cs - x2 * sn; v[1][n] = x2 * cs + x1 * sn;
;                         }
;                     }
; #pragma unroll
;                     for (int bj = 0; bj < 2; ++bj) {
;                         u32x4 o; o[0] = pk_bf16(v[bj][0][0], v[bj][0][1]); o[1] = pk_bf16(v[bj][0][2], v[bj][0][3]); o[2] = pk_bf16(v[bj][1][0], v[bj][1][1]); o[3] = pk_bf16(v[bj][1][2], v[bj][1][3]);
;                         bf16_t* dst = tile < 4 ? Q + (size_t)r * 1024 + (tile * 4 + wc) * 64 + dbase + 16 * bj
;                                                : Kd + ((size_t)(b * 4 + wc) * NKEY + kp0 + rl) * 64 + dbase + 16 * bj;
;                         *(u32x4*)dst = o;
.LBB0_762:
	v_add_u32_e32 v80, s19, v158
	v_ashrrev_i32_e32 v81, 31, v80
	v_readlane_b32 s22, v254, 27
	v_lshlrev_b64 v[80:81], 11, v[80:81]
	v_lshl_add_u64 v[82:83], s[60:61], 0, v[158:159]
	v_readlane_b32 s23, v254, 28
	v_lshlrev_b64 v[82:83], 7, v[82:83]
	v_cvt_pk_bf16_f32 v60, v60, v61
	v_cvt_pk_bf16_f32 v61, v62, v63
	v_cvt_pk_bf16_f32 v62, v56, v57
	v_lshl_add_u64 v[56:57], s[22:23], 0, v[80:81]
	v_cvt_pk_bf16_f32 v63, v58, v59
	v_lshl_add_u64 v[56:57], s[58:59], 1, v[56:57]
	v_lshl_add_u64 v[58:59], s[26:27], 0, v[82:83]
	v_cndmask_b32_e64 v57, v57, v59, s[2:3]
	v_cndmask_b32_e64 v56, v56, v58, s[2:3]
	v_lshl_add_u64 v[58:59], v[56:57], 0, v[168:169]
	v_cvt_pk_bf16_f32 v56, v50, v51
	v_mov_b32_e32 v50, v41
	v_mov_b32_e32 v51, v45
	v_cvt_pk_bf16_f32 v57, v48, v49
	v_mov_b32_e32 v48, v40
	v_mov_b32_e32 v49, v44
	v_pk_mul_f32 v[50:51], v[50:51], v[50:51]
	v_cvt_pk_bf16_f32 v54, v54, v55
	v_pk_fma_f32 v[48:49], v[48:49], v[48:49], v[50:51]
	v_mov_b32_e32 v50, v42
	v_mov_b32_e32 v51, v46
	v_cvt_pk_bf16_f32 v55, v52, v53
	v_pk_fma_f32 v[48:49], v[50:51], v[50:51], v[48:49]
	v_mov_b32_e32 v50, v43
	v_mov_b32_e32 v51, v47
	v_mov_b32_e32 v52, v33
	v_mov_b32_e32 v53, v37
	v_pk_fma_f32 v[48:49], v[50:51], v[50:51], v[48:49]
	v_mov_b32_e32 v50, v32
	v_mov_b32_e32 v51, v36
	v_pk_mul_f32 v[52:53], v[52:53], v[52:53]
	v_add_f32_e32 v48, v48, v49
	v_pk_fma_f32 v[50:51], v[50:51], v[50:51], v[52:53]
	v_mov_b32_e32 v52, v34
	v_mov_b32_e32 v53, v38
	v_pk_fma_f32 v[50:51], v[52:53], v[52:53], v[50:51]
	v_mov_b32_e32 v52, v35
	v_mov_b32_e32 v53, v39
	v_pk_fma_f32 v[50:51], v[52:53], v[52:53], v[50:51]
	global_store_dwordx4 v[58:59], v[60:63], off
	v_add_f32_e32 v48, v51, v48
	v_add_f32_e32 v48, v50, v48
	v_mov_b32_e32 v228, v48
	v_mov_b32_e32 v49, v48
	s_nop 1
	v_permlane16_swap_b32_e32 v228, v49
	s_nop 1
	v_mov_b32_dpp v49, v228 quad_perm:[0,1,2,3] row_mask:0xa bank_mask:0xf
	global_store_dwordx4 v[58:59], v[54:57], off offset:32
	s_waitcnt lgkmcnt(0)
	v_add_f32_e32 v48, v48, v49
	v_mov_b32_e32 v228, v48
	v_mov_b32_e32 v49, v48
	s_nop 1
	v_permlane32_swap_b32_e32 v228, v49
	s_nop 1
	v_mov_b32_dpp v49, v228 quad_perm:[0,1,2,3] row_mask:0xc bank_mask:0xf
	s_waitcnt lgkmcnt(0)
	v_add_f32_e32 v48, v48, v49
	v_fmamk_f32 v48, v48, 0x3c800000, v250
	v_cmp_gt_f32_e32 vcc, s21, v48
	v_mul_f32_e32 v49, 0x4b800000, v48
	s_nop 0
	v_cndmask_b32_e32 v48, v48, v49, vcc
	v_rsq_f32_e32 v48, v48
	s_nop 0
	v_mul_f32_e32 v49, 0x45800000, v48
	v_cndmask_b32_e32 v48, v48, v49, vcc
	v_pk_mul_f32 v[50:51], v[36:37], v[48:49] op_sel_hi:[1,0]
	v_pk_mul_f32 v[44:45], v[44:45], v[48:49] op_sel_hi:[1,0]
	v_pk_mul_f32 v[46:47], v[46:47], v[48:49] op_sel_hi:[1,0]
	v_pk_mul_f32 v[40:41], v[40:41], v[48:49] op_sel_hi:[1,0]
	v_pk_mul_f32 v[42:43], v[42:43], v[48:49] op_sel_hi:[1,0]
	v_pk_mul_f32 v[36:37], v[38:39], v[48:49] op_sel_hi:[1,0]
	v_pk_mul_f32 v[38:39], v[72:73], v[50:51]
	v_pk_mul_f32 v[50:51], v[32:33], v[48:49] op_sel_hi:[1,0]
	v_pk_mul_f32 v[32:33], v[34:35], v[48:49] op_sel_hi:[1,0]
	v_pk_mul_f32 v[46:47], v[78:79], v[46:47]
	v_pk_mul_f32 v[44:45], v[76:77], v[44:45]
	v_pk_mul_f32 v[42:43], v[70:71], v[42:43]
	v_pk_mul_f32 v[40:41], v[68:69], v[40:41]
	v_pk_mul_f32 v[36:37], v[74:75], v[36:37]
	v_pk_mul_f32 v[32:33], v[66:67], v[32:33]
	v_pk_mul_f32 v[34:35], v[64:65], v[50:51]
	s_and_b64 vcc, exec, s[4:5]
	s_cbranch_vccnz .LBB0_764
	v_add_u32_e32 v48, s20, v160
	v_lshrrev_b32_e32 v48, 6, v48
	v_cndmask_b32_e64 v48, v182, v48, s[44:45]
	v_lshlrev_b32_e32 v80, 7, v48
	v_add_u32_e32 v52, v185, v80
	ds_read_b128 v[48:51], v52
	ds_read_b128 v[52:55], v52 offset:16
	s_waitcnt lgkmcnt(1)
	v_mov_b32_e32 v58, v49
	v_mov_b32_e32 v59, v51
	v_pk_mul_f32 v[60:61], v[38:39], v[58:59]
	s_waitcnt lgkmcnt(0)
	v_mov_b32_e32 v62, v53
	v_mov_b32_e32 v63, v55
	v_mov_b32_e32 v53, v54
	v_mov_b32_e32 v49, v50
	v_pk_mul_f32 v[56:57], v[36:37], v[62:63]
	v_pk_fma_f32 v[54:55], v[44:45], v[48:49], v[60:61] neg_lo:[0,0,1] neg_hi:[0,0,1]
	v_pk_mul_f32 v[38:39], v[38:39], v[48:49]
	v_pk_mul_f32 v[36:37], v[36:37], v[52:53]
	v_add_u32_e32 v48, v186, v80
	v_pk_fma_f32 v[56:57], v[46:47], v[52:53], v[56:57] neg_lo:[0,0,1] neg_hi:[0,0,1]
	v_pk_fma_f32 v[36:37], v[46:47], v[62:63], v[36:37]
	v_pk_fma_f32 v[38:39], v[44:45], v[58:59], v[38:39]
	ds_read_b128 v[44:47], v48
	ds_read_b128 v[48:51], v48 offset:16
	s_waitcnt lgkmcnt(1)
	v_mov_b32_e32 v58, v45
	v_mov_b32_e32 v59, v47
	v_pk_mul_f32 v[60:61], v[34:35], v[58:59]
	s_waitcnt lgkmcnt(0)
	v_mov_b32_e32 v62, v49
	v_mov_b32_e32 v63, v51
	v_mov_b32_e32 v49, v50
	v_mov_b32_e32 v45, v46
	v_pk_mul_f32 v[52:53], v[32:33], v[62:63]
	v_pk_fma_f32 v[50:51], v[40:41], v[44:45], v[60:61] neg_lo:[0,0,1] neg_hi:[0,0,1]
	v_pk_mul_f32 v[34:35], v[34:35], v[44:45]
	v_pk_mul_f32 v[32:33], v[32:33], v[48:49]
	v_pk_fma_f32 v[52:53], v[42:43], v[48:49], v[52:53] neg_lo:[0,0,1] neg_hi:[0,0,1]
	v_pk_fma_f32 v[32:33], v[42:43], v[62:63], v[32:33]
	v_pk_fma_f32 v[34:35], v[40:41], v[58:59], v[34:35]
	v_mov_b64_e32 v[40:41], v[50:51]
	v_mov_b64_e32 v[44:45], v[54:55]
	v_mov_b64_e32 v[42:43], v[52:53]
	v_mov_b64_e32 v[46:47], v[56:57]
; #define LAS __attribute__((address_space(3)))
;     DI void operator()(const Acc& acc, const Unit& u, int wr, int wc, int fr, int fq) const {
;     ...
; #pragma unroll
;             for (int ai = 0; ai < 2; ++ai)
; #pragma unroll
;                 for (int m = 0; m < 4; ++m) {
;                     const int rl = ai * HALF + wr * 64 + m * 16 + fr, r = rowb + rl;
;                     float ss = 0.f;
; #pragma unroll
;                     for (int bj = 0; bj < 2; ++bj)
; #pragma unroll
;                         for (int n = 0; n < 2; ++n) { const f32x4 a = acc[ai][bj][m][n]; ss += a[0] * a[0] + a[1] * a[1] + a[2] * a[2] + a[3] * a[3]; }
;                     ss += shx(ss, 16, 16 * fq + fr); ss += shx(ss, 32, 16 * fq + fr);
;                     const float rstd = rsqrtf(ss * (1.f / 64.f) + LN_EPS);
;                     f32x4 v[2][2];
; #pragma unroll
;                     for (int bj = 0; bj < 2; ++bj)
; #pragma unroll
;                         for (int n = 0; n < 2; ++n) v[bj][n] = acc[ai][bj][m][n] * rstd * g[bj][n];
;                     if (latent) {
;                         const int s = s0 + rl, pos = (fq >> 1) ? (s & 63) : (s >> 6);
; #pragma unroll
;                         for (int n = 0; n < 2; ++n) {
;                             const LAS float* tp = tab + (pos * 16 + 8 * (fq & 1) + 4 * n) * 2;
;                             const f32x4 t0 = *(const LAS f32x4*)tp, t1 = *(const LAS f32x4*)(tp + 4);
;                             const f32x4 cs = {t0[0], t0[2], t1[0], t1[2]}, sn = {t0[1], t0[3], t1[1], t1[3]};
;                             const f32x4 x1 = v[0][n], x2 = v[1][n];
;                             v[0][n] = x1 * cs - x2 * sn; v[1][n] = x2 * cs + x1 * sn;
;                         }
;                     }
; #pragma unroll
;                     for (int bj = 0; bj < 2; ++bj) {
;                         u32x4 o; o[0] = pk_bf16(v[bj][0][0], v[bj][0][1]); o[1] = pk_bf16(v[bj][0][2], v[bj][0][3]); o[2] = pk_bf16(v[bj][1][0], v[bj][1][1]); o[3] = pk_bf16(v[bj][1][2], v[bj][1][3]);
;                         bf16_t* dst = tile < 4 ? Q + (size_t)r * 1024 + (tile * 4 + wc) * 64 + dbase + 16 * bj
;                                                : Kd + ((size_t)(b * 4 + wc) * NKEY + kp0 + rl) * 64 + dbase + 16 * bj;
;                         *(u32x4*)dst = o;
.LBB0_764:
	v_add_u32_e32 v48, s19, v160
	v_ashrrev_i32_e32 v49, 31, v48
	v_readlane_b32 s22, v254, 27
	v_lshlrev_b64 v[48:49], 11, v[48:49]
	v_lshl_add_u64 v[50:51], s[60:61], 0, v[160:161]
	v_readlane_b32 s23, v254, 28
	v_lshlrev_b64 v[50:51], 7, v[50:51]
	v_cvt_pk_bf16_f32 v44, v44, v45
	v_cvt_pk_bf16_f32 v45, v46, v47
	v_cvt_pk_bf16_f32 v46, v40, v41
	v_lshl_add_u64 v[40:41], s[22:23], 0, v[48:49]
	v_cvt_pk_bf16_f32 v47, v42, v43
	v_lshl_add_u64 v[40:41], s[58:59], 1, v[40:41]
	v_lshl_add_u64 v[42:43], s[26:27], 0, v[50:51]
	v_cndmask_b32_e64 v41, v41, v43, s[2:3]
	v_cndmask_b32_e64 v40, v40, v42, s[2:3]
	v_lshl_add_u64 v[42:43], v[40:41], 0, v[168:169]
	v_cvt_pk_bf16_f32 v40, v34, v35
	v_mov_b32_e32 v34, v25
	v_mov_b32_e32 v35, v29
	v_cvt_pk_bf16_f32 v41, v32, v33
	v_mov_b32_e32 v32, v24
	v_mov_b32_e32 v33, v28
	v_pk_mul_f32 v[34:35], v[34:35], v[34:35]
	v_cvt_pk_bf16_f32 v38, v38, v39
	v_pk_fma_f32 v[32:33], v[32:33], v[32:33], v[34:35]
	v_mov_b32_e32 v34, v26
	v_mov_b32_e32 v35, v30
	v_cvt_pk_bf16_f32 v39, v36, v37
	v_pk_fma_f32 v[32:33], v[34:35], v[34:35], v[32:33]
	v_mov_b32_e32 v34, v27
	v_mov_b32_e32 v35, v31
	v_mov_b32_e32 v36, v17
	v_mov_b32_e32 v37, v21
	v_pk_fma_f32 v[32:33], v[34:35], v[34:35], v[32:33]
	v_mov_b32_e32 v34, v16
	v_mov_b32_e32 v35, v20
	v_pk_mul_f32 v[36:37], v[36:37], v[36:37]
	v_add_f32_e32 v32, v32, v33
	v_pk_fma_f32 v[34:35], v[34:35], v[34:35], v[36:37]
	v_mov_b32_e32 v36, v18
	v_mov_b32_e32 v37, v22
	v_pk_fma_f32 v[34:35], v[36:37], v[36:37], v[34:35]
	v_mov_b32_e32 v36, v19
	v_mov_b32_e32 v37, v23
	v_pk_fma_f32 v[34:35], v[36:37], v[36:37], v[34:35]
	global_store_dwordx4 v[42:43], v[44:47], off
	v_add_f32_e32 v32, v35, v32
	v_add_f32_e32 v32, v34, v32
	v_mov_b32_e32 v228, v32
	v_mov_b32_e32 v33, v32
	s_nop 1
	v_permlane16_swap_b32_e32 v228, v33
	s_nop 1
	v_mov_b32_dpp v33, v228 quad_perm:[0,1,2,3] row_mask:0xa bank_mask:0xf
	global_store_dwordx4 v[42:43], v[38:41], off offset:32
	s_waitcnt lgkmcnt(0)
	v_add_f32_e32 v32, v32, v33
	v_mov_b32_e32 v228, v32
	v_mov_b32_e32 v33, v32
	s_nop 1
	v_permlane32_swap_b32_e32 v228, v33
	s_nop 1
	v_mov_b32_dpp v33, v228 quad_perm:[0,1,2,3] row_mask:0xc bank_mask:0xf
	s_waitcnt lgkmcnt(0)
	v_add_f32_e32 v32, v32, v33
	v_fmamk_f32 v32, v32, 0x3c800000, v250
	v_cmp_gt_f32_e32 vcc, s21, v32
	v_mul_f32_e32 v33, 0x4b800000, v32
	s_nop 0
	v_cndmask_b32_e32 v32, v32, v33, vcc
	v_rsq_f32_e32 v32, v32
	s_nop 0
	v_mul_f32_e32 v33, 0x45800000, v32
	v_cndmask_b32_e32 v32, v32, v33, vcc
	v_pk_mul_f32 v[34:35], v[20:21], v[32:33] op_sel_hi:[1,0]
	v_pk_mul_f32 v[28:29], v[28:29], v[32:33] op_sel_hi:[1,0]
	v_pk_mul_f32 v[30:31], v[30:31], v[32:33] op_sel_hi:[1,0]
	v_pk_mul_f32 v[24:25], v[24:25], v[32:33] op_sel_hi:[1,0]
	v_pk_mul_f32 v[26:27], v[26:27], v[32:33] op_sel_hi:[1,0]
	v_pk_mul_f32 v[20:21], v[22:23], v[32:33] op_sel_hi:[1,0]
	v_pk_mul_f32 v[22:23], v[72:73], v[34:35]
	v_pk_mul_f32 v[34:35], v[16:17], v[32:33] op_sel_hi:[1,0]
	v_pk_mul_f32 v[16:17], v[18:19], v[32:33] op_sel_hi:[1,0]
	v_pk_mul_f32 v[30:31], v[78:79], v[30:31]
	v_pk_mul_f32 v[28:29], v[76:77], v[28:29]
	v_pk_mul_f32 v[26:27], v[70:71], v[26:27]
	v_pk_mul_f32 v[24:25], v[68:69], v[24:25]
	v_pk_mul_f32 v[20:21], v[74:75], v[20:21]
	v_pk_mul_f32 v[16:17], v[66:67], v[16:17]
	v_pk_mul_f32 v[18:19], v[64:65], v[34:35]
	s_and_b64 vcc, exec, s[4:5]
	s_cbranch_vccnz .LBB0_766
	v_add_u32_e32 v32, s20, v162
	v_lshrrev_b32_e32 v32, 6, v32
	v_cndmask_b32_e64 v32, v183, v32, s[44:45]
	v_lshlrev_b32_e32 v48, 7, v32
	v_add_u32_e32 v36, v185, v48
	ds_read_b128 v[32:35], v36
	ds_read_b128 v[36:39], v36 offset:16
	s_waitcnt lgkmcnt(1)
	v_mov_b32_e32 v42, v33
	v_mov_b32_e32 v43, v35
	v_pk_mul_f32 v[44:45], v[22:23], v[42:43]
	s_waitcnt lgkmcnt(0)
	v_mov_b32_e32 v46, v37
	v_mov_b32_e32 v47, v39
	v_mov_b32_e32 v37, v38
	v_mov_b32_e32 v33, v34
	v_pk_mul_f32 v[40:41], v[20:21], v[46:47]
	v_pk_fma_f32 v[38:39], v[28:29], v[32:33], v[44:45] neg_lo:[0,0,1] neg_hi:[0,0,1]
	v_pk_mul_f32 v[22:23], v[22:23], v[32:33]
	v_pk_mul_f32 v[20:21], v[20:21], v[36:37]
	v_add_u32_e32 v32, v186, v48
	v_pk_fma_f32 v[40:41], v[30:31], v[36:37], v[40:41] neg_lo:[0,0,1] neg_hi:[0,0,1]
	v_pk_fma_f32 v[20:21], v[30:31], v[46:47], v[20:21]
	v_pk_fma_f32 v[22:23], v[28:29], v[42:43], v[22:23]
	ds_read_b128 v[28:31], v32
	ds_read_b128 v[32:35], v32 offset:16
	s_waitcnt lgkmcnt(1)
	v_mov_b32_e32 v42, v29
	v_mov_b32_e32 v43, v31
	v_pk_mul_f32 v[44:45], v[18:19], v[42:43]
	s_waitcnt lgkmcnt(0)
	v_mov_b32_e32 v46, v33
	v_mov_b32_e32 v47, v35
	v_mov_b32_e32 v33, v34
	v_mov_b32_e32 v29, v30
	v_pk_mul_f32 v[36:37], v[16:17], v[46:47]
	v_pk_fma_f32 v[34:35], v[24:25], v[28:29], v[44:45] neg_lo:[0,0,1] neg_hi:[0,0,1]
	v_pk_mul_f32 v[18:19], v[18:19], v[28:29]
	v_pk_mul_f32 v[16:17], v[16:17], v[32:33]
	v_pk_fma_f32 v[36:37], v[26:27], v[32:33], v[36:37] neg_lo:[0,0,1] neg_hi:[0,0,1]
	v_pk_fma_f32 v[16:17], v[26:27], v[46:47], v[16:17]
	v_pk_fma_f32 v[18:19], v[24:25], v[42:43], v[18:19]
	v_mov_b64_e32 v[24:25], v[34:35]
	v_mov_b64_e32 v[28:29], v[38:39]
	v_mov_b64_e32 v[26:27], v[36:37]
	v_mov_b64_e32 v[30:31], v[40:41]
; #define LAS __attribute__((address_space(3)))
;     DI void operator()(const Acc& acc, const Unit& u, int wr, int wc, int fr, int fq) const {
;     ...
; #pragma unroll
;             for (int ai = 0; ai < 2; ++ai)
; #pragma unroll
;                 for (int m = 0; m < 4; ++m) {
;                     const int rl = ai * HALF + wr * 64 + m * 16 + fr, r = rowb + rl;
;                     float ss = 0.f;
; #pragma unroll
;                     for (int bj = 0; bj < 2; ++bj)
; #pragma unroll
;                         for (int n = 0; n < 2; ++n) { const f32x4 a = acc[ai][bj][m][n]; ss += a[0] * a[0] + a[1] * a[1] + a[2] * a[2] + a[3] * a[3]; }
;                     ss += shx(ss, 16, 16 * fq + fr); ss += shx(ss, 32, 16 * fq + fr);
;                     const float rstd = rsqrtf(ss * (1.f / 64.f) + LN_EPS);
;                     f32x4 v[2][2];
; #pragma unroll
;                     for (int bj = 0; bj < 2; ++bj)
; #pragma unroll
;                         for (int n = 0; n < 2; ++n) v[bj][n] = acc[ai][bj][m][n] * rstd * g[bj][n];
;                     if (latent) {
;                         const int s = s0 + rl, pos = (fq >> 1) ? (s & 63) : (s >> 6);
; #pragma unroll
;                         for (int n = 0; n < 2; ++n) {
;                             const LAS float* tp = tab + (pos * 16 + 8 * (fq & 1) + 4 * n) * 2;
;                             const f32x4 t0 = *(const LAS f32x4*)tp, t1 = *(const LAS f32x4*)(tp + 4);
;                             const f32x4 cs = {t0[0], t0[2], t1[0], t1[2]}, sn = {t0[1], t0[3], t1[1], t1[3]};
;                             const f32x4 x1 = v[0][n], x2 = v[1][n];
;                             v[0][n] = x1 * cs - x2 * sn; v[1][n] = x2 * cs + x1 * sn;
;                         }
;                     }
; #pragma unroll
;                     for (int bj = 0; bj < 2; ++bj) {
;                         u32x4 o; o[0] = pk_bf16(v[bj][0][0], v[bj][0][1]); o[1] = pk_bf16(v[bj][0][2], v[bj][0][3]); o[2] = pk_bf16(v[bj][1][0], v[bj][1][1]); o[3] = pk_bf16(v[bj][1][2], v[bj][1][3]);
;                         bf16_t* dst = tile < 4 ? Q + (size_t)r * 1024 + (tile * 4 + wc) * 64 + dbase + 16 * bj
;                                                : Kd + ((size_t)(b * 4 + wc) * NKEY + kp0 + rl) * 64 + dbase + 16 * bj;
;                         *(u32x4*)dst = o;
.LBB0_766:
	v_add_u32_e32 v32, s19, v162
	v_ashrrev_i32_e32 v33, 31, v32
	v_readlane_b32 s22, v254, 27
	v_lshlrev_b64 v[32:33], 11, v[32:33]
	v_lshl_add_u64 v[34:35], s[60:61], 0, v[162:163]
	v_readlane_b32 s23, v254, 28
	v_lshlrev_b64 v[34:35], 7, v[34:35]
	v_cvt_pk_bf16_f32 v28, v28, v29
	v_cvt_pk_bf16_f32 v29, v30, v31
	v_cvt_pk_bf16_f32 v30, v24, v25
	v_lshl_add_u64 v[24:25], s[22:23], 0, v[32:33]
	v_cvt_pk_bf16_f32 v31, v26, v27
	v_lshl_add_u64 v[24:25], s[58:59], 1, v[24:25]
	v_lshl_add_u64 v[26:27], s[26:27], 0, v[34:35]
	v_cndmask_b32_e64 v25, v25, v27, s[2:3]
	v_cndmask_b32_e64 v24, v24, v26, s[2:3]
	v_lshl_add_u64 v[26:27], v[24:25], 0, v[168:169]
	v_cvt_pk_bf16_f32 v24, v18, v19
	v_mov_b32_e32 v18, v9
	v_mov_b32_e32 v19, v13
	v_cvt_pk_bf16_f32 v25, v16, v17
	v_mov_b32_e32 v16, v8
	v_mov_b32_e32 v17, v12
	v_pk_mul_f32 v[18:19], v[18:19], v[18:19]
	v_cvt_pk_bf16_f32 v22, v22, v23
	v_pk_fma_f32 v[16:17], v[16:17], v[16:17], v[18:19]
	v_mov_b32_e32 v18, v10
	v_mov_b32_e32 v19, v14
	v_cvt_pk_bf16_f32 v23, v20, v21
	v_pk_fma_f32 v[16:17], v[18:19], v[18:19], v[16:17]
	v_mov_b32_e32 v18, v11
	v_mov_b32_e32 v19, v15
	v_mov_b32_e32 v20, v5
	v_mov_b32_e32 v21, v1
	v_pk_fma_f32 v[16:17], v[18:19], v[18:19], v[16:17]
	v_mov_b32_e32 v18, v4
	v_mov_b32_e32 v19, v0
	v_pk_mul_f32 v[20:21], v[20:21], v[20:21]
	v_add_f32_e32 v16, v16, v17
	v_pk_fma_f32 v[18:19], v[18:19], v[18:19], v[20:21]
	v_mov_b32_e32 v20, v6
	v_mov_b32_e32 v21, v2
	v_pk_fma_f32 v[18:19], v[20:21], v[20:21], v[18:19]
	v_mov_b32_e32 v20, v7
	v_mov_b32_e32 v21, v3
	v_pk_fma_f32 v[18:19], v[20:21], v[20:21], v[18:19]
	global_store_dwordx4 v[26:27], v[28:31], off
	v_add_f32_e32 v16, v19, v16
	v_add_f32_e32 v16, v18, v16
	v_mov_b32_e32 v228, v16
	v_mov_b32_e32 v17, v16
	s_nop 1
	v_permlane16_swap_b32_e32 v228, v17
	s_nop 1
	v_mov_b32_dpp v17, v228 quad_perm:[0,1,2,3] row_mask:0xa bank_mask:0xf
	global_store_dwordx4 v[26:27], v[22:25], off offset:32
	s_waitcnt lgkmcnt(0)
	v_add_f32_e32 v16, v16, v17
	v_mov_b32_e32 v228, v16
	v_mov_b32_e32 v17, v16
	s_nop 1
	v_permlane32_swap_b32_e32 v228, v17
	s_nop 1
	v_mov_b32_dpp v17, v228 quad_perm:[0,1,2,3] row_mask:0xc bank_mask:0xf
	s_waitcnt lgkmcnt(0)
	v_add_f32_e32 v16, v16, v17
	v_fmamk_f32 v16, v16, 0x3c800000, v250
	v_cmp_gt_f32_e32 vcc, s21, v16
	v_mul_f32_e32 v17, 0x4b800000, v16
	s_nop 0
	v_cndmask_b32_e32 v16, v16, v17, vcc
	v_rsq_f32_e32 v16, v16
	s_nop 0
	v_mul_f32_e32 v17, 0x45800000, v16
	v_cndmask_b32_e32 v16, v16, v17, vcc
	v_pk_mul_f32 v[12:13], v[12:13], v[16:17] op_sel_hi:[1,0]
	v_pk_mul_f32 v[14:15], v[14:15], v[16:17] op_sel_hi:[1,0]
	v_pk_mul_f32 v[8:9], v[8:9], v[16:17] op_sel_hi:[1,0]
	v_pk_mul_f32 v[10:11], v[10:11], v[16:17] op_sel_hi:[1,0]
	v_pk_mul_f32 v[0:1], v[0:1], v[16:17] op_sel_hi:[1,0]
	v_pk_mul_f32 v[2:3], v[2:3], v[16:17] op_sel_hi:[1,0]
	v_pk_mul_f32 v[4:5], v[4:5], v[16:17] op_sel_hi:[1,0]
	v_pk_mul_f32 v[6:7], v[6:7], v[16:17] op_sel_hi:[1,0]
	v_pk_mul_f32 v[14:15], v[78:79], v[14:15]
	v_pk_mul_f32 v[12:13], v[76:77], v[12:13]
	v_pk_mul_f32 v[10:11], v[70:71], v[10:11]
	v_pk_mul_f32 v[8:9], v[68:69], v[8:9]
	v_pk_mul_f32 v[2:3], v[74:75], v[2:3]
	v_pk_mul_f32 v[0:1], v[72:73], v[0:1]
	v_pk_mul_f32 v[6:7], v[66:67], v[6:7]
	v_pk_mul_f32 v[4:5], v[64:65], v[4:5]
	s_and_b64 vcc, exec, s[4:5]
	s_cbranch_vccnz .LBB0_768
	v_add_u32_e32 v16, s20, v164
	v_lshrrev_b32_e32 v16, 6, v16
	v_cndmask_b32_e64 v16, v184, v16, s[44:45]
	v_lshlrev_b32_e32 v32, 7, v16
	v_add_u32_e32 v20, v185, v32
	ds_read_b128 v[16:19], v20
	ds_read_b128 v[20:23], v20 offset:16
	s_waitcnt lgkmcnt(1)
	v_mov_b32_e32 v26, v17
	v_mov_b32_e32 v27, v19
	v_pk_mul_f32 v[28:29], v[0:1], v[26:27]
	s_waitcnt lgkmcnt(0)
	v_mov_b32_e32 v30, v21
	v_mov_b32_e32 v31, v23
	v_mov_b32_e32 v21, v22
	v_mov_b32_e32 v17, v18
	v_pk_mul_f32 v[24:25], v[2:3], v[30:31]
	v_pk_fma_f32 v[22:23], v[12:13], v[16:17], v[28:29] neg_lo:[0,0,1] neg_hi:[0,0,1]
	v_pk_mul_f32 v[0:1], v[0:1], v[16:17]
	v_pk_mul_f32 v[2:3], v[2:3], v[20:21]
	v_add_u32_e32 v16, v186, v32
	v_pk_fma_f32 v[24:25], v[14:15], v[20:21], v[24:25] neg_lo:[0,0,1] neg_hi:[0,0,1]
	v_pk_fma_f32 v[2:3], v[14:15], v[30:31], v[2:3]
	v_pk_fma_f32 v[0:1], v[12:13], v[26:27], v[0:1]
	ds_read_b128 v[12:15], v16
	ds_read_b128 v[16:19], v16 offset:16
	s_waitcnt lgkmcnt(1)
	v_mov_b32_e32 v26, v13
	v_mov_b32_e32 v27, v15
	v_pk_mul_f32 v[28:29], v[4:5], v[26:27]
	s_waitcnt lgkmcnt(0)
	v_mov_b32_e32 v30, v17
	v_mov_b32_e32 v31, v19
	v_mov_b32_e32 v17, v18
	v_mov_b32_e32 v13, v14
	v_pk_mul_f32 v[20:21], v[6:7], v[30:31]
	v_pk_fma_f32 v[18:19], v[8:9], v[12:13], v[28:29] neg_lo:[0,0,1] neg_hi:[0,0,1]
	v_pk_mul_f32 v[4:5], v[4:5], v[12:13]
	v_pk_mul_f32 v[6:7], v[6:7], v[16:17]
	v_pk_fma_f32 v[20:21], v[10:11], v[16:17], v[20:21] neg_lo:[0,0,1] neg_hi:[0,0,1]
	v_pk_fma_f32 v[6:7], v[10:11], v[30:31], v[6:7]
	v_pk_fma_f32 v[4:5], v[8:9], v[26:27], v[4:5]
	v_mov_b64_e32 v[8:9], v[18:19]
	v_mov_b64_e32 v[12:13], v[22:23]
	v_mov_b64_e32 v[10:11], v[20:21]
	v_mov_b64_e32 v[14:15], v[24:25]
